# v7 + GEMM load segments reordered: LDS-DMA pieces issued first, ds_read fragment loads after them
# speedup vs baseline: 1.0260x; 1.0260x over previous
.LBB0_38:
	s_add_u32 s10, s8, 0x100
	s_addc_u32 s11, s9, 0
	s_add_i32 s48, 0, 0x10000
	s_cmp_eq_u32 s22, 40
	s_cselect_b32 s15, s1, s11
	s_cselect_b32 s14, s0, s10
	s_cselect_b32 s13, s37, s90
	s_cselect_b32 s12, s36, s21
	s_add_i32 s49, 0, 0x14000
	v_add_u32_e32 v154, s48, v143
	v_add_u32_e32 v158, s49, v143
	s_add_i32 m0, s29, 0xc000
	s_nop 0
	global_load_lds_dwordx4 v136, s[8:9]
	s_add_i32 m0, s29, 0xe000
	s_nop 0
	global_load_lds_dwordx4 v134, s[8:9]
	ds_read_b128 v[138:141], v154
	ds_read_b128 v[146:149], v154 offset:1024
	ds_read_b128 v[150:153], v154 offset:2048
	ds_read_b128 v[154:157], v154 offset:3072
	ds_read_b128 v[162:165], v158
	ds_read_b128 v[166:169], v158 offset:1024
	ds_read_b128 v[170:173], v158 offset:2048
	ds_read_b128 v[174:177], v158 offset:3072
	ds_read_b128 v[178:181], v145
	ds_read_b128 v[182:185], v145 offset:1024
	ds_read_b128 v[186:189], v145 offset:2048
	ds_read_b128 v[190:193], v145 offset:3072
	ds_read_b128 v[194:197], v145 offset:4096
	ds_read_b128 v[198:201], v145 offset:5120
	ds_read_b128 v[202:205], v145 offset:6144
	ds_read_b128 v[206:209], v145 offset:7168
	s_waitcnt vmcnt(8)
	s_waitcnt lgkmcnt(0)
	s_barrier
	v_mfma_f32_16x16x32_bf16 v[124:127], v[138:141], v[178:181], v[124:127]
	v_mfma_f32_16x16x32_bf16 v[120:123], v[150:153], v[178:181], v[120:123]
	v_mfma_f32_16x16x32_bf16 v[108:111], v[138:141], v[186:189], v[108:111]
	v_mfma_f32_16x16x32_bf16 v[104:107], v[150:153], v[186:189], v[104:107]
	v_mfma_f32_16x16x32_bf16 v[92:95], v[138:141], v[194:197], v[92:95]
	v_mfma_f32_16x16x32_bf16 v[88:91], v[150:153], v[194:197], v[88:91]
	v_mfma_f32_16x16x32_bf16 v[76:79], v[138:141], v[202:205], v[76:79]
	v_mfma_f32_16x16x32_bf16 v[72:75], v[150:153], v[202:205], v[72:75]
	v_mfma_f32_16x16x32_bf16 v[124:127], v[146:149], v[182:185], v[124:127]
	v_mfma_f32_16x16x32_bf16 v[120:123], v[154:157], v[182:185], v[120:123]
	v_mfma_f32_16x16x32_bf16 v[108:111], v[146:149], v[190:193], v[108:111]
	v_mfma_f32_16x16x32_bf16 v[104:107], v[154:157], v[190:193], v[104:107]
	v_mfma_f32_16x16x32_bf16 v[92:95], v[146:149], v[198:201], v[92:95]
	v_mfma_f32_16x16x32_bf16 v[88:91], v[154:157], v[198:201], v[88:91]
	v_mfma_f32_16x16x32_bf16 v[76:79], v[146:149], v[206:209], v[76:79]
	v_mfma_f32_16x16x32_bf16 v[72:75], v[154:157], v[206:209], v[72:75]
	v_mfma_f32_16x16x32_bf16 v[116:119], v[162:165], v[178:181], v[116:119]
	v_mfma_f32_16x16x32_bf16 v[112:115], v[170:173], v[178:181], v[112:115]
	v_mfma_f32_16x16x32_bf16 v[100:103], v[162:165], v[186:189], v[100:103]
	v_mfma_f32_16x16x32_bf16 v[96:99], v[170:173], v[186:189], v[96:99]
	v_mfma_f32_16x16x32_bf16 v[84:87], v[162:165], v[194:197], v[84:87]
	v_mfma_f32_16x16x32_bf16 v[80:83], v[170:173], v[194:197], v[80:83]
	v_mfma_f32_16x16x32_bf16 v[68:71], v[162:165], v[202:205], v[68:71]
	v_mfma_f32_16x16x32_bf16 v[64:67], v[170:173], v[202:205], v[64:67]
	v_mfma_f32_16x16x32_bf16 v[116:119], v[166:169], v[182:185], v[116:119]
	v_mfma_f32_16x16x32_bf16 v[112:115], v[174:177], v[182:185], v[112:115]
	v_mfma_f32_16x16x32_bf16 v[100:103], v[166:169], v[190:193], v[100:103]
	v_mfma_f32_16x16x32_bf16 v[96:99], v[174:177], v[190:193], v[96:99]
	v_mfma_f32_16x16x32_bf16 v[84:87], v[166:169], v[198:201], v[84:87]
	v_mfma_f32_16x16x32_bf16 v[80:83], v[174:177], v[198:201], v[80:83]
	v_mfma_f32_16x16x32_bf16 v[68:71], v[166:169], v[206:209], v[68:71]
	v_mfma_f32_16x16x32_bf16 v[64:67], v[174:177], v[206:209], v[64:67]
	s_barrier
	s_add_i32 s8, s48, s28
	s_mov_b32 m0, s8
	s_nop 0
	global_load_lds_dwordx4 v160, s[12:13]
	s_add_i32 m0, s8, 0x2000
	s_add_u32 s8, s12, 0xb0000
	s_addc_u32 s9, s13, 0
	s_add_i32 s48, s49, s28
	global_load_lds_dwordx4 v132, s[12:13]
	s_mov_b32 m0, s48
	s_nop 0
	global_load_lds_dwordx4 v160, s[8:9]
	s_add_i32 m0, s48, 0x2000
	s_nop 0
	global_load_lds_dwordx4 v132, s[8:9]
	s_mov_b32 m0, s29
	s_nop 0
	global_load_lds_dwordx4 v128, s[14:15]
	s_mov_b32 m0, s30
	s_nop 0
	global_load_lds_dwordx4 v130, s[14:15]
	ds_read_b128 v[178:181], v145 offset:16384
	ds_read_b128 v[182:185], v145 offset:17408
	ds_read_b128 v[186:189], v145 offset:18432
	ds_read_b128 v[190:193], v145 offset:19456
	ds_read_b128 v[206:209], v145 offset:23552
	ds_read_b128 v[202:205], v145 offset:22528
	ds_read_b128 v[198:201], v145 offset:21504
	ds_read_b128 v[194:197], v145 offset:20480
	s_waitcnt vmcnt(8)
	s_waitcnt lgkmcnt(0)
	s_barrier
	v_mfma_f32_16x16x32_bf16 v[60:63], v[138:141], v[178:181], v[60:63]
	v_mfma_f32_16x16x32_bf16 v[56:59], v[150:153], v[178:181], v[56:59]
	v_mfma_f32_16x16x32_bf16 v[44:47], v[138:141], v[186:189], v[44:47]
	v_mfma_f32_16x16x32_bf16 v[40:43], v[150:153], v[186:189], v[40:43]
	v_mfma_f32_16x16x32_bf16 v[28:31], v[138:141], v[194:197], v[28:31]
	v_mfma_f32_16x16x32_bf16 v[24:27], v[150:153], v[194:197], v[24:27]
	v_mfma_f32_16x16x32_bf16 v[12:15], v[138:141], v[202:205], v[12:15]
	v_mfma_f32_16x16x32_bf16 v[8:11], v[150:153], v[202:205], v[8:11]
	v_mfma_f32_16x16x32_bf16 v[60:63], v[146:149], v[182:185], v[60:63]
	v_mfma_f32_16x16x32_bf16 v[56:59], v[154:157], v[182:185], v[56:59]
	v_mfma_f32_16x16x32_bf16 v[44:47], v[146:149], v[190:193], v[44:47]
	v_mfma_f32_16x16x32_bf16 v[40:43], v[154:157], v[190:193], v[40:43]
	v_mfma_f32_16x16x32_bf16 v[28:31], v[146:149], v[198:201], v[28:31]
	v_mfma_f32_16x16x32_bf16 v[24:27], v[154:157], v[198:201], v[24:27]
	v_mfma_f32_16x16x32_bf16 v[12:15], v[146:149], v[206:209], v[12:15]
	v_mfma_f32_16x16x32_bf16 v[8:11], v[154:157], v[206:209], v[8:11]
	v_mfma_f32_16x16x32_bf16 v[52:55], v[162:165], v[178:181], v[52:55]
	v_mfma_f32_16x16x32_bf16 v[48:51], v[170:173], v[178:181], v[48:51]
	v_mfma_f32_16x16x32_bf16 v[36:39], v[162:165], v[186:189], v[36:39]
	v_mfma_f32_16x16x32_bf16 v[32:35], v[170:173], v[186:189], v[32:35]
	v_mfma_f32_16x16x32_bf16 v[20:23], v[162:165], v[194:197], v[20:23]
	v_mfma_f32_16x16x32_bf16 v[16:19], v[170:173], v[194:197], v[16:19]
	v_mfma_f32_16x16x32_bf16 v[4:7], v[162:165], v[202:205], v[4:7]
	v_mfma_f32_16x16x32_bf16 v[0:3], v[170:173], v[202:205], v[0:3]
	v_mfma_f32_16x16x32_bf16 v[52:55], v[166:169], v[182:185], v[52:55]
	v_mfma_f32_16x16x32_bf16 v[48:51], v[174:177], v[182:185], v[48:51]
	v_mfma_f32_16x16x32_bf16 v[36:39], v[166:169], v[190:193], v[36:39]
	v_mfma_f32_16x16x32_bf16 v[32:35], v[174:177], v[190:193], v[32:35]
	v_mfma_f32_16x16x32_bf16 v[20:23], v[166:169], v[198:201], v[20:23]
	v_mfma_f32_16x16x32_bf16 v[16:19], v[174:177], v[198:201], v[16:19]
	v_mfma_f32_16x16x32_bf16 v[4:7], v[166:169], v[206:209], v[4:7]
	v_mfma_f32_16x16x32_bf16 v[0:3], v[174:177], v[206:209], v[0:3]
	s_barrier
	s_add_i32 s48, 0, 0x18000
	s_add_i32 s49, 0, 0x1c000
	v_add_u32_e32 v154, s48, v143
	v_add_u32_e32 v174, s49, v143
	s_add_u32 s8, s14, 0xb0000
	s_addc_u32 s9, s15, 0
	s_mov_b32 m0, s31
	s_nop 0
	global_load_lds_dwordx4 v128, s[8:9]
	s_mov_b32 m0, s33
	s_nop 0
	global_load_lds_dwordx4 v130, s[8:9]
	ds_read_b128 v[138:141], v154
	ds_read_b128 v[146:149], v154 offset:1024
	ds_read_b128 v[150:153], v154 offset:2048
	ds_read_b128 v[154:157], v154 offset:3072
	ds_read_b128 v[162:165], v174
	ds_read_b128 v[166:169], v174 offset:1024
	ds_read_b128 v[170:173], v174 offset:2048
	ds_read_b128 v[174:177], v174 offset:3072
	ds_read_b128 v[178:181], v145 offset:32768
	ds_read_b128 v[182:185], v145 offset:33792
	ds_read_b128 v[186:189], v145 offset:34816
	ds_read_b128 v[190:193], v145 offset:35840
	ds_read_b128 v[194:197], v145 offset:36864
	ds_read_b128 v[198:201], v145 offset:37888
	ds_read_b128 v[202:205], v145 offset:38912
	ds_read_b128 v[206:209], v145 offset:39936
	s_waitcnt vmcnt(8)
	s_waitcnt lgkmcnt(0)
	s_barrier
	v_mfma_f32_16x16x32_bf16 v[124:127], v[138:141], v[178:181], v[124:127]
	v_mfma_f32_16x16x32_bf16 v[120:123], v[150:153], v[178:181], v[120:123]
	v_mfma_f32_16x16x32_bf16 v[108:111], v[138:141], v[186:189], v[108:111]
	v_mfma_f32_16x16x32_bf16 v[104:107], v[150:153], v[186:189], v[104:107]
	v_mfma_f32_16x16x32_bf16 v[92:95], v[138:141], v[194:197], v[92:95]
	v_mfma_f32_16x16x32_bf16 v[88:91], v[150:153], v[194:197], v[88:91]
	v_mfma_f32_16x16x32_bf16 v[76:79], v[138:141], v[202:205], v[76:79]
	v_mfma_f32_16x16x32_bf16 v[72:75], v[150:153], v[202:205], v[72:75]
	v_mfma_f32_16x16x32_bf16 v[124:127], v[146:149], v[182:185], v[124:127]
	v_mfma_f32_16x16x32_bf16 v[120:123], v[154:157], v[182:185], v[120:123]
	v_mfma_f32_16x16x32_bf16 v[108:111], v[146:149], v[190:193], v[108:111]
	v_mfma_f32_16x16x32_bf16 v[104:107], v[154:157], v[190:193], v[104:107]
	v_mfma_f32_16x16x32_bf16 v[92:95], v[146:149], v[198:201], v[92:95]
	v_mfma_f32_16x16x32_bf16 v[88:91], v[154:157], v[198:201], v[88:91]
	v_mfma_f32_16x16x32_bf16 v[76:79], v[146:149], v[206:209], v[76:79]
	v_mfma_f32_16x16x32_bf16 v[72:75], v[154:157], v[206:209], v[72:75]
	v_mfma_f32_16x16x32_bf16 v[116:119], v[162:165], v[178:181], v[116:119]
	v_mfma_f32_16x16x32_bf16 v[112:115], v[170:173], v[178:181], v[112:115]
	v_mfma_f32_16x16x32_bf16 v[100:103], v[162:165], v[186:189], v[100:103]
	v_mfma_f32_16x16x32_bf16 v[96:99], v[170:173], v[186:189], v[96:99]
	v_mfma_f32_16x16x32_bf16 v[84:87], v[162:165], v[194:197], v[84:87]
	v_mfma_f32_16x16x32_bf16 v[80:83], v[170:173], v[194:197], v[80:83]
	v_mfma_f32_16x16x32_bf16 v[68:71], v[162:165], v[202:205], v[68:71]
	v_mfma_f32_16x16x32_bf16 v[64:67], v[170:173], v[202:205], v[64:67]
	v_mfma_f32_16x16x32_bf16 v[116:119], v[166:169], v[182:185], v[116:119]
	v_mfma_f32_16x16x32_bf16 v[112:115], v[174:177], v[182:185], v[112:115]
	v_mfma_f32_16x16x32_bf16 v[100:103], v[166:169], v[190:193], v[100:103]
	v_mfma_f32_16x16x32_bf16 v[96:99], v[174:177], v[190:193], v[96:99]
	v_mfma_f32_16x16x32_bf16 v[84:87], v[166:169], v[198:201], v[84:87]
	v_mfma_f32_16x16x32_bf16 v[80:83], v[174:177], v[198:201], v[80:83]
	v_mfma_f32_16x16x32_bf16 v[68:71], v[166:169], v[206:209], v[68:71]
	v_mfma_f32_16x16x32_bf16 v[64:67], v[174:177], v[206:209], v[64:67]
	s_barrier
	s_add_i32 s8, s48, s28
	s_add_i32 m0, s8, 0xffffff80
	s_nop 0
	global_load_lds_dwordx4 v160, s[12:13] offset:128
	s_add_i32 m0, s8, 0x1f80
	s_add_u32 s8, s12, 0xb0080
	s_addc_u32 s9, s13, 0
	global_load_lds_dwordx4 v132, s[12:13] offset:128
	s_add_i32 s12, s49, s28
	s_mov_b32 m0, s12
	s_nop 0
	global_load_lds_dwordx4 v160, s[8:9]
	s_add_i32 m0, s12, 0x2000
	s_nop 0
	global_load_lds_dwordx4 v132, s[8:9]
	s_add_i32 m0, s34, 0xffffff80
	s_nop 0
	global_load_lds_dwordx4 v128, s[14:15] offset:128
	s_add_i32 m0, s35, 0xffffff80
	s_nop 0
	global_load_lds_dwordx4 v130, s[14:15] offset:128
	ds_read_b128 v[178:181], v145 offset:49152
	ds_read_b128 v[182:185], v145 offset:50176
	ds_read_b128 v[186:189], v145 offset:51200
	ds_read_b128 v[190:193], v145 offset:52224
	ds_read_b128 v[206:209], v145 offset:56320
	ds_read_b128 v[202:205], v145 offset:55296
	ds_read_b128 v[198:201], v145 offset:54272
	ds_read_b128 v[194:197], v145 offset:53248
	s_waitcnt vmcnt(8)
	s_waitcnt lgkmcnt(0)
	s_barrier
	v_mfma_f32_16x16x32_bf16 v[60:63], v[138:141], v[178:181], v[60:63]
	v_mfma_f32_16x16x32_bf16 v[56:59], v[150:153], v[178:181], v[56:59]
	v_mfma_f32_16x16x32_bf16 v[44:47], v[138:141], v[186:189], v[44:47]
	v_mfma_f32_16x16x32_bf16 v[40:43], v[150:153], v[186:189], v[40:43]
	v_mfma_f32_16x16x32_bf16 v[28:31], v[138:141], v[194:197], v[28:31]
	v_mfma_f32_16x16x32_bf16 v[24:27], v[150:153], v[194:197], v[24:27]
	v_mfma_f32_16x16x32_bf16 v[12:15], v[138:141], v[202:205], v[12:15]
	v_mfma_f32_16x16x32_bf16 v[8:11], v[150:153], v[202:205], v[8:11]
	v_mfma_f32_16x16x32_bf16 v[60:63], v[146:149], v[182:185], v[60:63]
	v_mfma_f32_16x16x32_bf16 v[56:59], v[154:157], v[182:185], v[56:59]
	v_mfma_f32_16x16x32_bf16 v[44:47], v[146:149], v[190:193], v[44:47]
	v_mfma_f32_16x16x32_bf16 v[40:43], v[154:157], v[190:193], v[40:43]
	v_mfma_f32_16x16x32_bf16 v[28:31], v[146:149], v[198:201], v[28:31]
	v_mfma_f32_16x16x32_bf16 v[24:27], v[154:157], v[198:201], v[24:27]
	v_mfma_f32_16x16x32_bf16 v[12:15], v[146:149], v[206:209], v[12:15]
	v_mfma_f32_16x16x32_bf16 v[8:11], v[154:157], v[206:209], v[8:11]
	v_mfma_f32_16x16x32_bf16 v[52:55], v[162:165], v[178:181], v[52:55]
	v_mfma_f32_16x16x32_bf16 v[48:51], v[170:173], v[178:181], v[48:51]
	v_mfma_f32_16x16x32_bf16 v[36:39], v[162:165], v[186:189], v[36:39]
	v_mfma_f32_16x16x32_bf16 v[32:35], v[170:173], v[186:189], v[32:35]
	v_mfma_f32_16x16x32_bf16 v[20:23], v[162:165], v[194:197], v[20:23]
	v_mfma_f32_16x16x32_bf16 v[16:19], v[170:173], v[194:197], v[16:19]
	v_mfma_f32_16x16x32_bf16 v[4:7], v[162:165], v[202:205], v[4:7]
	v_mfma_f32_16x16x32_bf16 v[0:3], v[170:173], v[202:205], v[0:3]
	v_mfma_f32_16x16x32_bf16 v[52:55], v[166:169], v[182:185], v[52:55]
	v_mfma_f32_16x16x32_bf16 v[48:51], v[174:177], v[182:185], v[48:51]
	v_mfma_f32_16x16x32_bf16 v[36:39], v[166:169], v[190:193], v[36:39]
	v_mfma_f32_16x16x32_bf16 v[32:35], v[174:177], v[190:193], v[32:35]
	v_mfma_f32_16x16x32_bf16 v[20:23], v[166:169], v[198:201], v[20:23]
	v_mfma_f32_16x16x32_bf16 v[16:19], v[174:177], v[198:201], v[16:19]
	v_mfma_f32_16x16x32_bf16 v[4:7], v[166:169], v[206:209], v[4:7]
	v_mfma_f32_16x16x32_bf16 v[0:3], v[174:177], v[206:209], v[0:3]
	s_barrier
	s_add_i32 s22, s22, 2
	s_add_u32 s21, s21, 0x100
	s_addc_u32 s90, s90, 0
	s_cmp_gt_u32 s22, 41
	s_mov_b64 s[8:9], s[10:11]
	s_cbranch_scc0 .LBB0_38
	v_lshl_add_u32 v140, s44, 8, v142
	v_lshl_or_b32 v138, s45, 8, v144
	v_lshlrev_b32_e32 v139, 12, v140
	v_lshl_add_u32 v139, v138, 2, v139
	v_lshlrev_b32_e32 v141, 11, v140
	v_lshl_add_u32 v138, v138, 1, v141
	s_mov_b64 s[8:9], s[4:5]
	global_load_dwordx4 v[146:149], v138, s[8:9]
	global_load_dwordx4 v[150:153], v138, s[8:9] offset:256
	s_add_u32 s8, s8, 0x8000
	s_addc_u32 s9, s9, 0
	global_load_dwordx4 v[154:157], v138, s[8:9]
	global_load_dwordx4 v[162:165], v138, s[8:9] offset:256
	s_add_u32 s8, s8, 0x8000
	s_addc_u32 s9, s9, 0
	global_load_dwordx4 v[166:169], v138, s[8:9]
	global_load_dwordx4 v[174:177], v138, s[8:9] offset:256
	s_add_u32 s8, s8, 0x8000
	s_addc_u32 s9, s9, 0
	global_load_dwordx4 v[178:181], v138, s[8:9]
	global_load_dwordx4 v[182:185], v138, s[8:9] offset:256
	s_add_u32 s8, s8, 0x28000
	s_addc_u32 s9, s9, 0
	global_load_dwordx4 v[186:189], v138, s[8:9]
	global_load_dwordx4 v[190:193], v138, s[8:9] offset:256
	s_add_u32 s8, s8, 0x8000
	s_addc_u32 s9, s9, 0
	global_load_dwordx4 v[194:197], v138, s[8:9]
	global_load_dwordx4 v[198:201], v138, s[8:9] offset:256
	s_add_u32 s8, s8, 0x8000
	s_addc_u32 s9, s9, 0
	global_load_dwordx4 v[202:205], v138, s[8:9]
	global_load_dwordx4 v[206:209], v138, s[8:9] offset:256
	s_add_u32 s8, s8, 0x8000
	s_addc_u32 s9, s9, 0
	global_load_dwordx4 v[210:213], v138, s[8:9]
	global_load_dwordx4 v[214:217], v138, s[8:9] offset:256
	s_and_b64 vcc, exec, s[6:7]
	s_cbranch_vccz .LBB0_41
	s_barrier

.LBB0_56:
	s_add_u32 s12, s10, 0xfffc0080
	s_addc_u32 s13, s11, -1
	s_add_i32 s48, 0, 0x10000
	s_cmp_eq_u32 s22, 12
	s_cselect_b32 s15, s20, s13
	s_cselect_b32 s14, s37, s12
	s_cselect_b32 s13, s41, s21
	s_cselect_b32 s12, s91, s96
	s_add_i32 s50, 0, 0x14000
	v_add_u32_e32 v154, s48, v147
	v_add_u32_e32 v158, s50, v147
	s_add_i32 m0, s30, 0xc000
	s_nop 0
	global_load_lds_dwordx4 v136, s[10:11]
	s_add_i32 m0, s30, 0xe000
	s_nop 0
	global_load_lds_dwordx4 v134, s[10:11]
	ds_read_b128 v[138:141], v154
	ds_read_b128 v[142:145], v154 offset:1024
	ds_read_b128 v[150:153], v154 offset:2048
	ds_read_b128 v[154:157], v154 offset:3072
	ds_read_b128 v[162:165], v158
	ds_read_b128 v[166:169], v158 offset:1024
	ds_read_b128 v[170:173], v158 offset:2048
	ds_read_b128 v[174:177], v158 offset:3072
	ds_read_b128 v[178:181], v149
	ds_read_b128 v[182:185], v149 offset:1024
	ds_read_b128 v[186:189], v149 offset:2048
	ds_read_b128 v[190:193], v149 offset:3072
	ds_read_b128 v[194:197], v149 offset:4096
	ds_read_b128 v[198:201], v149 offset:5120
	ds_read_b128 v[202:205], v149 offset:6144
	ds_read_b128 v[206:209], v149 offset:7168
	s_waitcnt vmcnt(8)
	s_waitcnt lgkmcnt(0)
	s_barrier
	v_mfma_f32_16x16x32_bf16 v[124:127], v[138:141], v[178:181], v[124:127]
	v_mfma_f32_16x16x32_bf16 v[116:119], v[150:153], v[178:181], v[116:119]
	v_mfma_f32_16x16x32_bf16 v[108:111], v[138:141], v[186:189], v[108:111]
	v_mfma_f32_16x16x32_bf16 v[100:103], v[150:153], v[186:189], v[100:103]
	v_mfma_f32_16x16x32_bf16 v[92:95], v[138:141], v[194:197], v[92:95]
	v_mfma_f32_16x16x32_bf16 v[84:87], v[150:153], v[194:197], v[84:87]
	v_mfma_f32_16x16x32_bf16 v[76:79], v[138:141], v[202:205], v[76:79]
	v_mfma_f32_16x16x32_bf16 v[64:67], v[150:153], v[202:205], v[64:67]
	v_mfma_f32_16x16x32_bf16 v[124:127], v[142:145], v[182:185], v[124:127]
	v_mfma_f32_16x16x32_bf16 v[116:119], v[154:157], v[182:185], v[116:119]
	v_mfma_f32_16x16x32_bf16 v[108:111], v[142:145], v[190:193], v[108:111]
	v_mfma_f32_16x16x32_bf16 v[100:103], v[154:157], v[190:193], v[100:103]
	v_mfma_f32_16x16x32_bf16 v[92:95], v[142:145], v[198:201], v[92:95]
	v_mfma_f32_16x16x32_bf16 v[84:87], v[154:157], v[198:201], v[84:87]
	v_mfma_f32_16x16x32_bf16 v[76:79], v[142:145], v[206:209], v[76:79]
	v_mfma_f32_16x16x32_bf16 v[64:67], v[154:157], v[206:209], v[64:67]
	v_mfma_f32_16x16x32_bf16 v[120:123], v[162:165], v[178:181], v[120:123]
	v_mfma_f32_16x16x32_bf16 v[112:115], v[170:173], v[178:181], v[112:115]
	v_mfma_f32_16x16x32_bf16 v[104:107], v[162:165], v[186:189], v[104:107]
	v_mfma_f32_16x16x32_bf16 v[96:99], v[170:173], v[186:189], v[96:99]
	v_mfma_f32_16x16x32_bf16 v[88:91], v[162:165], v[194:197], v[88:91]
	v_mfma_f32_16x16x32_bf16 v[80:83], v[170:173], v[194:197], v[80:83]
	v_mfma_f32_16x16x32_bf16 v[72:75], v[162:165], v[202:205], v[72:75]
	v_mfma_f32_16x16x32_bf16 v[68:71], v[170:173], v[202:205], v[68:71]
	v_mfma_f32_16x16x32_bf16 v[120:123], v[166:169], v[182:185], v[120:123]
	v_mfma_f32_16x16x32_bf16 v[112:115], v[174:177], v[182:185], v[112:115]
	v_mfma_f32_16x16x32_bf16 v[104:107], v[166:169], v[190:193], v[104:107]
	v_mfma_f32_16x16x32_bf16 v[96:99], v[174:177], v[190:193], v[96:99]
	v_mfma_f32_16x16x32_bf16 v[88:91], v[166:169], v[198:201], v[88:91]
	v_mfma_f32_16x16x32_bf16 v[80:83], v[174:177], v[198:201], v[80:83]
	v_mfma_f32_16x16x32_bf16 v[72:75], v[166:169], v[206:209], v[72:75]
	v_mfma_f32_16x16x32_bf16 v[68:71], v[174:177], v[206:209], v[68:71]
	s_barrier
	s_add_i32 s48, s48, s28
	s_mov_b32 m0, s48
	s_nop 0
	global_load_lds_dwordx4 v160, s[12:13]
	s_add_i32 m0, s48, 0x2000
	s_add_u32 s48, s12, 0x40000
	s_addc_u32 s49, s13, 0
	s_add_i32 s50, s50, s28
	global_load_lds_dwordx4 v128, s[12:13]
	s_mov_b32 m0, s50
	s_nop 0
	global_load_lds_dwordx4 v160, s[48:49]
	s_add_i32 m0, s50, 0x2000
	s_nop 0
	global_load_lds_dwordx4 v128, s[48:49]
	s_mov_b32 m0, s30
	s_nop 0
	global_load_lds_dwordx4 v132, s[14:15]
	s_mov_b32 m0, s31
	s_nop 0
	global_load_lds_dwordx4 v130, s[14:15]
	ds_read_b128 v[178:181], v149 offset:16384
	ds_read_b128 v[182:185], v149 offset:17408
	ds_read_b128 v[186:189], v149 offset:18432
	ds_read_b128 v[190:193], v149 offset:19456
	ds_read_b128 v[206:209], v149 offset:23552
	ds_read_b128 v[202:205], v149 offset:22528
	ds_read_b128 v[198:201], v149 offset:21504
	ds_read_b128 v[194:197], v149 offset:20480
	s_waitcnt vmcnt(8)
	s_waitcnt lgkmcnt(0)
	s_barrier
	v_mfma_f32_16x16x32_bf16 v[60:63], v[138:141], v[178:181], v[60:63]
	v_mfma_f32_16x16x32_bf16 v[48:51], v[150:153], v[178:181], v[48:51]
	v_mfma_f32_16x16x32_bf16 v[44:47], v[138:141], v[186:189], v[44:47]
	v_mfma_f32_16x16x32_bf16 v[32:35], v[150:153], v[186:189], v[32:35]
	v_mfma_f32_16x16x32_bf16 v[28:31], v[138:141], v[194:197], v[28:31]
	v_mfma_f32_16x16x32_bf16 v[16:19], v[150:153], v[194:197], v[16:19]
	v_mfma_f32_16x16x32_bf16 v[12:15], v[138:141], v[202:205], v[12:15]
	v_mfma_f32_16x16x32_bf16 v[0:3], v[150:153], v[202:205], v[0:3]
	v_mfma_f32_16x16x32_bf16 v[60:63], v[142:145], v[182:185], v[60:63]
	v_mfma_f32_16x16x32_bf16 v[48:51], v[154:157], v[182:185], v[48:51]
	v_mfma_f32_16x16x32_bf16 v[44:47], v[142:145], v[190:193], v[44:47]
	v_mfma_f32_16x16x32_bf16 v[32:35], v[154:157], v[190:193], v[32:35]
	v_mfma_f32_16x16x32_bf16 v[28:31], v[142:145], v[198:201], v[28:31]
	v_mfma_f32_16x16x32_bf16 v[16:19], v[154:157], v[198:201], v[16:19]
	v_mfma_f32_16x16x32_bf16 v[12:15], v[142:145], v[206:209], v[12:15]
	v_mfma_f32_16x16x32_bf16 v[0:3], v[154:157], v[206:209], v[0:3]
	v_mfma_f32_16x16x32_bf16 v[56:59], v[162:165], v[178:181], v[56:59]
	v_mfma_f32_16x16x32_bf16 v[52:55], v[170:173], v[178:181], v[52:55]
	v_mfma_f32_16x16x32_bf16 v[40:43], v[162:165], v[186:189], v[40:43]
	v_mfma_f32_16x16x32_bf16 v[36:39], v[170:173], v[186:189], v[36:39]
	v_mfma_f32_16x16x32_bf16 v[24:27], v[162:165], v[194:197], v[24:27]
	v_mfma_f32_16x16x32_bf16 v[20:23], v[170:173], v[194:197], v[20:23]
	v_mfma_f32_16x16x32_bf16 v[8:11], v[162:165], v[202:205], v[8:11]
	v_mfma_f32_16x16x32_bf16 v[4:7], v[170:173], v[202:205], v[4:7]
	v_mfma_f32_16x16x32_bf16 v[56:59], v[166:169], v[182:185], v[56:59]
	v_mfma_f32_16x16x32_bf16 v[52:55], v[174:177], v[182:185], v[52:55]
	v_mfma_f32_16x16x32_bf16 v[40:43], v[166:169], v[190:193], v[40:43]
	v_mfma_f32_16x16x32_bf16 v[36:39], v[174:177], v[190:193], v[36:39]
	v_mfma_f32_16x16x32_bf16 v[24:27], v[166:169], v[198:201], v[24:27]
	v_mfma_f32_16x16x32_bf16 v[20:23], v[174:177], v[198:201], v[20:23]
	v_mfma_f32_16x16x32_bf16 v[8:11], v[166:169], v[206:209], v[8:11]
	v_mfma_f32_16x16x32_bf16 v[4:7], v[174:177], v[206:209], v[4:7]
	s_barrier
	s_add_i32 s48, 0, 0x18000
	s_add_i32 s49, 0, 0x1c000
	v_add_u32_e32 v154, s48, v147
	v_add_u32_e32 v174, s49, v147
	s_mov_b64 s[100:101], s[14:15]
	s_add_u32 s14, s14, 0x40000
	s_addc_u32 s15, s15, 0
	s_mov_b32 m0, s33
	s_nop 0
	global_load_lds_dwordx4 v132, s[14:15]
	s_mov_b32 m0, s34
	s_nop 0
	global_load_lds_dwordx4 v130, s[14:15]
	ds_read_b128 v[138:141], v154
	ds_read_b128 v[142:145], v154 offset:1024
	ds_read_b128 v[150:153], v154 offset:2048
	ds_read_b128 v[154:157], v154 offset:3072
	ds_read_b128 v[162:165], v174
	ds_read_b128 v[166:169], v174 offset:1024
	ds_read_b128 v[170:173], v174 offset:2048
	ds_read_b128 v[174:177], v174 offset:3072
	ds_read_b128 v[178:181], v149 offset:32768
	ds_read_b128 v[182:185], v149 offset:33792
	ds_read_b128 v[186:189], v149 offset:34816
	ds_read_b128 v[190:193], v149 offset:35840
	ds_read_b128 v[194:197], v149 offset:36864
	ds_read_b128 v[198:201], v149 offset:37888
	ds_read_b128 v[202:205], v149 offset:38912
	ds_read_b128 v[206:209], v149 offset:39936
	s_waitcnt vmcnt(8)
	s_waitcnt lgkmcnt(0)
	s_barrier
	v_mfma_f32_16x16x32_bf16 v[124:127], v[138:141], v[178:181], v[124:127]
	v_mfma_f32_16x16x32_bf16 v[116:119], v[150:153], v[178:181], v[116:119]
	v_mfma_f32_16x16x32_bf16 v[108:111], v[138:141], v[186:189], v[108:111]
	v_mfma_f32_16x16x32_bf16 v[100:103], v[150:153], v[186:189], v[100:103]
	v_mfma_f32_16x16x32_bf16 v[92:95], v[138:141], v[194:197], v[92:95]
	v_mfma_f32_16x16x32_bf16 v[84:87], v[150:153], v[194:197], v[84:87]
	v_mfma_f32_16x16x32_bf16 v[76:79], v[138:141], v[202:205], v[76:79]
	v_mfma_f32_16x16x32_bf16 v[64:67], v[150:153], v[202:205], v[64:67]
	v_mfma_f32_16x16x32_bf16 v[124:127], v[142:145], v[182:185], v[124:127]
	v_mfma_f32_16x16x32_bf16 v[116:119], v[154:157], v[182:185], v[116:119]
	v_mfma_f32_16x16x32_bf16 v[108:111], v[142:145], v[190:193], v[108:111]
	v_mfma_f32_16x16x32_bf16 v[100:103], v[154:157], v[190:193], v[100:103]
	v_mfma_f32_16x16x32_bf16 v[92:95], v[142:145], v[198:201], v[92:95]
	v_mfma_f32_16x16x32_bf16 v[84:87], v[154:157], v[198:201], v[84:87]
	v_mfma_f32_16x16x32_bf16 v[76:79], v[142:145], v[206:209], v[76:79]
	v_mfma_f32_16x16x32_bf16 v[64:67], v[154:157], v[206:209], v[64:67]
	v_mfma_f32_16x16x32_bf16 v[120:123], v[162:165], v[178:181], v[120:123]
	v_mfma_f32_16x16x32_bf16 v[112:115], v[170:173], v[178:181], v[112:115]
	v_mfma_f32_16x16x32_bf16 v[104:107], v[162:165], v[186:189], v[104:107]
	v_mfma_f32_16x16x32_bf16 v[96:99], v[170:173], v[186:189], v[96:99]
	v_mfma_f32_16x16x32_bf16 v[88:91], v[162:165], v[194:197], v[88:91]
	v_mfma_f32_16x16x32_bf16 v[80:83], v[170:173], v[194:197], v[80:83]
	v_mfma_f32_16x16x32_bf16 v[72:75], v[162:165], v[202:205], v[72:75]
	v_mfma_f32_16x16x32_bf16 v[68:71], v[170:173], v[202:205], v[68:71]
	v_mfma_f32_16x16x32_bf16 v[120:123], v[166:169], v[182:185], v[120:123]
	v_mfma_f32_16x16x32_bf16 v[112:115], v[174:177], v[182:185], v[112:115]
	v_mfma_f32_16x16x32_bf16 v[104:107], v[166:169], v[190:193], v[104:107]
	v_mfma_f32_16x16x32_bf16 v[96:99], v[174:177], v[190:193], v[96:99]
	v_mfma_f32_16x16x32_bf16 v[88:91], v[166:169], v[198:201], v[88:91]
	v_mfma_f32_16x16x32_bf16 v[80:83], v[174:177], v[198:201], v[80:83]
	v_mfma_f32_16x16x32_bf16 v[72:75], v[166:169], v[206:209], v[72:75]
	v_mfma_f32_16x16x32_bf16 v[68:71], v[174:177], v[206:209], v[68:71]
	s_barrier
	s_add_i32 s14, s48, s28
	s_add_i32 m0, s14, 0xffffff80
	s_nop 0
	global_load_lds_dwordx4 v160, s[12:13] offset:128
	s_add_i32 m0, s14, 0x1f80
	s_nop 0
	global_load_lds_dwordx4 v128, s[12:13] offset:128
	s_add_u32 s12, s12, 0x40080
	s_addc_u32 s13, s13, 0
	s_add_i32 s14, s49, s28
	s_mov_b32 m0, s14
	s_nop 0
	global_load_lds_dwordx4 v160, s[12:13]
	s_add_i32 m0, s14, 0x2000
	s_nop 0
	global_load_lds_dwordx4 v128, s[12:13]
	s_add_i32 m0, s35, 0xffffff80
	s_nop 0
	global_load_lds_dwordx4 v132, s[100:101] offset:128
	s_add_i32 m0, s90, 0xffffff80
	s_nop 0
	global_load_lds_dwordx4 v130, s[100:101] offset:128
	ds_read_b128 v[178:181], v149 offset:49152
	ds_read_b128 v[182:185], v149 offset:50176
	ds_read_b128 v[186:189], v149 offset:51200
	ds_read_b128 v[206:209], v149 offset:56320
	ds_read_b128 v[202:205], v149 offset:55296
	ds_read_b128 v[198:201], v149 offset:54272
	ds_read_b128 v[194:197], v149 offset:53248
	ds_read_b128 v[190:193], v149 offset:52224
	s_waitcnt vmcnt(8)
	s_waitcnt lgkmcnt(0)
	s_barrier
	v_mfma_f32_16x16x32_bf16 v[60:63], v[138:141], v[178:181], v[60:63]
	v_mfma_f32_16x16x32_bf16 v[48:51], v[150:153], v[178:181], v[48:51]
	v_mfma_f32_16x16x32_bf16 v[44:47], v[138:141], v[186:189], v[44:47]
	v_mfma_f32_16x16x32_bf16 v[32:35], v[150:153], v[186:189], v[32:35]
	v_mfma_f32_16x16x32_bf16 v[28:31], v[138:141], v[194:197], v[28:31]
	v_mfma_f32_16x16x32_bf16 v[16:19], v[150:153], v[194:197], v[16:19]
	v_mfma_f32_16x16x32_bf16 v[12:15], v[138:141], v[202:205], v[12:15]
	v_mfma_f32_16x16x32_bf16 v[0:3], v[150:153], v[202:205], v[0:3]
	v_mfma_f32_16x16x32_bf16 v[60:63], v[142:145], v[182:185], v[60:63]
	v_mfma_f32_16x16x32_bf16 v[48:51], v[154:157], v[182:185], v[48:51]
	v_mfma_f32_16x16x32_bf16 v[44:47], v[142:145], v[190:193], v[44:47]
	v_mfma_f32_16x16x32_bf16 v[32:35], v[154:157], v[190:193], v[32:35]
	v_mfma_f32_16x16x32_bf16 v[28:31], v[142:145], v[198:201], v[28:31]
	v_mfma_f32_16x16x32_bf16 v[16:19], v[154:157], v[198:201], v[16:19]
	v_mfma_f32_16x16x32_bf16 v[12:15], v[142:145], v[206:209], v[12:15]
	v_mfma_f32_16x16x32_bf16 v[0:3], v[154:157], v[206:209], v[0:3]
	v_mfma_f32_16x16x32_bf16 v[56:59], v[162:165], v[178:181], v[56:59]
	v_mfma_f32_16x16x32_bf16 v[52:55], v[170:173], v[178:181], v[52:55]
	v_mfma_f32_16x16x32_bf16 v[40:43], v[162:165], v[186:189], v[40:43]
	v_mfma_f32_16x16x32_bf16 v[36:39], v[170:173], v[186:189], v[36:39]
	v_mfma_f32_16x16x32_bf16 v[24:27], v[162:165], v[194:197], v[24:27]
	v_mfma_f32_16x16x32_bf16 v[20:23], v[170:173], v[194:197], v[20:23]
	v_mfma_f32_16x16x32_bf16 v[8:11], v[162:165], v[202:205], v[8:11]
	v_mfma_f32_16x16x32_bf16 v[4:7], v[170:173], v[202:205], v[4:7]
	v_mfma_f32_16x16x32_bf16 v[56:59], v[166:169], v[182:185], v[56:59]
	v_mfma_f32_16x16x32_bf16 v[52:55], v[174:177], v[182:185], v[52:55]
	v_mfma_f32_16x16x32_bf16 v[40:43], v[166:169], v[190:193], v[40:43]
	v_mfma_f32_16x16x32_bf16 v[36:39], v[174:177], v[190:193], v[36:39]
	v_mfma_f32_16x16x32_bf16 v[24:27], v[166:169], v[198:201], v[24:27]
	v_mfma_f32_16x16x32_bf16 v[20:23], v[174:177], v[198:201], v[20:23]
	v_mfma_f32_16x16x32_bf16 v[8:11], v[166:169], v[206:209], v[8:11]
	v_mfma_f32_16x16x32_bf16 v[4:7], v[174:177], v[206:209], v[4:7]
	s_barrier
	s_add_i32 s22, s22, 2
	s_add_u32 s96, s96, 0x100
	s_addc_u32 s21, s21, 0
	s_add_u32 s10, s10, 0x100
	s_addc_u32 s11, s11, 0
	s_cmp_gt_u32 s22, 13
	s_cbranch_scc0 .LBB0_56
	v_lshl_add_u32 v192, s8, 8, v146
	v_lshlrev_b32_e32 v192, 3, v192
	global_load_dwordx2 v[176:177], v192, s[4:5]
	global_load_dwordx2 v[178:179], v192, s[4:5] offset:128
	global_load_dwordx2 v[180:181], v192, s[4:5] offset:256
	global_load_dwordx2 v[182:183], v192, s[4:5] offset:384
	global_load_dwordx2 v[184:185], v192, s[4:5] offset:1024
	global_load_dwordx2 v[186:187], v192, s[4:5] offset:1152
	global_load_dwordx2 v[188:189], v192, s[4:5] offset:1280
	global_load_dwordx2 v[190:191], v192, s[4:5] offset:1408
	s_and_b64 vcc, exec, s[6:7]
	s_cbranch_vccz .LBB0_59
	s_barrier

.LBB0_84:
	s_add_u32 s12, vcc_lo, 0xfffc0080
	s_addc_u32 s13, vcc_hi, -1
	s_add_i32 s48, 0, 0x10000
	s_cmp_eq_u32 s22, 12
	s_cselect_b32 s15, s9, s13
	s_cselect_b32 s14, s20, s12
	s_cselect_b32 s13, s37, s21
	s_cselect_b32 s12, s45, s90
	s_add_i32 s50, 0, 0x14000
	v_add_u32_e32 v154, s48, v143
	v_add_u32_e32 v158, s50, v143
	s_add_i32 m0, s11, 0xc000
	s_nop 0
	global_load_lds_dwordx4 v136, vcc
	s_add_i32 m0, s11, 0xe000
	s_nop 0
	global_load_lds_dwordx4 v134, vcc
	ds_read_b128 v[138:141], v154
	ds_read_b128 v[146:149], v154 offset:1024
	ds_read_b128 v[150:153], v154 offset:2048
	ds_read_b128 v[154:157], v154 offset:3072
	ds_read_b128 v[162:165], v158
	ds_read_b128 v[166:169], v158 offset:1024
	ds_read_b128 v[170:173], v158 offset:2048
	ds_read_b128 v[174:177], v158 offset:3072
	ds_read_b128 v[178:181], v145
	ds_read_b128 v[182:185], v145 offset:1024
	ds_read_b128 v[186:189], v145 offset:2048
	ds_read_b128 v[190:193], v145 offset:3072
	ds_read_b128 v[194:197], v145 offset:4096
	ds_read_b128 v[198:201], v145 offset:5120
	ds_read_b128 v[202:205], v145 offset:6144
	ds_read_b128 v[206:209], v145 offset:7168
	s_waitcnt vmcnt(8)
	s_waitcnt lgkmcnt(0)
	s_barrier
	v_mfma_f32_16x16x32_bf16 v[124:127], v[138:141], v[178:181], v[124:127]
	v_mfma_f32_16x16x32_bf16 v[120:123], v[150:153], v[178:181], v[120:123]
	v_mfma_f32_16x16x32_bf16 v[108:111], v[138:141], v[186:189], v[108:111]
	v_mfma_f32_16x16x32_bf16 v[104:107], v[150:153], v[186:189], v[104:107]
	v_mfma_f32_16x16x32_bf16 v[92:95], v[138:141], v[194:197], v[92:95]
	v_mfma_f32_16x16x32_bf16 v[88:91], v[150:153], v[194:197], v[88:91]
	v_mfma_f32_16x16x32_bf16 v[76:79], v[138:141], v[202:205], v[76:79]
	v_mfma_f32_16x16x32_bf16 v[72:75], v[150:153], v[202:205], v[72:75]
	v_mfma_f32_16x16x32_bf16 v[124:127], v[146:149], v[182:185], v[124:127]
	v_mfma_f32_16x16x32_bf16 v[120:123], v[154:157], v[182:185], v[120:123]
	v_mfma_f32_16x16x32_bf16 v[108:111], v[146:149], v[190:193], v[108:111]
	v_mfma_f32_16x16x32_bf16 v[104:107], v[154:157], v[190:193], v[104:107]
	v_mfma_f32_16x16x32_bf16 v[92:95], v[146:149], v[198:201], v[92:95]
	v_mfma_f32_16x16x32_bf16 v[88:91], v[154:157], v[198:201], v[88:91]
	v_mfma_f32_16x16x32_bf16 v[76:79], v[146:149], v[206:209], v[76:79]
	v_mfma_f32_16x16x32_bf16 v[72:75], v[154:157], v[206:209], v[72:75]
	v_mfma_f32_16x16x32_bf16 v[116:119], v[162:165], v[178:181], v[116:119]
	v_mfma_f32_16x16x32_bf16 v[112:115], v[170:173], v[178:181], v[112:115]
	v_mfma_f32_16x16x32_bf16 v[100:103], v[162:165], v[186:189], v[100:103]
	v_mfma_f32_16x16x32_bf16 v[96:99], v[170:173], v[186:189], v[96:99]
	v_mfma_f32_16x16x32_bf16 v[84:87], v[162:165], v[194:197], v[84:87]
	v_mfma_f32_16x16x32_bf16 v[80:83], v[170:173], v[194:197], v[80:83]
	v_mfma_f32_16x16x32_bf16 v[68:71], v[162:165], v[202:205], v[68:71]
	v_mfma_f32_16x16x32_bf16 v[64:67], v[170:173], v[202:205], v[64:67]
	v_mfma_f32_16x16x32_bf16 v[116:119], v[166:169], v[182:185], v[116:119]
	v_mfma_f32_16x16x32_bf16 v[112:115], v[174:177], v[182:185], v[112:115]
	v_mfma_f32_16x16x32_bf16 v[100:103], v[166:169], v[190:193], v[100:103]
	v_mfma_f32_16x16x32_bf16 v[96:99], v[174:177], v[190:193], v[96:99]
	v_mfma_f32_16x16x32_bf16 v[84:87], v[166:169], v[198:201], v[84:87]
	v_mfma_f32_16x16x32_bf16 v[80:83], v[174:177], v[198:201], v[80:83]
	v_mfma_f32_16x16x32_bf16 v[68:71], v[166:169], v[206:209], v[68:71]
	v_mfma_f32_16x16x32_bf16 v[64:67], v[174:177], v[206:209], v[64:67]
	s_barrier
	s_add_i32 s48, s48, s28
	s_mov_b32 m0, s48
	s_nop 0
	global_load_lds_dwordx4 v160, s[12:13]
	s_add_i32 m0, s48, 0x2000
	s_add_u32 s48, s12, 0x40000
	s_addc_u32 s49, s13, 0
	s_add_i32 s50, s50, s28
	global_load_lds_dwordx4 v132, s[12:13]
	s_mov_b32 m0, s50
	s_nop 0
	global_load_lds_dwordx4 v160, s[48:49]
	s_add_i32 m0, s50, 0x2000
	s_nop 0
	global_load_lds_dwordx4 v132, s[48:49]
	s_mov_b32 m0, s11
	s_nop 0
	global_load_lds_dwordx4 v128, s[14:15]
	s_mov_b32 m0, s29
	s_nop 0
	global_load_lds_dwordx4 v130, s[14:15]
	ds_read_b128 v[178:181], v145 offset:16384
	ds_read_b128 v[182:185], v145 offset:17408
	ds_read_b128 v[186:189], v145 offset:18432
	ds_read_b128 v[190:193], v145 offset:19456
	ds_read_b128 v[206:209], v145 offset:23552
	ds_read_b128 v[202:205], v145 offset:22528
	ds_read_b128 v[198:201], v145 offset:21504
	ds_read_b128 v[194:197], v145 offset:20480
	s_waitcnt vmcnt(8)
	s_waitcnt lgkmcnt(0)
	s_barrier
	v_mfma_f32_16x16x32_bf16 v[60:63], v[138:141], v[178:181], v[60:63]
	v_mfma_f32_16x16x32_bf16 v[56:59], v[150:153], v[178:181], v[56:59]
	v_mfma_f32_16x16x32_bf16 v[44:47], v[138:141], v[186:189], v[44:47]
	v_mfma_f32_16x16x32_bf16 v[40:43], v[150:153], v[186:189], v[40:43]
	v_mfma_f32_16x16x32_bf16 v[28:31], v[138:141], v[194:197], v[28:31]
	v_mfma_f32_16x16x32_bf16 v[24:27], v[150:153], v[194:197], v[24:27]
	v_mfma_f32_16x16x32_bf16 v[12:15], v[138:141], v[202:205], v[12:15]
	v_mfma_f32_16x16x32_bf16 v[8:11], v[150:153], v[202:205], v[8:11]
	v_mfma_f32_16x16x32_bf16 v[60:63], v[146:149], v[182:185], v[60:63]
	v_mfma_f32_16x16x32_bf16 v[56:59], v[154:157], v[182:185], v[56:59]
	v_mfma_f32_16x16x32_bf16 v[44:47], v[146:149], v[190:193], v[44:47]
	v_mfma_f32_16x16x32_bf16 v[40:43], v[154:157], v[190:193], v[40:43]
	v_mfma_f32_16x16x32_bf16 v[28:31], v[146:149], v[198:201], v[28:31]
	v_mfma_f32_16x16x32_bf16 v[24:27], v[154:157], v[198:201], v[24:27]
	v_mfma_f32_16x16x32_bf16 v[12:15], v[146:149], v[206:209], v[12:15]
	v_mfma_f32_16x16x32_bf16 v[8:11], v[154:157], v[206:209], v[8:11]
	v_mfma_f32_16x16x32_bf16 v[52:55], v[162:165], v[178:181], v[52:55]
	v_mfma_f32_16x16x32_bf16 v[48:51], v[170:173], v[178:181], v[48:51]
	v_mfma_f32_16x16x32_bf16 v[36:39], v[162:165], v[186:189], v[36:39]
	v_mfma_f32_16x16x32_bf16 v[32:35], v[170:173], v[186:189], v[32:35]
	v_mfma_f32_16x16x32_bf16 v[20:23], v[162:165], v[194:197], v[20:23]
	v_mfma_f32_16x16x32_bf16 v[16:19], v[170:173], v[194:197], v[16:19]
	v_mfma_f32_16x16x32_bf16 v[4:7], v[162:165], v[202:205], v[4:7]
	v_mfma_f32_16x16x32_bf16 v[0:3], v[170:173], v[202:205], v[0:3]
	v_mfma_f32_16x16x32_bf16 v[52:55], v[166:169], v[182:185], v[52:55]
	v_mfma_f32_16x16x32_bf16 v[48:51], v[174:177], v[182:185], v[48:51]
	v_mfma_f32_16x16x32_bf16 v[36:39], v[166:169], v[190:193], v[36:39]
	v_mfma_f32_16x16x32_bf16 v[32:35], v[174:177], v[190:193], v[32:35]
	v_mfma_f32_16x16x32_bf16 v[20:23], v[166:169], v[198:201], v[20:23]
	v_mfma_f32_16x16x32_bf16 v[16:19], v[174:177], v[198:201], v[16:19]
	v_mfma_f32_16x16x32_bf16 v[4:7], v[166:169], v[206:209], v[4:7]
	v_mfma_f32_16x16x32_bf16 v[0:3], v[174:177], v[206:209], v[0:3]
	s_barrier
	s_add_i32 s48, 0, 0x18000
	s_add_i32 s49, 0, 0x1c000
	v_add_u32_e32 v154, s48, v143
	v_add_u32_e32 v174, s49, v143
	s_mov_b64 s[100:101], s[14:15]
	s_add_u32 s14, s14, 0x40000
	s_addc_u32 s15, s15, 0
	s_mov_b32 m0, s30
	s_nop 0
	global_load_lds_dwordx4 v128, s[14:15]
	s_mov_b32 m0, s31
	s_nop 0
	global_load_lds_dwordx4 v130, s[14:15]
	ds_read_b128 v[138:141], v154
	ds_read_b128 v[146:149], v154 offset:1024
	ds_read_b128 v[150:153], v154 offset:2048
	ds_read_b128 v[154:157], v154 offset:3072
	ds_read_b128 v[162:165], v174
	ds_read_b128 v[166:169], v174 offset:1024
	ds_read_b128 v[170:173], v174 offset:2048
	ds_read_b128 v[174:177], v174 offset:3072
	ds_read_b128 v[178:181], v145 offset:32768
	ds_read_b128 v[182:185], v145 offset:33792
	ds_read_b128 v[186:189], v145 offset:34816
	ds_read_b128 v[190:193], v145 offset:35840
	ds_read_b128 v[194:197], v145 offset:36864
	ds_read_b128 v[198:201], v145 offset:37888
	ds_read_b128 v[202:205], v145 offset:38912
	ds_read_b128 v[206:209], v145 offset:39936
	s_waitcnt vmcnt(8)
	s_waitcnt lgkmcnt(0)
	s_barrier
	v_mfma_f32_16x16x32_bf16 v[124:127], v[138:141], v[178:181], v[124:127]
	v_mfma_f32_16x16x32_bf16 v[120:123], v[150:153], v[178:181], v[120:123]
	v_mfma_f32_16x16x32_bf16 v[108:111], v[138:141], v[186:189], v[108:111]
	v_mfma_f32_16x16x32_bf16 v[104:107], v[150:153], v[186:189], v[104:107]
	v_mfma_f32_16x16x32_bf16 v[92:95], v[138:141], v[194:197], v[92:95]
	v_mfma_f32_16x16x32_bf16 v[88:91], v[150:153], v[194:197], v[88:91]
	v_mfma_f32_16x16x32_bf16 v[76:79], v[138:141], v[202:205], v[76:79]
	v_mfma_f32_16x16x32_bf16 v[72:75], v[150:153], v[202:205], v[72:75]
	v_mfma_f32_16x16x32_bf16 v[124:127], v[146:149], v[182:185], v[124:127]
	v_mfma_f32_16x16x32_bf16 v[120:123], v[154:157], v[182:185], v[120:123]
	v_mfma_f32_16x16x32_bf16 v[108:111], v[146:149], v[190:193], v[108:111]
	v_mfma_f32_16x16x32_bf16 v[104:107], v[154:157], v[190:193], v[104:107]
	v_mfma_f32_16x16x32_bf16 v[92:95], v[146:149], v[198:201], v[92:95]
	v_mfma_f32_16x16x32_bf16 v[88:91], v[154:157], v[198:201], v[88:91]
	v_mfma_f32_16x16x32_bf16 v[76:79], v[146:149], v[206:209], v[76:79]
	v_mfma_f32_16x16x32_bf16 v[72:75], v[154:157], v[206:209], v[72:75]
	v_mfma_f32_16x16x32_bf16 v[116:119], v[162:165], v[178:181], v[116:119]
	v_mfma_f32_16x16x32_bf16 v[112:115], v[170:173], v[178:181], v[112:115]
	v_mfma_f32_16x16x32_bf16 v[100:103], v[162:165], v[186:189], v[100:103]
	v_mfma_f32_16x16x32_bf16 v[96:99], v[170:173], v[186:189], v[96:99]
	v_mfma_f32_16x16x32_bf16 v[84:87], v[162:165], v[194:197], v[84:87]
	v_mfma_f32_16x16x32_bf16 v[80:83], v[170:173], v[194:197], v[80:83]
	v_mfma_f32_16x16x32_bf16 v[68:71], v[162:165], v[202:205], v[68:71]
	v_mfma_f32_16x16x32_bf16 v[64:67], v[170:173], v[202:205], v[64:67]
	v_mfma_f32_16x16x32_bf16 v[116:119], v[166:169], v[182:185], v[116:119]
	v_mfma_f32_16x16x32_bf16 v[112:115], v[174:177], v[182:185], v[112:115]
	v_mfma_f32_16x16x32_bf16 v[100:103], v[166:169], v[190:193], v[100:103]
	v_mfma_f32_16x16x32_bf16 v[96:99], v[174:177], v[190:193], v[96:99]
	v_mfma_f32_16x16x32_bf16 v[84:87], v[166:169], v[198:201], v[84:87]
	v_mfma_f32_16x16x32_bf16 v[80:83], v[174:177], v[198:201], v[80:83]
	v_mfma_f32_16x16x32_bf16 v[68:71], v[166:169], v[206:209], v[68:71]
	v_mfma_f32_16x16x32_bf16 v[64:67], v[174:177], v[206:209], v[64:67]
	s_barrier
	s_add_i32 s14, s48, s28
	s_add_i32 m0, s14, 0xffffff80
	s_nop 0
	global_load_lds_dwordx4 v160, s[12:13] offset:128
	s_add_i32 m0, s14, 0x1f80
	s_nop 0
	global_load_lds_dwordx4 v132, s[12:13] offset:128
	s_add_u32 s12, s12, 0x40080
	s_addc_u32 s13, s13, 0
	s_add_i32 s14, s49, s28
	s_mov_b32 m0, s14
	s_nop 0
	global_load_lds_dwordx4 v160, s[12:13]
	s_add_i32 m0, s14, 0x2000
	s_nop 0
	global_load_lds_dwordx4 v132, s[12:13]
	s_add_i32 m0, s33, 0xffffff80
	s_nop 0
	global_load_lds_dwordx4 v128, s[100:101] offset:128
	s_add_i32 m0, s34, 0xffffff80
	s_nop 0
	global_load_lds_dwordx4 v130, s[100:101] offset:128
	ds_read_b128 v[178:181], v145 offset:49152
	ds_read_b128 v[182:185], v145 offset:50176
	ds_read_b128 v[186:189], v145 offset:51200
	ds_read_b128 v[206:209], v145 offset:56320
	ds_read_b128 v[202:205], v145 offset:55296
	ds_read_b128 v[198:201], v145 offset:54272
	ds_read_b128 v[194:197], v145 offset:53248
	ds_read_b128 v[190:193], v145 offset:52224
	s_waitcnt vmcnt(8)
	s_waitcnt lgkmcnt(0)
	s_barrier
	v_mfma_f32_16x16x32_bf16 v[60:63], v[138:141], v[178:181], v[60:63]
	v_mfma_f32_16x16x32_bf16 v[56:59], v[150:153], v[178:181], v[56:59]
	v_mfma_f32_16x16x32_bf16 v[44:47], v[138:141], v[186:189], v[44:47]
	v_mfma_f32_16x16x32_bf16 v[40:43], v[150:153], v[186:189], v[40:43]
	v_mfma_f32_16x16x32_bf16 v[28:31], v[138:141], v[194:197], v[28:31]
	v_mfma_f32_16x16x32_bf16 v[24:27], v[150:153], v[194:197], v[24:27]
	v_mfma_f32_16x16x32_bf16 v[12:15], v[138:141], v[202:205], v[12:15]
	v_mfma_f32_16x16x32_bf16 v[8:11], v[150:153], v[202:205], v[8:11]
	v_mfma_f32_16x16x32_bf16 v[60:63], v[146:149], v[182:185], v[60:63]
	v_mfma_f32_16x16x32_bf16 v[56:59], v[154:157], v[182:185], v[56:59]
	v_mfma_f32_16x16x32_bf16 v[44:47], v[146:149], v[190:193], v[44:47]
	v_mfma_f32_16x16x32_bf16 v[40:43], v[154:157], v[190:193], v[40:43]
	v_mfma_f32_16x16x32_bf16 v[28:31], v[146:149], v[198:201], v[28:31]
	v_mfma_f32_16x16x32_bf16 v[24:27], v[154:157], v[198:201], v[24:27]
	v_mfma_f32_16x16x32_bf16 v[12:15], v[146:149], v[206:209], v[12:15]
	v_mfma_f32_16x16x32_bf16 v[8:11], v[154:157], v[206:209], v[8:11]
	v_mfma_f32_16x16x32_bf16 v[52:55], v[162:165], v[178:181], v[52:55]
	v_mfma_f32_16x16x32_bf16 v[48:51], v[170:173], v[178:181], v[48:51]
	v_mfma_f32_16x16x32_bf16 v[36:39], v[162:165], v[186:189], v[36:39]
	v_mfma_f32_16x16x32_bf16 v[32:35], v[170:173], v[186:189], v[32:35]
	v_mfma_f32_16x16x32_bf16 v[20:23], v[162:165], v[194:197], v[20:23]
	v_mfma_f32_16x16x32_bf16 v[16:19], v[170:173], v[194:197], v[16:19]
	v_mfma_f32_16x16x32_bf16 v[4:7], v[162:165], v[202:205], v[4:7]
	v_mfma_f32_16x16x32_bf16 v[0:3], v[170:173], v[202:205], v[0:3]
	v_mfma_f32_16x16x32_bf16 v[52:55], v[166:169], v[182:185], v[52:55]
	v_mfma_f32_16x16x32_bf16 v[48:51], v[174:177], v[182:185], v[48:51]
	v_mfma_f32_16x16x32_bf16 v[36:39], v[166:169], v[190:193], v[36:39]
	v_mfma_f32_16x16x32_bf16 v[32:35], v[174:177], v[190:193], v[32:35]
	v_mfma_f32_16x16x32_bf16 v[20:23], v[166:169], v[198:201], v[20:23]
	v_mfma_f32_16x16x32_bf16 v[16:19], v[174:177], v[198:201], v[16:19]
	v_mfma_f32_16x16x32_bf16 v[4:7], v[166:169], v[206:209], v[4:7]
	v_mfma_f32_16x16x32_bf16 v[0:3], v[174:177], v[206:209], v[0:3]
	s_barrier
	s_add_i32 s22, s22, 2
	s_add_u32 s90, s90, 0x100
	s_addc_u32 s21, s21, 0
	s_add_u32 vcc_lo, vcc_lo, 0x100
	s_addc_u32 vcc_hi, vcc_hi, 0
	s_cmp_gt_u32 s22, 13
	s_cbranch_scc0 .LBB0_84
	v_lshl_add_u32 v140, s8, 8, v142
	v_lshl_or_b32 v138, s10, 8, v144
	v_lshlrev_b32_e32 v141, 11, v140
	v_lshl_add_u32 v138, v138, 1, v141
	v_lshlrev_b32_e32 v139, 3, v140
	s_mov_b64 s[8:9], s[2:3]
	global_load_dwordx4 v[146:149], v138, s[8:9]
	global_load_dwordx4 v[150:153], v138, s[8:9] offset:256
	s_add_u32 s8, s8, 0x8000
	s_addc_u32 s9, s9, 0
	global_load_dwordx4 v[154:157], v138, s[8:9]
	global_load_dwordx4 v[162:165], v138, s[8:9] offset:256
	s_add_u32 s8, s8, 0x8000
	s_addc_u32 s9, s9, 0
	global_load_dwordx4 v[166:169], v138, s[8:9]
	global_load_dwordx4 v[174:177], v138, s[8:9] offset:256
	s_add_u32 s8, s8, 0x8000
	s_addc_u32 s9, s9, 0
	global_load_dwordx4 v[178:181], v138, s[8:9]
	global_load_dwordx4 v[182:185], v138, s[8:9] offset:256
	s_add_u32 s8, s8, 0x28000
	s_addc_u32 s9, s9, 0
	global_load_dwordx4 v[186:189], v138, s[8:9]
	global_load_dwordx4 v[190:193], v138, s[8:9] offset:256
	s_add_u32 s8, s8, 0x8000
	s_addc_u32 s9, s9, 0
	global_load_dwordx4 v[194:197], v138, s[8:9]
	global_load_dwordx4 v[198:201], v138, s[8:9] offset:256
	s_add_u32 s8, s8, 0x8000
	s_addc_u32 s9, s9, 0
	global_load_dwordx4 v[202:205], v138, s[8:9]
	global_load_dwordx4 v[206:209], v138, s[8:9] offset:256
	s_add_u32 s8, s8, 0x8000
	s_addc_u32 s9, s9, 0
	global_load_dwordx4 v[210:213], v138, s[8:9]
	global_load_dwordx4 v[214:217], v138, s[8:9] offset:256
	s_and_b64 vcc, exec, s[6:7]
	s_cbranch_vccz .LBB0_87
	s_barrier

.LBB0_139:
	s_add_u32 s14, s10, 0xfffc0080
	s_addc_u32 s15, s11, -1
	s_add_i32 s48, 0, 0x10000
	s_cmp_eq_u32 s22, 12
	s_cselect_b32 s93, s9, s15
	s_cselect_b32 s92, s41, s14
	s_cselect_b32 s15, s45, s21
	s_cselect_b32 s14, vcc_lo, vcc_hi
	s_add_i32 s50, 0, 0x14000
	v_add_u32_e32 v140, s48, v202
	v_add_u32_e32 v156, s50, v202
	s_add_i32 m0, s31, 0xc000
	s_nop 0
	global_load_lds_dwordx4 v186, s[10:11]
	s_add_i32 m0, s31, 0xe000
	s_nop 0
	global_load_lds_dwordx4 v184, s[10:11]
	ds_read_b128 v[128:131], v140
	ds_read_b128 v[132:135], v140 offset:1024
	ds_read_b128 v[136:139], v140 offset:2048
	ds_read_b128 v[140:143], v140 offset:3072
	ds_read_b128 v[144:147], v156
	ds_read_b128 v[148:151], v156 offset:1024
	ds_read_b128 v[152:155], v156 offset:2048
	ds_read_b128 v[156:159], v156 offset:3072
	ds_read_b128 v[188:191], v204
	ds_read_b128 v[192:195], v204 offset:1024
	ds_read_b128 v[196:199], v204 offset:2048
	ds_read_b128 v[206:209], v204 offset:3072
	ds_read_b128 v[210:213], v204 offset:4096
	ds_read_b128 v[214:217], v204 offset:5120
	ds_read_b128 v[238:241], v204 offset:6144
	ds_read_b128 v[246:249], v204 offset:7168
	s_waitcnt vmcnt(8)
	s_waitcnt lgkmcnt(0)
	s_barrier
	v_mfma_f32_16x16x32_bf16 v[124:127], v[128:131], v[188:191], v[124:127]
	v_mfma_f32_16x16x32_bf16 v[120:123], v[136:139], v[188:191], v[120:123]
	v_mfma_f32_16x16x32_bf16 v[108:111], v[128:131], v[196:199], v[108:111]
	v_mfma_f32_16x16x32_bf16 v[104:107], v[136:139], v[196:199], v[104:107]
	v_mfma_f32_16x16x32_bf16 v[92:95], v[128:131], v[210:213], v[92:95]
	v_mfma_f32_16x16x32_bf16 v[88:91], v[136:139], v[210:213], v[88:91]
	v_mfma_f32_16x16x32_bf16 v[76:79], v[128:131], v[238:241], v[76:79]
	v_mfma_f32_16x16x32_bf16 v[72:75], v[136:139], v[238:241], v[72:75]
	v_mfma_f32_16x16x32_bf16 v[124:127], v[132:135], v[192:195], v[124:127]
	v_mfma_f32_16x16x32_bf16 v[120:123], v[140:143], v[192:195], v[120:123]
	v_mfma_f32_16x16x32_bf16 v[108:111], v[132:135], v[206:209], v[108:111]
	v_mfma_f32_16x16x32_bf16 v[104:107], v[140:143], v[206:209], v[104:107]
	v_mfma_f32_16x16x32_bf16 v[92:95], v[132:135], v[214:217], v[92:95]
	v_mfma_f32_16x16x32_bf16 v[88:91], v[140:143], v[214:217], v[88:91]
	v_mfma_f32_16x16x32_bf16 v[76:79], v[132:135], v[246:249], v[76:79]
	v_mfma_f32_16x16x32_bf16 v[72:75], v[140:143], v[246:249], v[72:75]
	v_mfma_f32_16x16x32_bf16 v[116:119], v[144:147], v[188:191], v[116:119]
	v_mfma_f32_16x16x32_bf16 v[112:115], v[152:155], v[188:191], v[112:115]
	v_mfma_f32_16x16x32_bf16 v[100:103], v[144:147], v[196:199], v[100:103]
	v_mfma_f32_16x16x32_bf16 v[96:99], v[152:155], v[196:199], v[96:99]
	v_mfma_f32_16x16x32_bf16 v[84:87], v[144:147], v[210:213], v[84:87]
	v_mfma_f32_16x16x32_bf16 v[80:83], v[152:155], v[210:213], v[80:83]
	v_mfma_f32_16x16x32_bf16 v[68:71], v[144:147], v[238:241], v[68:71]
	v_mfma_f32_16x16x32_bf16 v[64:67], v[152:155], v[238:241], v[64:67]
	v_mfma_f32_16x16x32_bf16 v[116:119], v[148:151], v[192:195], v[116:119]
	v_mfma_f32_16x16x32_bf16 v[112:115], v[156:159], v[192:195], v[112:115]
	v_mfma_f32_16x16x32_bf16 v[100:103], v[148:151], v[206:209], v[100:103]
	v_mfma_f32_16x16x32_bf16 v[96:99], v[156:159], v[206:209], v[96:99]
	v_mfma_f32_16x16x32_bf16 v[84:87], v[148:151], v[214:217], v[84:87]
	v_mfma_f32_16x16x32_bf16 v[80:83], v[156:159], v[214:217], v[80:83]
	v_mfma_f32_16x16x32_bf16 v[68:71], v[148:151], v[246:249], v[68:71]
	v_mfma_f32_16x16x32_bf16 v[64:67], v[156:159], v[246:249], v[64:67]
	s_barrier
	s_add_i32 s48, s48, s29
	s_mov_b32 m0, s48
	s_nop 0
	global_load_lds_dwordx4 v178, s[14:15]
	s_add_i32 m0, s48, 0x2000
	s_add_u32 s48, s14, 0x40000
	s_addc_u32 s49, s15, 0
	s_add_i32 s50, s50, s29
	global_load_lds_dwordx4 v174, s[14:15]
	s_mov_b32 m0, s50
	s_nop 0
	global_load_lds_dwordx4 v178, s[48:49]
	s_add_i32 m0, s50, 0x2000
	s_nop 0
	global_load_lds_dwordx4 v174, s[48:49]
	s_mov_b32 m0, s31
	s_nop 0
	global_load_lds_dwordx4 v180, s[92:93]
	s_mov_b32 m0, s34
	s_nop 0
	global_load_lds_dwordx4 v176, s[92:93]
	ds_read_b128 v[188:191], v204 offset:16384
	ds_read_b128 v[192:195], v204 offset:17408
	ds_read_b128 v[196:199], v204 offset:18432
	ds_read_b128 v[206:209], v204 offset:19456
	ds_read_b128 v[246:249], v204 offset:23552
	ds_read_b128 v[238:241], v204 offset:22528
	ds_read_b128 v[214:217], v204 offset:21504
	ds_read_b128 v[210:213], v204 offset:20480
	s_waitcnt vmcnt(8)
	s_waitcnt lgkmcnt(0)
	s_barrier
	v_mfma_f32_16x16x32_bf16 v[60:63], v[128:131], v[188:191], v[60:63]
	v_mfma_f32_16x16x32_bf16 v[56:59], v[136:139], v[188:191], v[56:59]
	v_mfma_f32_16x16x32_bf16 v[44:47], v[128:131], v[196:199], v[44:47]
	v_mfma_f32_16x16x32_bf16 v[40:43], v[136:139], v[196:199], v[40:43]
	v_mfma_f32_16x16x32_bf16 v[28:31], v[128:131], v[210:213], v[28:31]
	v_mfma_f32_16x16x32_bf16 v[24:27], v[136:139], v[210:213], v[24:27]
	v_mfma_f32_16x16x32_bf16 v[12:15], v[128:131], v[238:241], v[12:15]
	v_mfma_f32_16x16x32_bf16 v[8:11], v[136:139], v[238:241], v[8:11]
	v_mfma_f32_16x16x32_bf16 v[60:63], v[132:135], v[192:195], v[60:63]
	v_mfma_f32_16x16x32_bf16 v[56:59], v[140:143], v[192:195], v[56:59]
	v_mfma_f32_16x16x32_bf16 v[44:47], v[132:135], v[206:209], v[44:47]
	v_mfma_f32_16x16x32_bf16 v[40:43], v[140:143], v[206:209], v[40:43]
	v_mfma_f32_16x16x32_bf16 v[28:31], v[132:135], v[214:217], v[28:31]
	v_mfma_f32_16x16x32_bf16 v[24:27], v[140:143], v[214:217], v[24:27]
	v_mfma_f32_16x16x32_bf16 v[12:15], v[132:135], v[246:249], v[12:15]
	v_mfma_f32_16x16x32_bf16 v[8:11], v[140:143], v[246:249], v[8:11]
	v_mfma_f32_16x16x32_bf16 v[52:55], v[144:147], v[188:191], v[52:55]
	v_mfma_f32_16x16x32_bf16 v[48:51], v[152:155], v[188:191], v[48:51]
	v_mfma_f32_16x16x32_bf16 v[36:39], v[144:147], v[196:199], v[36:39]
	v_mfma_f32_16x16x32_bf16 v[32:35], v[152:155], v[196:199], v[32:35]
	v_mfma_f32_16x16x32_bf16 v[20:23], v[144:147], v[210:213], v[20:23]
	v_mfma_f32_16x16x32_bf16 v[16:19], v[152:155], v[210:213], v[16:19]
	v_mfma_f32_16x16x32_bf16 v[4:7], v[144:147], v[238:241], v[4:7]
	v_mfma_f32_16x16x32_bf16 v[0:3], v[152:155], v[238:241], v[0:3]
	v_mfma_f32_16x16x32_bf16 v[52:55], v[148:151], v[192:195], v[52:55]
	v_mfma_f32_16x16x32_bf16 v[48:51], v[156:159], v[192:195], v[48:51]
	v_mfma_f32_16x16x32_bf16 v[36:39], v[148:151], v[206:209], v[36:39]
	v_mfma_f32_16x16x32_bf16 v[32:35], v[156:159], v[206:209], v[32:35]
	v_mfma_f32_16x16x32_bf16 v[20:23], v[148:151], v[214:217], v[20:23]
	v_mfma_f32_16x16x32_bf16 v[16:19], v[156:159], v[214:217], v[16:19]
	v_mfma_f32_16x16x32_bf16 v[4:7], v[148:151], v[246:249], v[4:7]
	v_mfma_f32_16x16x32_bf16 v[0:3], v[156:159], v[246:249], v[0:3]
	s_barrier
	s_add_i32 s50, 0, 0x18000
	s_add_i32 s51, 0, 0x1c000
	v_add_u32_e32 v140, s50, v202
	v_add_u32_e32 v156, s51, v202
	s_add_u32 s48, s92, 0x40000
	s_addc_u32 s49, s93, 0
	s_mov_b32 m0, s35
	s_nop 0
	global_load_lds_dwordx4 v180, s[48:49]
	s_mov_b32 m0, s90
	s_nop 0
	global_load_lds_dwordx4 v176, s[48:49]
	ds_read_b128 v[128:131], v140
	ds_read_b128 v[132:135], v140 offset:1024
	ds_read_b128 v[136:139], v140 offset:2048
	ds_read_b128 v[140:143], v140 offset:3072
	ds_read_b128 v[144:147], v156
	ds_read_b128 v[148:151], v156 offset:1024
	ds_read_b128 v[152:155], v156 offset:2048
	ds_read_b128 v[156:159], v156 offset:3072
	ds_read_b128 v[188:191], v204 offset:32768
	ds_read_b128 v[192:195], v204 offset:33792
	ds_read_b128 v[196:199], v204 offset:34816
	ds_read_b128 v[206:209], v204 offset:35840
	ds_read_b128 v[210:213], v204 offset:36864
	ds_read_b128 v[214:217], v204 offset:37888
	ds_read_b128 v[238:241], v204 offset:38912
	ds_read_b128 v[246:249], v204 offset:39936
	s_waitcnt vmcnt(8)
	s_waitcnt lgkmcnt(0)
	s_barrier
	v_mfma_f32_16x16x32_bf16 v[124:127], v[128:131], v[188:191], v[124:127]
	v_mfma_f32_16x16x32_bf16 v[120:123], v[136:139], v[188:191], v[120:123]
	v_mfma_f32_16x16x32_bf16 v[108:111], v[128:131], v[196:199], v[108:111]
	v_mfma_f32_16x16x32_bf16 v[104:107], v[136:139], v[196:199], v[104:107]
	v_mfma_f32_16x16x32_bf16 v[92:95], v[128:131], v[210:213], v[92:95]
	v_mfma_f32_16x16x32_bf16 v[88:91], v[136:139], v[210:213], v[88:91]
	v_mfma_f32_16x16x32_bf16 v[76:79], v[128:131], v[238:241], v[76:79]
	v_mfma_f32_16x16x32_bf16 v[72:75], v[136:139], v[238:241], v[72:75]
	v_mfma_f32_16x16x32_bf16 v[124:127], v[132:135], v[192:195], v[124:127]
	v_mfma_f32_16x16x32_bf16 v[120:123], v[140:143], v[192:195], v[120:123]
	v_mfma_f32_16x16x32_bf16 v[108:111], v[132:135], v[206:209], v[108:111]
	v_mfma_f32_16x16x32_bf16 v[104:107], v[140:143], v[206:209], v[104:107]
	v_mfma_f32_16x16x32_bf16 v[92:95], v[132:135], v[214:217], v[92:95]
	v_mfma_f32_16x16x32_bf16 v[88:91], v[140:143], v[214:217], v[88:91]
	v_mfma_f32_16x16x32_bf16 v[76:79], v[132:135], v[246:249], v[76:79]
	v_mfma_f32_16x16x32_bf16 v[72:75], v[140:143], v[246:249], v[72:75]
	v_mfma_f32_16x16x32_bf16 v[116:119], v[144:147], v[188:191], v[116:119]
	v_mfma_f32_16x16x32_bf16 v[112:115], v[152:155], v[188:191], v[112:115]
	v_mfma_f32_16x16x32_bf16 v[100:103], v[144:147], v[196:199], v[100:103]
	v_mfma_f32_16x16x32_bf16 v[96:99], v[152:155], v[196:199], v[96:99]
	v_mfma_f32_16x16x32_bf16 v[84:87], v[144:147], v[210:213], v[84:87]
	v_mfma_f32_16x16x32_bf16 v[80:83], v[152:155], v[210:213], v[80:83]
	v_mfma_f32_16x16x32_bf16 v[68:71], v[144:147], v[238:241], v[68:71]
	v_mfma_f32_16x16x32_bf16 v[64:67], v[152:155], v[238:241], v[64:67]
	v_mfma_f32_16x16x32_bf16 v[116:119], v[148:151], v[192:195], v[116:119]
	v_mfma_f32_16x16x32_bf16 v[112:115], v[156:159], v[192:195], v[112:115]
	v_mfma_f32_16x16x32_bf16 v[100:103], v[148:151], v[206:209], v[100:103]
	v_mfma_f32_16x16x32_bf16 v[96:99], v[156:159], v[206:209], v[96:99]
	v_mfma_f32_16x16x32_bf16 v[84:87], v[148:151], v[214:217], v[84:87]
	v_mfma_f32_16x16x32_bf16 v[80:83], v[156:159], v[214:217], v[80:83]
	v_mfma_f32_16x16x32_bf16 v[68:71], v[148:151], v[246:249], v[68:71]
	v_mfma_f32_16x16x32_bf16 v[64:67], v[156:159], v[246:249], v[64:67]
	s_barrier
	s_add_i32 s48, s50, s29
	s_add_i32 m0, s48, 0xffffff80
	s_nop 0
	global_load_lds_dwordx4 v178, s[14:15] offset:128
	s_add_i32 m0, s48, 0x1f80
	s_nop 0
	global_load_lds_dwordx4 v174, s[14:15] offset:128
	s_add_u32 s14, s14, 0x40080
	s_addc_u32 s15, s15, 0
	s_add_i32 s48, s51, s29
	s_mov_b32 m0, s48
	s_nop 0
	global_load_lds_dwordx4 v178, s[14:15]
	s_add_i32 m0, s48, 0x2000
	s_nop 0
	global_load_lds_dwordx4 v174, s[14:15]
	s_add_i32 m0, s19, 0xffffff80
	s_nop 0
	global_load_lds_dwordx4 v180, s[92:93] offset:128
	s_add_i32 m0, s33, 0xffffff80
	s_nop 0
	global_load_lds_dwordx4 v176, s[92:93] offset:128
	ds_read_b128 v[188:191], v204 offset:49152
	ds_read_b128 v[192:195], v204 offset:50176
	ds_read_b128 v[196:199], v204 offset:51200
	ds_read_b128 v[246:249], v204 offset:56320
	ds_read_b128 v[238:241], v204 offset:55296
	ds_read_b128 v[214:217], v204 offset:54272
	ds_read_b128 v[210:213], v204 offset:53248
	ds_read_b128 v[206:209], v204 offset:52224
	s_waitcnt vmcnt(8)
	s_waitcnt lgkmcnt(0)
	s_barrier
	v_mfma_f32_16x16x32_bf16 v[60:63], v[128:131], v[188:191], v[60:63]
	v_mfma_f32_16x16x32_bf16 v[56:59], v[136:139], v[188:191], v[56:59]
	v_mfma_f32_16x16x32_bf16 v[44:47], v[128:131], v[196:199], v[44:47]
	v_mfma_f32_16x16x32_bf16 v[40:43], v[136:139], v[196:199], v[40:43]
	v_mfma_f32_16x16x32_bf16 v[28:31], v[128:131], v[210:213], v[28:31]
	v_mfma_f32_16x16x32_bf16 v[24:27], v[136:139], v[210:213], v[24:27]
	v_mfma_f32_16x16x32_bf16 v[12:15], v[128:131], v[238:241], v[12:15]
	v_mfma_f32_16x16x32_bf16 v[8:11], v[136:139], v[238:241], v[8:11]
	v_mfma_f32_16x16x32_bf16 v[60:63], v[132:135], v[192:195], v[60:63]
	v_mfma_f32_16x16x32_bf16 v[56:59], v[140:143], v[192:195], v[56:59]
	v_mfma_f32_16x16x32_bf16 v[44:47], v[132:135], v[206:209], v[44:47]
	v_mfma_f32_16x16x32_bf16 v[40:43], v[140:143], v[206:209], v[40:43]
	v_mfma_f32_16x16x32_bf16 v[28:31], v[132:135], v[214:217], v[28:31]
	v_mfma_f32_16x16x32_bf16 v[24:27], v[140:143], v[214:217], v[24:27]
	v_mfma_f32_16x16x32_bf16 v[12:15], v[132:135], v[246:249], v[12:15]
	v_mfma_f32_16x16x32_bf16 v[8:11], v[140:143], v[246:249], v[8:11]
	v_mfma_f32_16x16x32_bf16 v[52:55], v[144:147], v[188:191], v[52:55]
	v_mfma_f32_16x16x32_bf16 v[48:51], v[152:155], v[188:191], v[48:51]
	v_mfma_f32_16x16x32_bf16 v[36:39], v[144:147], v[196:199], v[36:39]
	v_mfma_f32_16x16x32_bf16 v[32:35], v[152:155], v[196:199], v[32:35]
	v_mfma_f32_16x16x32_bf16 v[20:23], v[144:147], v[210:213], v[20:23]
	v_mfma_f32_16x16x32_bf16 v[16:19], v[152:155], v[210:213], v[16:19]
	v_mfma_f32_16x16x32_bf16 v[4:7], v[144:147], v[238:241], v[4:7]
	v_mfma_f32_16x16x32_bf16 v[0:3], v[152:155], v[238:241], v[0:3]
	v_mfma_f32_16x16x32_bf16 v[52:55], v[148:151], v[192:195], v[52:55]
	v_mfma_f32_16x16x32_bf16 v[48:51], v[156:159], v[192:195], v[48:51]
	v_mfma_f32_16x16x32_bf16 v[36:39], v[148:151], v[206:209], v[36:39]
	v_mfma_f32_16x16x32_bf16 v[32:35], v[156:159], v[206:209], v[32:35]
	v_mfma_f32_16x16x32_bf16 v[20:23], v[148:151], v[214:217], v[20:23]
	v_mfma_f32_16x16x32_bf16 v[16:19], v[156:159], v[214:217], v[16:19]
	v_mfma_f32_16x16x32_bf16 v[4:7], v[148:151], v[246:249], v[4:7]
	v_mfma_f32_16x16x32_bf16 v[0:3], v[156:159], v[246:249], v[0:3]
	s_barrier
	s_add_i32 s22, s22, 2
	s_add_u32 vcc_hi, vcc_hi, 0x100
	s_addc_u32 s21, s21, 0
	s_add_u32 s10, s10, 0x100
	s_addc_u32 s11, s11, 0
	s_cmp_gt_u32 s22, 13
	s_cbranch_scc0 .LBB0_139
	s_and_b64 vcc, exec, s[36:37]
	s_cbranch_vccz .LBB0_142
	s_barrier

.LBB0_178:
	s_add_u32 s10, s8, 0x100
	s_addc_u32 s11, s9, 0
	s_add_i32 s48, 0, 0x10000
	s_cmp_eq_u32 s22, 40
	s_cselect_b32 s15, s1, s11
	s_cselect_b32 s14, s0, s10
	s_cselect_b32 s13, s45, s96
	s_cselect_b32 s12, s44, s21
	s_add_i32 s49, 0, 0x14000
	v_add_u32_e32 v154, s48, v143
	v_add_u32_e32 v158, s49, v143
	s_add_i32 m0, s29, 0xc000
	s_nop 0
	global_load_lds_dwordx4 v136, s[8:9]
	s_add_i32 m0, s29, 0xe000
	s_nop 0
	global_load_lds_dwordx4 v134, s[8:9]
	ds_read_b128 v[138:141], v154
	ds_read_b128 v[146:149], v154 offset:1024
	ds_read_b128 v[150:153], v154 offset:2048
	ds_read_b128 v[154:157], v154 offset:3072
	ds_read_b128 v[174:177], v158
	ds_read_b128 v[178:181], v158 offset:1024
	ds_read_b128 v[182:185], v158 offset:2048
	ds_read_b128 v[186:189], v158 offset:3072
	ds_read_b128 v[190:193], v145
	ds_read_b128 v[194:197], v145 offset:1024
	ds_read_b128 v[198:201], v145 offset:2048
	ds_read_b128 v[202:205], v145 offset:3072
	ds_read_b128 v[206:209], v145 offset:4096
	ds_read_b128 v[210:213], v145 offset:5120
	ds_read_b128 v[214:217], v145 offset:6144
	ds_read_b128 v[238:241], v145 offset:7168
	s_waitcnt vmcnt(8)
	s_waitcnt lgkmcnt(0)
	s_barrier
	v_mfma_f32_16x16x32_bf16 v[124:127], v[138:141], v[190:193], v[124:127]
	v_mfma_f32_16x16x32_bf16 v[120:123], v[150:153], v[190:193], v[120:123]
	v_mfma_f32_16x16x32_bf16 v[108:111], v[138:141], v[198:201], v[108:111]
	v_mfma_f32_16x16x32_bf16 v[104:107], v[150:153], v[198:201], v[104:107]
	v_mfma_f32_16x16x32_bf16 v[92:95], v[138:141], v[206:209], v[92:95]
	v_mfma_f32_16x16x32_bf16 v[88:91], v[150:153], v[206:209], v[88:91]
	v_mfma_f32_16x16x32_bf16 v[76:79], v[138:141], v[214:217], v[76:79]
	v_mfma_f32_16x16x32_bf16 v[72:75], v[150:153], v[214:217], v[72:75]
	v_mfma_f32_16x16x32_bf16 v[124:127], v[146:149], v[194:197], v[124:127]
	v_mfma_f32_16x16x32_bf16 v[120:123], v[154:157], v[194:197], v[120:123]
	v_mfma_f32_16x16x32_bf16 v[108:111], v[146:149], v[202:205], v[108:111]
	v_mfma_f32_16x16x32_bf16 v[104:107], v[154:157], v[202:205], v[104:107]
	v_mfma_f32_16x16x32_bf16 v[92:95], v[146:149], v[210:213], v[92:95]
	v_mfma_f32_16x16x32_bf16 v[88:91], v[154:157], v[210:213], v[88:91]
	v_mfma_f32_16x16x32_bf16 v[76:79], v[146:149], v[238:241], v[76:79]
	v_mfma_f32_16x16x32_bf16 v[72:75], v[154:157], v[238:241], v[72:75]
	v_mfma_f32_16x16x32_bf16 v[116:119], v[174:177], v[190:193], v[116:119]
	v_mfma_f32_16x16x32_bf16 v[112:115], v[182:185], v[190:193], v[112:115]
	v_mfma_f32_16x16x32_bf16 v[100:103], v[174:177], v[198:201], v[100:103]
	v_mfma_f32_16x16x32_bf16 v[96:99], v[182:185], v[198:201], v[96:99]
	v_mfma_f32_16x16x32_bf16 v[84:87], v[174:177], v[206:209], v[84:87]
	v_mfma_f32_16x16x32_bf16 v[80:83], v[182:185], v[206:209], v[80:83]
	v_mfma_f32_16x16x32_bf16 v[68:71], v[174:177], v[214:217], v[68:71]
	v_mfma_f32_16x16x32_bf16 v[64:67], v[182:185], v[214:217], v[64:67]
	v_mfma_f32_16x16x32_bf16 v[116:119], v[178:181], v[194:197], v[116:119]
	v_mfma_f32_16x16x32_bf16 v[112:115], v[186:189], v[194:197], v[112:115]
	v_mfma_f32_16x16x32_bf16 v[100:103], v[178:181], v[202:205], v[100:103]
	v_mfma_f32_16x16x32_bf16 v[96:99], v[186:189], v[202:205], v[96:99]
	v_mfma_f32_16x16x32_bf16 v[84:87], v[178:181], v[210:213], v[84:87]
	v_mfma_f32_16x16x32_bf16 v[80:83], v[186:189], v[210:213], v[80:83]
	v_mfma_f32_16x16x32_bf16 v[68:71], v[178:181], v[238:241], v[68:71]
	v_mfma_f32_16x16x32_bf16 v[64:67], v[186:189], v[238:241], v[64:67]
	s_barrier
	s_add_i32 s8, s48, s28
	s_mov_b32 m0, s8
	s_nop 0
	global_load_lds_dwordx4 v160, s[12:13]
	s_add_i32 m0, s8, 0x2000
	s_add_u32 s8, s12, 0xb0000
	s_addc_u32 s9, s13, 0
	s_add_i32 s48, s49, s28
	global_load_lds_dwordx4 v132, s[12:13]
	s_mov_b32 m0, s48
	s_nop 0
	global_load_lds_dwordx4 v160, s[8:9]
	s_add_i32 m0, s48, 0x2000
	s_nop 0
	global_load_lds_dwordx4 v132, s[8:9]
	s_mov_b32 m0, s29
	s_nop 0
	global_load_lds_dwordx4 v128, s[14:15]
	s_mov_b32 m0, s30
	s_nop 0
	global_load_lds_dwordx4 v130, s[14:15]
	ds_read_b128 v[190:193], v145 offset:16384
	ds_read_b128 v[194:197], v145 offset:17408
	ds_read_b128 v[198:201], v145 offset:18432
	ds_read_b128 v[202:205], v145 offset:19456
	ds_read_b128 v[238:241], v145 offset:23552
	ds_read_b128 v[214:217], v145 offset:22528
	ds_read_b128 v[210:213], v145 offset:21504
	ds_read_b128 v[206:209], v145 offset:20480
	s_waitcnt vmcnt(8)
	s_waitcnt lgkmcnt(0)
	s_barrier
	v_mfma_f32_16x16x32_bf16 v[60:63], v[138:141], v[190:193], v[60:63]
	v_mfma_f32_16x16x32_bf16 v[56:59], v[150:153], v[190:193], v[56:59]
	v_mfma_f32_16x16x32_bf16 v[44:47], v[138:141], v[198:201], v[44:47]
	v_mfma_f32_16x16x32_bf16 v[40:43], v[150:153], v[198:201], v[40:43]
	v_mfma_f32_16x16x32_bf16 v[28:31], v[138:141], v[206:209], v[28:31]
	v_mfma_f32_16x16x32_bf16 v[24:27], v[150:153], v[206:209], v[24:27]
	v_mfma_f32_16x16x32_bf16 v[12:15], v[138:141], v[214:217], v[12:15]
	v_mfma_f32_16x16x32_bf16 v[8:11], v[150:153], v[214:217], v[8:11]
	v_mfma_f32_16x16x32_bf16 v[60:63], v[146:149], v[194:197], v[60:63]
	v_mfma_f32_16x16x32_bf16 v[56:59], v[154:157], v[194:197], v[56:59]
	v_mfma_f32_16x16x32_bf16 v[44:47], v[146:149], v[202:205], v[44:47]
	v_mfma_f32_16x16x32_bf16 v[40:43], v[154:157], v[202:205], v[40:43]
	v_mfma_f32_16x16x32_bf16 v[28:31], v[146:149], v[210:213], v[28:31]
	v_mfma_f32_16x16x32_bf16 v[24:27], v[154:157], v[210:213], v[24:27]
	v_mfma_f32_16x16x32_bf16 v[12:15], v[146:149], v[238:241], v[12:15]
	v_mfma_f32_16x16x32_bf16 v[8:11], v[154:157], v[238:241], v[8:11]
	v_mfma_f32_16x16x32_bf16 v[52:55], v[174:177], v[190:193], v[52:55]
	v_mfma_f32_16x16x32_bf16 v[48:51], v[182:185], v[190:193], v[48:51]
	v_mfma_f32_16x16x32_bf16 v[36:39], v[174:177], v[198:201], v[36:39]
	v_mfma_f32_16x16x32_bf16 v[32:35], v[182:185], v[198:201], v[32:35]
	v_mfma_f32_16x16x32_bf16 v[20:23], v[174:177], v[206:209], v[20:23]
	v_mfma_f32_16x16x32_bf16 v[16:19], v[182:185], v[206:209], v[16:19]
	v_mfma_f32_16x16x32_bf16 v[4:7], v[174:177], v[214:217], v[4:7]
	v_mfma_f32_16x16x32_bf16 v[0:3], v[182:185], v[214:217], v[0:3]
	v_mfma_f32_16x16x32_bf16 v[52:55], v[178:181], v[194:197], v[52:55]
	v_mfma_f32_16x16x32_bf16 v[48:51], v[186:189], v[194:197], v[48:51]
	v_mfma_f32_16x16x32_bf16 v[36:39], v[178:181], v[202:205], v[36:39]
	v_mfma_f32_16x16x32_bf16 v[32:35], v[186:189], v[202:205], v[32:35]
	v_mfma_f32_16x16x32_bf16 v[20:23], v[178:181], v[210:213], v[20:23]
	v_mfma_f32_16x16x32_bf16 v[16:19], v[186:189], v[210:213], v[16:19]
	v_mfma_f32_16x16x32_bf16 v[4:7], v[178:181], v[238:241], v[4:7]
	v_mfma_f32_16x16x32_bf16 v[0:3], v[186:189], v[238:241], v[0:3]
	s_barrier
	s_add_i32 s48, 0, 0x18000
	s_add_i32 s49, 0, 0x1c000
	v_add_u32_e32 v154, s48, v143
	v_add_u32_e32 v168, s49, v143
	s_add_u32 s8, s14, 0xb0000
	s_addc_u32 s9, s15, 0
	s_mov_b32 m0, s31
	s_nop 0
	global_load_lds_dwordx4 v128, s[8:9]
	s_mov_b32 m0, s33
	s_nop 0
	global_load_lds_dwordx4 v130, s[8:9]
	ds_read_b128 v[138:141], v154
	ds_read_b128 v[146:149], v154 offset:1024
	ds_read_b128 v[150:153], v154 offset:2048
	ds_read_b128 v[154:157], v154 offset:3072
	ds_read_b128 v[174:177], v168
	ds_read_b128 v[178:181], v168 offset:1024
	ds_read_b128 v[182:185], v168 offset:2048
	ds_read_b128 v[186:189], v168 offset:3072
	ds_read_b128 v[190:193], v145 offset:32768
	ds_read_b128 v[194:197], v145 offset:33792
	ds_read_b128 v[198:201], v145 offset:34816
	ds_read_b128 v[202:205], v145 offset:35840
	ds_read_b128 v[206:209], v145 offset:36864
	ds_read_b128 v[210:213], v145 offset:37888
	ds_read_b128 v[214:217], v145 offset:38912
	ds_read_b128 v[238:241], v145 offset:39936
	s_waitcnt vmcnt(8)
	s_waitcnt lgkmcnt(0)
	s_barrier
	v_mfma_f32_16x16x32_bf16 v[124:127], v[138:141], v[190:193], v[124:127]
	v_mfma_f32_16x16x32_bf16 v[120:123], v[150:153], v[190:193], v[120:123]
	v_mfma_f32_16x16x32_bf16 v[108:111], v[138:141], v[198:201], v[108:111]
	v_mfma_f32_16x16x32_bf16 v[104:107], v[150:153], v[198:201], v[104:107]
	v_mfma_f32_16x16x32_bf16 v[92:95], v[138:141], v[206:209], v[92:95]
	v_mfma_f32_16x16x32_bf16 v[88:91], v[150:153], v[206:209], v[88:91]
	v_mfma_f32_16x16x32_bf16 v[76:79], v[138:141], v[214:217], v[76:79]
	v_mfma_f32_16x16x32_bf16 v[72:75], v[150:153], v[214:217], v[72:75]
	v_mfma_f32_16x16x32_bf16 v[124:127], v[146:149], v[194:197], v[124:127]
	v_mfma_f32_16x16x32_bf16 v[120:123], v[154:157], v[194:197], v[120:123]
	v_mfma_f32_16x16x32_bf16 v[108:111], v[146:149], v[202:205], v[108:111]
	v_mfma_f32_16x16x32_bf16 v[104:107], v[154:157], v[202:205], v[104:107]
	v_mfma_f32_16x16x32_bf16 v[92:95], v[146:149], v[210:213], v[92:95]
	v_mfma_f32_16x16x32_bf16 v[88:91], v[154:157], v[210:213], v[88:91]
	v_mfma_f32_16x16x32_bf16 v[76:79], v[146:149], v[238:241], v[76:79]
	v_mfma_f32_16x16x32_bf16 v[72:75], v[154:157], v[238:241], v[72:75]
	v_mfma_f32_16x16x32_bf16 v[116:119], v[174:177], v[190:193], v[116:119]
	v_mfma_f32_16x16x32_bf16 v[112:115], v[182:185], v[190:193], v[112:115]
	v_mfma_f32_16x16x32_bf16 v[100:103], v[174:177], v[198:201], v[100:103]
	v_mfma_f32_16x16x32_bf16 v[96:99], v[182:185], v[198:201], v[96:99]
	v_mfma_f32_16x16x32_bf16 v[84:87], v[174:177], v[206:209], v[84:87]
	v_mfma_f32_16x16x32_bf16 v[80:83], v[182:185], v[206:209], v[80:83]
	v_mfma_f32_16x16x32_bf16 v[68:71], v[174:177], v[214:217], v[68:71]
	v_mfma_f32_16x16x32_bf16 v[64:67], v[182:185], v[214:217], v[64:67]
	v_mfma_f32_16x16x32_bf16 v[116:119], v[178:181], v[194:197], v[116:119]
	v_mfma_f32_16x16x32_bf16 v[112:115], v[186:189], v[194:197], v[112:115]
	v_mfma_f32_16x16x32_bf16 v[100:103], v[178:181], v[202:205], v[100:103]
	v_mfma_f32_16x16x32_bf16 v[96:99], v[186:189], v[202:205], v[96:99]
	v_mfma_f32_16x16x32_bf16 v[84:87], v[178:181], v[210:213], v[84:87]
	v_mfma_f32_16x16x32_bf16 v[80:83], v[186:189], v[210:213], v[80:83]
	v_mfma_f32_16x16x32_bf16 v[68:71], v[178:181], v[238:241], v[68:71]
	v_mfma_f32_16x16x32_bf16 v[64:67], v[186:189], v[238:241], v[64:67]
	s_barrier
	s_add_i32 s8, s48, s28
	s_add_i32 m0, s8, 0xffffff80
	s_nop 0
	global_load_lds_dwordx4 v160, s[12:13] offset:128
	s_add_i32 m0, s8, 0x1f80
	s_add_u32 s8, s12, 0xb0080
	s_addc_u32 s9, s13, 0
	global_load_lds_dwordx4 v132, s[12:13] offset:128
	s_add_i32 s12, s49, s28
	s_mov_b32 m0, s12
	s_nop 0
	global_load_lds_dwordx4 v160, s[8:9]
	s_add_i32 m0, s12, 0x2000
	s_nop 0
	global_load_lds_dwordx4 v132, s[8:9]
	s_add_i32 m0, s34, 0xffffff80
	s_nop 0
	global_load_lds_dwordx4 v128, s[14:15] offset:128
	s_add_i32 m0, s35, 0xffffff80
	s_nop 0
	global_load_lds_dwordx4 v130, s[14:15] offset:128
	ds_read_b128 v[190:193], v145 offset:49152
	ds_read_b128 v[194:197], v145 offset:50176
	ds_read_b128 v[198:201], v145 offset:51200
	ds_read_b128 v[202:205], v145 offset:52224
	ds_read_b128 v[238:241], v145 offset:56320
	ds_read_b128 v[214:217], v145 offset:55296
	ds_read_b128 v[210:213], v145 offset:54272
	ds_read_b128 v[206:209], v145 offset:53248
	s_waitcnt vmcnt(8)
	s_waitcnt lgkmcnt(0)
	s_barrier
	v_mfma_f32_16x16x32_bf16 v[60:63], v[138:141], v[190:193], v[60:63]
	v_mfma_f32_16x16x32_bf16 v[56:59], v[150:153], v[190:193], v[56:59]
	v_mfma_f32_16x16x32_bf16 v[44:47], v[138:141], v[198:201], v[44:47]
	v_mfma_f32_16x16x32_bf16 v[40:43], v[150:153], v[198:201], v[40:43]
	v_mfma_f32_16x16x32_bf16 v[28:31], v[138:141], v[206:209], v[28:31]
	v_mfma_f32_16x16x32_bf16 v[24:27], v[150:153], v[206:209], v[24:27]
	v_mfma_f32_16x16x32_bf16 v[12:15], v[138:141], v[214:217], v[12:15]
	v_mfma_f32_16x16x32_bf16 v[8:11], v[150:153], v[214:217], v[8:11]
	v_mfma_f32_16x16x32_bf16 v[60:63], v[146:149], v[194:197], v[60:63]
	v_mfma_f32_16x16x32_bf16 v[56:59], v[154:157], v[194:197], v[56:59]
	v_mfma_f32_16x16x32_bf16 v[44:47], v[146:149], v[202:205], v[44:47]
	v_mfma_f32_16x16x32_bf16 v[40:43], v[154:157], v[202:205], v[40:43]
	v_mfma_f32_16x16x32_bf16 v[28:31], v[146:149], v[210:213], v[28:31]
	v_mfma_f32_16x16x32_bf16 v[24:27], v[154:157], v[210:213], v[24:27]
	v_mfma_f32_16x16x32_bf16 v[12:15], v[146:149], v[238:241], v[12:15]
	v_mfma_f32_16x16x32_bf16 v[8:11], v[154:157], v[238:241], v[8:11]
	v_mfma_f32_16x16x32_bf16 v[52:55], v[174:177], v[190:193], v[52:55]
	v_mfma_f32_16x16x32_bf16 v[48:51], v[182:185], v[190:193], v[48:51]
	v_mfma_f32_16x16x32_bf16 v[36:39], v[174:177], v[198:201], v[36:39]
	v_mfma_f32_16x16x32_bf16 v[32:35], v[182:185], v[198:201], v[32:35]
	v_mfma_f32_16x16x32_bf16 v[20:23], v[174:177], v[206:209], v[20:23]
	v_mfma_f32_16x16x32_bf16 v[16:19], v[182:185], v[206:209], v[16:19]
	v_mfma_f32_16x16x32_bf16 v[4:7], v[174:177], v[214:217], v[4:7]
	v_mfma_f32_16x16x32_bf16 v[0:3], v[182:185], v[214:217], v[0:3]
	v_mfma_f32_16x16x32_bf16 v[52:55], v[178:181], v[194:197], v[52:55]
	v_mfma_f32_16x16x32_bf16 v[48:51], v[186:189], v[194:197], v[48:51]
	v_mfma_f32_16x16x32_bf16 v[36:39], v[178:181], v[202:205], v[36:39]
	v_mfma_f32_16x16x32_bf16 v[32:35], v[186:189], v[202:205], v[32:35]
	v_mfma_f32_16x16x32_bf16 v[20:23], v[178:181], v[210:213], v[20:23]
	v_mfma_f32_16x16x32_bf16 v[16:19], v[186:189], v[210:213], v[16:19]
	v_mfma_f32_16x16x32_bf16 v[4:7], v[178:181], v[238:241], v[4:7]
	v_mfma_f32_16x16x32_bf16 v[0:3], v[186:189], v[238:241], v[0:3]
	s_barrier
	s_add_i32 s22, s22, 2
	s_add_u32 s21, s21, 0x100
	s_addc_u32 s96, s96, 0
	s_cmp_gt_u32 s22, 41
	s_mov_b64 s[8:9], s[10:11]
	s_cbranch_scc0 .LBB0_178
	v_lshl_add_u32 v140, s20, 8, v142
	v_lshl_or_b32 v138, s93, 8, v144
	v_lshlrev_b32_e32 v141, 11, v140
	v_lshl_add_u32 v138, v138, 1, v141
	v_lshlrev_b32_e32 v139, 3, v140
	s_mov_b64 s[8:9], s[4:5]
	global_load_dwordx4 v[146:149], v138, s[8:9]
	global_load_dwordx4 v[150:153], v138, s[8:9] offset:256
	s_add_u32 s8, s8, 0x8000
	s_addc_u32 s9, s9, 0
	global_load_dwordx4 v[154:157], v138, s[8:9]
	global_load_dwordx4 v[162:165], v138, s[8:9] offset:256
	s_add_u32 s8, s8, 0x8000
	s_addc_u32 s9, s9, 0
	global_load_dwordx4 v[166:169], v138, s[8:9]
	global_load_dwordx4 v[174:177], v138, s[8:9] offset:256
	s_add_u32 s8, s8, 0x8000
	s_addc_u32 s9, s9, 0
	global_load_dwordx4 v[178:181], v138, s[8:9]
	global_load_dwordx4 v[182:185], v138, s[8:9] offset:256
	s_add_u32 s8, s8, 0x28000
	s_addc_u32 s9, s9, 0
	global_load_dwordx4 v[186:189], v138, s[8:9]
	global_load_dwordx4 v[190:193], v138, s[8:9] offset:256
	s_add_u32 s8, s8, 0x8000
	s_addc_u32 s9, s9, 0
	global_load_dwordx4 v[194:197], v138, s[8:9]
	global_load_dwordx4 v[198:201], v138, s[8:9] offset:256
	s_add_u32 s8, s8, 0x8000
	s_addc_u32 s9, s9, 0
	global_load_dwordx4 v[202:205], v138, s[8:9]
	global_load_dwordx4 v[206:209], v138, s[8:9] offset:256
	s_add_u32 s8, s8, 0x8000
	s_addc_u32 s9, s9, 0
	global_load_dwordx4 v[210:213], v138, s[8:9]
	global_load_dwordx4 v[214:217], v138, s[8:9] offset:256
	s_and_b64 vcc, exec, s[36:37]
	s_cbranch_vccz .LBB0_181
	s_barrier

.LBB0_212:
	s_add_u32 s12, s10, 0xfffc0080
	s_addc_u32 s13, s11, -1
	s_add_i32 s22, 0, 0x10000
	s_cmp_eq_u32 s21, 12
	s_cselect_b32 s15, s20, s13
	s_cselect_b32 s14, s37, s12
	s_cselect_b32 s13, s41, s97
	s_cselect_b32 s12, s91, s96
	s_add_i32 s50, 0, 0x14000
	v_add_u32_e32 v154, s22, v147
	v_add_u32_e32 v158, s50, v147
	s_add_i32 m0, s30, 0xc000
	s_nop 0
	global_load_lds_dwordx4 v136, s[10:11]
	s_add_i32 m0, s30, 0xe000
	s_nop 0
	global_load_lds_dwordx4 v134, s[10:11]
	ds_read_b128 v[138:141], v154
	ds_read_b128 v[142:145], v154 offset:1024
	ds_read_b128 v[150:153], v154 offset:2048
	ds_read_b128 v[154:157], v154 offset:3072
	ds_read_b128 v[174:177], v158
	ds_read_b128 v[178:181], v158 offset:1024
	ds_read_b128 v[182:185], v158 offset:2048
	ds_read_b128 v[186:189], v158 offset:3072
	ds_read_b128 v[190:193], v149
	ds_read_b128 v[194:197], v149 offset:1024
	ds_read_b128 v[198:201], v149 offset:2048
	ds_read_b128 v[202:205], v149 offset:3072
	ds_read_b128 v[206:209], v149 offset:4096
	ds_read_b128 v[210:213], v149 offset:5120
	ds_read_b128 v[214:217], v149 offset:6144
	ds_read_b128 v[238:241], v149 offset:7168
	s_waitcnt vmcnt(8)
	s_waitcnt lgkmcnt(0)
	s_barrier
	v_mfma_f32_16x16x32_bf16 v[124:127], v[138:141], v[190:193], v[124:127]
	v_mfma_f32_16x16x32_bf16 v[116:119], v[150:153], v[190:193], v[116:119]
	v_mfma_f32_16x16x32_bf16 v[108:111], v[138:141], v[198:201], v[108:111]
	v_mfma_f32_16x16x32_bf16 v[100:103], v[150:153], v[198:201], v[100:103]
	v_mfma_f32_16x16x32_bf16 v[92:95], v[138:141], v[206:209], v[92:95]
	v_mfma_f32_16x16x32_bf16 v[84:87], v[150:153], v[206:209], v[84:87]
	v_mfma_f32_16x16x32_bf16 v[76:79], v[138:141], v[214:217], v[76:79]
	v_mfma_f32_16x16x32_bf16 v[64:67], v[150:153], v[214:217], v[64:67]
	v_mfma_f32_16x16x32_bf16 v[124:127], v[142:145], v[194:197], v[124:127]
	v_mfma_f32_16x16x32_bf16 v[116:119], v[154:157], v[194:197], v[116:119]
	v_mfma_f32_16x16x32_bf16 v[108:111], v[142:145], v[202:205], v[108:111]
	v_mfma_f32_16x16x32_bf16 v[100:103], v[154:157], v[202:205], v[100:103]
	v_mfma_f32_16x16x32_bf16 v[92:95], v[142:145], v[210:213], v[92:95]
	v_mfma_f32_16x16x32_bf16 v[84:87], v[154:157], v[210:213], v[84:87]
	v_mfma_f32_16x16x32_bf16 v[76:79], v[142:145], v[238:241], v[76:79]
	v_mfma_f32_16x16x32_bf16 v[64:67], v[154:157], v[238:241], v[64:67]
	v_mfma_f32_16x16x32_bf16 v[120:123], v[174:177], v[190:193], v[120:123]
	v_mfma_f32_16x16x32_bf16 v[112:115], v[182:185], v[190:193], v[112:115]
	v_mfma_f32_16x16x32_bf16 v[104:107], v[174:177], v[198:201], v[104:107]
	v_mfma_f32_16x16x32_bf16 v[96:99], v[182:185], v[198:201], v[96:99]
	v_mfma_f32_16x16x32_bf16 v[88:91], v[174:177], v[206:209], v[88:91]
	v_mfma_f32_16x16x32_bf16 v[80:83], v[182:185], v[206:209], v[80:83]
	v_mfma_f32_16x16x32_bf16 v[72:75], v[174:177], v[214:217], v[72:75]
	v_mfma_f32_16x16x32_bf16 v[68:71], v[182:185], v[214:217], v[68:71]
	v_mfma_f32_16x16x32_bf16 v[120:123], v[178:181], v[194:197], v[120:123]
	v_mfma_f32_16x16x32_bf16 v[112:115], v[186:189], v[194:197], v[112:115]
	v_mfma_f32_16x16x32_bf16 v[104:107], v[178:181], v[202:205], v[104:107]
	v_mfma_f32_16x16x32_bf16 v[96:99], v[186:189], v[202:205], v[96:99]
	v_mfma_f32_16x16x32_bf16 v[88:91], v[178:181], v[210:213], v[88:91]
	v_mfma_f32_16x16x32_bf16 v[80:83], v[186:189], v[210:213], v[80:83]
	v_mfma_f32_16x16x32_bf16 v[72:75], v[178:181], v[238:241], v[72:75]
	v_mfma_f32_16x16x32_bf16 v[68:71], v[186:189], v[238:241], v[68:71]
	s_barrier
	s_add_i32 s22, s22, s28
	s_mov_b32 m0, s22
	s_nop 0
	global_load_lds_dwordx4 v160, s[12:13]
	s_add_i32 m0, s22, 0x2000
	s_add_u32 s48, s12, 0x40000
	s_addc_u32 s49, s13, 0
	s_add_i32 s22, s50, s28
	global_load_lds_dwordx4 v128, s[12:13]
	s_mov_b32 m0, s22
	s_nop 0
	global_load_lds_dwordx4 v160, s[48:49]
	s_add_i32 m0, s22, 0x2000
	s_nop 0
	global_load_lds_dwordx4 v128, s[48:49]
	s_mov_b32 m0, s30
	s_nop 0
	global_load_lds_dwordx4 v132, s[14:15]
	s_mov_b32 m0, s31
	s_nop 0
	global_load_lds_dwordx4 v130, s[14:15]
	ds_read_b128 v[190:193], v149 offset:16384
	ds_read_b128 v[194:197], v149 offset:17408
	ds_read_b128 v[198:201], v149 offset:18432
	ds_read_b128 v[202:205], v149 offset:19456
	ds_read_b128 v[238:241], v149 offset:23552
	ds_read_b128 v[214:217], v149 offset:22528
	ds_read_b128 v[210:213], v149 offset:21504
	ds_read_b128 v[206:209], v149 offset:20480
	s_waitcnt vmcnt(8)
	s_waitcnt lgkmcnt(0)
	s_barrier
	v_mfma_f32_16x16x32_bf16 v[60:63], v[138:141], v[190:193], v[60:63]
	v_mfma_f32_16x16x32_bf16 v[48:51], v[150:153], v[190:193], v[48:51]
	v_mfma_f32_16x16x32_bf16 v[44:47], v[138:141], v[198:201], v[44:47]
	v_mfma_f32_16x16x32_bf16 v[32:35], v[150:153], v[198:201], v[32:35]
	v_mfma_f32_16x16x32_bf16 v[28:31], v[138:141], v[206:209], v[28:31]
	v_mfma_f32_16x16x32_bf16 v[16:19], v[150:153], v[206:209], v[16:19]
	v_mfma_f32_16x16x32_bf16 v[12:15], v[138:141], v[214:217], v[12:15]
	v_mfma_f32_16x16x32_bf16 v[0:3], v[150:153], v[214:217], v[0:3]
	v_mfma_f32_16x16x32_bf16 v[60:63], v[142:145], v[194:197], v[60:63]
	v_mfma_f32_16x16x32_bf16 v[48:51], v[154:157], v[194:197], v[48:51]
	v_mfma_f32_16x16x32_bf16 v[44:47], v[142:145], v[202:205], v[44:47]
	v_mfma_f32_16x16x32_bf16 v[32:35], v[154:157], v[202:205], v[32:35]
	v_mfma_f32_16x16x32_bf16 v[28:31], v[142:145], v[210:213], v[28:31]
	v_mfma_f32_16x16x32_bf16 v[16:19], v[154:157], v[210:213], v[16:19]
	v_mfma_f32_16x16x32_bf16 v[12:15], v[142:145], v[238:241], v[12:15]
	v_mfma_f32_16x16x32_bf16 v[0:3], v[154:157], v[238:241], v[0:3]
	v_mfma_f32_16x16x32_bf16 v[56:59], v[174:177], v[190:193], v[56:59]
	v_mfma_f32_16x16x32_bf16 v[52:55], v[182:185], v[190:193], v[52:55]
	v_mfma_f32_16x16x32_bf16 v[40:43], v[174:177], v[198:201], v[40:43]
	v_mfma_f32_16x16x32_bf16 v[36:39], v[182:185], v[198:201], v[36:39]
	v_mfma_f32_16x16x32_bf16 v[24:27], v[174:177], v[206:209], v[24:27]
	v_mfma_f32_16x16x32_bf16 v[20:23], v[182:185], v[206:209], v[20:23]
	v_mfma_f32_16x16x32_bf16 v[8:11], v[174:177], v[214:217], v[8:11]
	v_mfma_f32_16x16x32_bf16 v[4:7], v[182:185], v[214:217], v[4:7]
	v_mfma_f32_16x16x32_bf16 v[56:59], v[178:181], v[194:197], v[56:59]
	v_mfma_f32_16x16x32_bf16 v[52:55], v[186:189], v[194:197], v[52:55]
	v_mfma_f32_16x16x32_bf16 v[40:43], v[178:181], v[202:205], v[40:43]
	v_mfma_f32_16x16x32_bf16 v[36:39], v[186:189], v[202:205], v[36:39]
	v_mfma_f32_16x16x32_bf16 v[24:27], v[178:181], v[210:213], v[24:27]
	v_mfma_f32_16x16x32_bf16 v[20:23], v[186:189], v[210:213], v[20:23]
	v_mfma_f32_16x16x32_bf16 v[8:11], v[178:181], v[238:241], v[8:11]
	v_mfma_f32_16x16x32_bf16 v[4:7], v[186:189], v[238:241], v[4:7]
	s_barrier
	s_add_i32 s22, 0, 0x18000
	s_add_i32 s48, 0, 0x1c000
	v_add_u32_e32 v154, s22, v147
	v_add_u32_e32 v168, s48, v147
	s_mov_b64 s[100:101], s[14:15]
	s_add_u32 s14, s14, 0x40000
	s_addc_u32 s15, s15, 0
	s_mov_b32 m0, s33
	s_nop 0
	global_load_lds_dwordx4 v132, s[14:15]
	s_mov_b32 m0, s34
	s_nop 0
	global_load_lds_dwordx4 v130, s[14:15]
	ds_read_b128 v[138:141], v154
	ds_read_b128 v[142:145], v154 offset:1024
	ds_read_b128 v[150:153], v154 offset:2048
	ds_read_b128 v[154:157], v154 offset:3072
	ds_read_b128 v[174:177], v168
	ds_read_b128 v[178:181], v168 offset:1024
	ds_read_b128 v[182:185], v168 offset:2048
	ds_read_b128 v[186:189], v168 offset:3072
	ds_read_b128 v[190:193], v149 offset:32768
	ds_read_b128 v[194:197], v149 offset:33792
	ds_read_b128 v[198:201], v149 offset:34816
	ds_read_b128 v[202:205], v149 offset:35840
	ds_read_b128 v[206:209], v149 offset:36864
	ds_read_b128 v[210:213], v149 offset:37888
	ds_read_b128 v[214:217], v149 offset:38912
	ds_read_b128 v[238:241], v149 offset:39936
	s_waitcnt vmcnt(8)
	s_waitcnt lgkmcnt(0)
	s_barrier
	v_mfma_f32_16x16x32_bf16 v[124:127], v[138:141], v[190:193], v[124:127]
	v_mfma_f32_16x16x32_bf16 v[116:119], v[150:153], v[190:193], v[116:119]
	v_mfma_f32_16x16x32_bf16 v[108:111], v[138:141], v[198:201], v[108:111]
	v_mfma_f32_16x16x32_bf16 v[100:103], v[150:153], v[198:201], v[100:103]
	v_mfma_f32_16x16x32_bf16 v[92:95], v[138:141], v[206:209], v[92:95]
	v_mfma_f32_16x16x32_bf16 v[84:87], v[150:153], v[206:209], v[84:87]
	v_mfma_f32_16x16x32_bf16 v[76:79], v[138:141], v[214:217], v[76:79]
	v_mfma_f32_16x16x32_bf16 v[64:67], v[150:153], v[214:217], v[64:67]
	v_mfma_f32_16x16x32_bf16 v[124:127], v[142:145], v[194:197], v[124:127]
	v_mfma_f32_16x16x32_bf16 v[116:119], v[154:157], v[194:197], v[116:119]
	v_mfma_f32_16x16x32_bf16 v[108:111], v[142:145], v[202:205], v[108:111]
	v_mfma_f32_16x16x32_bf16 v[100:103], v[154:157], v[202:205], v[100:103]
	v_mfma_f32_16x16x32_bf16 v[92:95], v[142:145], v[210:213], v[92:95]
	v_mfma_f32_16x16x32_bf16 v[84:87], v[154:157], v[210:213], v[84:87]
	v_mfma_f32_16x16x32_bf16 v[76:79], v[142:145], v[238:241], v[76:79]
	v_mfma_f32_16x16x32_bf16 v[64:67], v[154:157], v[238:241], v[64:67]
	v_mfma_f32_16x16x32_bf16 v[120:123], v[174:177], v[190:193], v[120:123]
	v_mfma_f32_16x16x32_bf16 v[112:115], v[182:185], v[190:193], v[112:115]
	v_mfma_f32_16x16x32_bf16 v[104:107], v[174:177], v[198:201], v[104:107]
	v_mfma_f32_16x16x32_bf16 v[96:99], v[182:185], v[198:201], v[96:99]
	v_mfma_f32_16x16x32_bf16 v[88:91], v[174:177], v[206:209], v[88:91]
	v_mfma_f32_16x16x32_bf16 v[80:83], v[182:185], v[206:209], v[80:83]
	v_mfma_f32_16x16x32_bf16 v[72:75], v[174:177], v[214:217], v[72:75]
	v_mfma_f32_16x16x32_bf16 v[68:71], v[182:185], v[214:217], v[68:71]
	v_mfma_f32_16x16x32_bf16 v[120:123], v[178:181], v[194:197], v[120:123]
	v_mfma_f32_16x16x32_bf16 v[112:115], v[186:189], v[194:197], v[112:115]
	v_mfma_f32_16x16x32_bf16 v[104:107], v[178:181], v[202:205], v[104:107]
	v_mfma_f32_16x16x32_bf16 v[96:99], v[186:189], v[202:205], v[96:99]
	v_mfma_f32_16x16x32_bf16 v[88:91], v[178:181], v[210:213], v[88:91]
	v_mfma_f32_16x16x32_bf16 v[80:83], v[186:189], v[210:213], v[80:83]
	v_mfma_f32_16x16x32_bf16 v[72:75], v[178:181], v[238:241], v[72:75]
	v_mfma_f32_16x16x32_bf16 v[68:71], v[186:189], v[238:241], v[68:71]
	s_barrier
	s_add_i32 s14, s22, s28
	s_add_i32 m0, s14, 0xffffff80
	s_nop 0
	global_load_lds_dwordx4 v160, s[12:13] offset:128
	s_add_i32 m0, s14, 0x1f80
	s_nop 0
	global_load_lds_dwordx4 v128, s[12:13] offset:128
	s_add_u32 s12, s12, 0x40080
	s_addc_u32 s13, s13, 0
	s_add_i32 s14, s48, s28
	s_mov_b32 m0, s14
	s_nop 0
	global_load_lds_dwordx4 v160, s[12:13]
	s_add_i32 m0, s14, 0x2000
	s_nop 0
	global_load_lds_dwordx4 v128, s[12:13]
	s_add_i32 m0, s35, 0xffffff80
	s_nop 0
	global_load_lds_dwordx4 v132, s[100:101] offset:128
	s_add_i32 m0, s90, 0xffffff80
	s_nop 0
	global_load_lds_dwordx4 v130, s[100:101] offset:128
	ds_read_b128 v[190:193], v149 offset:49152
	ds_read_b128 v[194:197], v149 offset:50176
	ds_read_b128 v[198:201], v149 offset:51200
	ds_read_b128 v[238:241], v149 offset:56320
	ds_read_b128 v[214:217], v149 offset:55296
	ds_read_b128 v[210:213], v149 offset:54272
	ds_read_b128 v[206:209], v149 offset:53248
	ds_read_b128 v[202:205], v149 offset:52224
	s_waitcnt vmcnt(8)
	s_waitcnt lgkmcnt(0)
	s_barrier
	v_mfma_f32_16x16x32_bf16 v[60:63], v[138:141], v[190:193], v[60:63]
	v_mfma_f32_16x16x32_bf16 v[48:51], v[150:153], v[190:193], v[48:51]
	v_mfma_f32_16x16x32_bf16 v[44:47], v[138:141], v[198:201], v[44:47]
	v_mfma_f32_16x16x32_bf16 v[32:35], v[150:153], v[198:201], v[32:35]
	v_mfma_f32_16x16x32_bf16 v[28:31], v[138:141], v[206:209], v[28:31]
	v_mfma_f32_16x16x32_bf16 v[16:19], v[150:153], v[206:209], v[16:19]
	v_mfma_f32_16x16x32_bf16 v[12:15], v[138:141], v[214:217], v[12:15]
	v_mfma_f32_16x16x32_bf16 v[0:3], v[150:153], v[214:217], v[0:3]
	v_mfma_f32_16x16x32_bf16 v[60:63], v[142:145], v[194:197], v[60:63]
	v_mfma_f32_16x16x32_bf16 v[48:51], v[154:157], v[194:197], v[48:51]
	v_mfma_f32_16x16x32_bf16 v[44:47], v[142:145], v[202:205], v[44:47]
	v_mfma_f32_16x16x32_bf16 v[32:35], v[154:157], v[202:205], v[32:35]
	v_mfma_f32_16x16x32_bf16 v[28:31], v[142:145], v[210:213], v[28:31]
	v_mfma_f32_16x16x32_bf16 v[16:19], v[154:157], v[210:213], v[16:19]
	v_mfma_f32_16x16x32_bf16 v[12:15], v[142:145], v[238:241], v[12:15]
	v_mfma_f32_16x16x32_bf16 v[0:3], v[154:157], v[238:241], v[0:3]
	v_mfma_f32_16x16x32_bf16 v[56:59], v[174:177], v[190:193], v[56:59]
	v_mfma_f32_16x16x32_bf16 v[52:55], v[182:185], v[190:193], v[52:55]
	v_mfma_f32_16x16x32_bf16 v[40:43], v[174:177], v[198:201], v[40:43]
	v_mfma_f32_16x16x32_bf16 v[36:39], v[182:185], v[198:201], v[36:39]
	v_mfma_f32_16x16x32_bf16 v[24:27], v[174:177], v[206:209], v[24:27]
	v_mfma_f32_16x16x32_bf16 v[20:23], v[182:185], v[206:209], v[20:23]
	v_mfma_f32_16x16x32_bf16 v[8:11], v[174:177], v[214:217], v[8:11]
	v_mfma_f32_16x16x32_bf16 v[4:7], v[182:185], v[214:217], v[4:7]
	v_mfma_f32_16x16x32_bf16 v[56:59], v[178:181], v[194:197], v[56:59]
	v_mfma_f32_16x16x32_bf16 v[52:55], v[186:189], v[194:197], v[52:55]
	v_mfma_f32_16x16x32_bf16 v[40:43], v[178:181], v[202:205], v[40:43]
	v_mfma_f32_16x16x32_bf16 v[36:39], v[186:189], v[202:205], v[36:39]
	v_mfma_f32_16x16x32_bf16 v[24:27], v[178:181], v[210:213], v[24:27]
	v_mfma_f32_16x16x32_bf16 v[20:23], v[186:189], v[210:213], v[20:23]
	v_mfma_f32_16x16x32_bf16 v[8:11], v[178:181], v[238:241], v[8:11]
	v_mfma_f32_16x16x32_bf16 v[4:7], v[186:189], v[238:241], v[4:7]
	s_barrier
	s_add_i32 s21, s21, 2
	s_add_u32 s96, s96, 0x100
	s_addc_u32 s97, s97, 0
	s_add_u32 s10, s10, 0x100
	s_addc_u32 s11, s11, 0
	s_cmp_gt_u32 s21, 13
	s_cbranch_scc0 .LBB0_212
	v_lshl_add_u32 v192, s8, 8, v146
	v_lshlrev_b32_e32 v192, 3, v192
	global_load_dwordx2 v[176:177], v192, s[4:5]
	global_load_dwordx2 v[178:179], v192, s[4:5] offset:128
	global_load_dwordx2 v[180:181], v192, s[4:5] offset:256
	global_load_dwordx2 v[182:183], v192, s[4:5] offset:384
	global_load_dwordx2 v[184:185], v192, s[4:5] offset:1024
	global_load_dwordx2 v[186:187], v192, s[4:5] offset:1152
	global_load_dwordx2 v[188:189], v192, s[4:5] offset:1280
	global_load_dwordx2 v[190:191], v192, s[4:5] offset:1408
	s_and_b64 vcc, exec, s[6:7]
	s_cbranch_vccz .LBB0_215
	s_barrier

.LBB0_310:
	s_add_u32 s12, vcc_lo, 0xfffc0080
	s_addc_u32 s13, vcc_hi, -1
	s_add_i32 s22, 0, 0x10000
	s_cmp_eq_u32 s21, 12
	s_cselect_b32 s93, s9, s13
	s_cselect_b32 s92, s20, s12
	s_cselect_b32 s13, s11, s91
	s_cselect_b32 s12, s45, s90
	s_add_i32 s50, 0, 0x14000
	v_add_u32_e32 v154, s22, v143
	v_add_u32_e32 v158, s50, v143
	s_add_i32 m0, s29, 0xc000
	s_nop 0
	global_load_lds_dwordx4 v136, vcc
	s_add_i32 m0, s29, 0xe000
	s_nop 0
	global_load_lds_dwordx4 v134, vcc
	ds_read_b128 v[138:141], v154
	ds_read_b128 v[146:149], v154 offset:1024
	ds_read_b128 v[150:153], v154 offset:2048
	ds_read_b128 v[154:157], v154 offset:3072
	ds_read_b128 v[174:177], v158
	ds_read_b128 v[178:181], v158 offset:1024
	ds_read_b128 v[182:185], v158 offset:2048
	ds_read_b128 v[186:189], v158 offset:3072
	ds_read_b128 v[190:193], v145
	ds_read_b128 v[194:197], v145 offset:1024
	ds_read_b128 v[198:201], v145 offset:2048
	ds_read_b128 v[202:205], v145 offset:3072
	ds_read_b128 v[206:209], v145 offset:4096
	ds_read_b128 v[210:213], v145 offset:5120
	ds_read_b128 v[214:217], v145 offset:6144
	ds_read_b128 v[238:241], v145 offset:7168
	s_waitcnt vmcnt(8)
	s_waitcnt lgkmcnt(0)
	s_barrier
	v_mfma_f32_16x16x32_bf16 v[124:127], v[138:141], v[190:193], v[124:127]
	v_mfma_f32_16x16x32_bf16 v[120:123], v[150:153], v[190:193], v[120:123]
	v_mfma_f32_16x16x32_bf16 v[108:111], v[138:141], v[198:201], v[108:111]
	v_mfma_f32_16x16x32_bf16 v[104:107], v[150:153], v[198:201], v[104:107]
	v_mfma_f32_16x16x32_bf16 v[92:95], v[138:141], v[206:209], v[92:95]
	v_mfma_f32_16x16x32_bf16 v[88:91], v[150:153], v[206:209], v[88:91]
	v_mfma_f32_16x16x32_bf16 v[76:79], v[138:141], v[214:217], v[76:79]
	v_mfma_f32_16x16x32_bf16 v[72:75], v[150:153], v[214:217], v[72:75]
	v_mfma_f32_16x16x32_bf16 v[124:127], v[146:149], v[194:197], v[124:127]
	v_mfma_f32_16x16x32_bf16 v[120:123], v[154:157], v[194:197], v[120:123]
	v_mfma_f32_16x16x32_bf16 v[108:111], v[146:149], v[202:205], v[108:111]
	v_mfma_f32_16x16x32_bf16 v[104:107], v[154:157], v[202:205], v[104:107]
	v_mfma_f32_16x16x32_bf16 v[92:95], v[146:149], v[210:213], v[92:95]
	v_mfma_f32_16x16x32_bf16 v[88:91], v[154:157], v[210:213], v[88:91]
	v_mfma_f32_16x16x32_bf16 v[76:79], v[146:149], v[238:241], v[76:79]
	v_mfma_f32_16x16x32_bf16 v[72:75], v[154:157], v[238:241], v[72:75]
	v_mfma_f32_16x16x32_bf16 v[116:119], v[174:177], v[190:193], v[116:119]
	v_mfma_f32_16x16x32_bf16 v[112:115], v[182:185], v[190:193], v[112:115]
	v_mfma_f32_16x16x32_bf16 v[100:103], v[174:177], v[198:201], v[100:103]
	v_mfma_f32_16x16x32_bf16 v[96:99], v[182:185], v[198:201], v[96:99]
	v_mfma_f32_16x16x32_bf16 v[84:87], v[174:177], v[206:209], v[84:87]
	v_mfma_f32_16x16x32_bf16 v[80:83], v[182:185], v[206:209], v[80:83]
	v_mfma_f32_16x16x32_bf16 v[68:71], v[174:177], v[214:217], v[68:71]
	v_mfma_f32_16x16x32_bf16 v[64:67], v[182:185], v[214:217], v[64:67]
	v_mfma_f32_16x16x32_bf16 v[116:119], v[178:181], v[194:197], v[116:119]
	v_mfma_f32_16x16x32_bf16 v[112:115], v[186:189], v[194:197], v[112:115]
	v_mfma_f32_16x16x32_bf16 v[100:103], v[178:181], v[202:205], v[100:103]
	v_mfma_f32_16x16x32_bf16 v[96:99], v[186:189], v[202:205], v[96:99]
	v_mfma_f32_16x16x32_bf16 v[84:87], v[178:181], v[210:213], v[84:87]
	v_mfma_f32_16x16x32_bf16 v[80:83], v[186:189], v[210:213], v[80:83]
	v_mfma_f32_16x16x32_bf16 v[68:71], v[178:181], v[238:241], v[68:71]
	v_mfma_f32_16x16x32_bf16 v[64:67], v[186:189], v[238:241], v[64:67]
	s_barrier
	s_add_i32 s22, s22, s28
	s_mov_b32 m0, s22
	s_nop 0
	global_load_lds_dwordx4 v160, s[12:13]
	s_add_i32 m0, s22, 0x2000
	s_add_u32 s48, s12, 0x40000
	s_addc_u32 s49, s13, 0
	s_add_i32 s22, s50, s28
	global_load_lds_dwordx4 v132, s[12:13]
	s_mov_b32 m0, s22
	s_nop 0
	global_load_lds_dwordx4 v160, s[48:49]
	s_add_i32 m0, s22, 0x2000
	s_nop 0
	global_load_lds_dwordx4 v132, s[48:49]
	s_mov_b32 m0, s29
	s_nop 0
	global_load_lds_dwordx4 v128, s[92:93]
	s_mov_b32 m0, s30
	s_nop 0
	global_load_lds_dwordx4 v130, s[92:93]
	ds_read_b128 v[190:193], v145 offset:16384
	ds_read_b128 v[194:197], v145 offset:17408
	ds_read_b128 v[198:201], v145 offset:18432
	ds_read_b128 v[202:205], v145 offset:19456
	ds_read_b128 v[238:241], v145 offset:23552
	ds_read_b128 v[214:217], v145 offset:22528
	ds_read_b128 v[210:213], v145 offset:21504
	ds_read_b128 v[206:209], v145 offset:20480
	s_waitcnt vmcnt(8)
	s_waitcnt lgkmcnt(0)
	s_barrier
	v_mfma_f32_16x16x32_bf16 v[60:63], v[138:141], v[190:193], v[60:63]
	v_mfma_f32_16x16x32_bf16 v[56:59], v[150:153], v[190:193], v[56:59]
	v_mfma_f32_16x16x32_bf16 v[44:47], v[138:141], v[198:201], v[44:47]
	v_mfma_f32_16x16x32_bf16 v[40:43], v[150:153], v[198:201], v[40:43]
	v_mfma_f32_16x16x32_bf16 v[28:31], v[138:141], v[206:209], v[28:31]
	v_mfma_f32_16x16x32_bf16 v[24:27], v[150:153], v[206:209], v[24:27]
	v_mfma_f32_16x16x32_bf16 v[12:15], v[138:141], v[214:217], v[12:15]
	v_mfma_f32_16x16x32_bf16 v[8:11], v[150:153], v[214:217], v[8:11]
	v_mfma_f32_16x16x32_bf16 v[60:63], v[146:149], v[194:197], v[60:63]
	v_mfma_f32_16x16x32_bf16 v[56:59], v[154:157], v[194:197], v[56:59]
	v_mfma_f32_16x16x32_bf16 v[44:47], v[146:149], v[202:205], v[44:47]
	v_mfma_f32_16x16x32_bf16 v[40:43], v[154:157], v[202:205], v[40:43]
	v_mfma_f32_16x16x32_bf16 v[28:31], v[146:149], v[210:213], v[28:31]
	v_mfma_f32_16x16x32_bf16 v[24:27], v[154:157], v[210:213], v[24:27]
	v_mfma_f32_16x16x32_bf16 v[12:15], v[146:149], v[238:241], v[12:15]
	v_mfma_f32_16x16x32_bf16 v[8:11], v[154:157], v[238:241], v[8:11]
	v_mfma_f32_16x16x32_bf16 v[52:55], v[174:177], v[190:193], v[52:55]
	v_mfma_f32_16x16x32_bf16 v[48:51], v[182:185], v[190:193], v[48:51]
	v_mfma_f32_16x16x32_bf16 v[36:39], v[174:177], v[198:201], v[36:39]
	v_mfma_f32_16x16x32_bf16 v[32:35], v[182:185], v[198:201], v[32:35]
	v_mfma_f32_16x16x32_bf16 v[20:23], v[174:177], v[206:209], v[20:23]
	v_mfma_f32_16x16x32_bf16 v[16:19], v[182:185], v[206:209], v[16:19]
	v_mfma_f32_16x16x32_bf16 v[4:7], v[174:177], v[214:217], v[4:7]
	v_mfma_f32_16x16x32_bf16 v[0:3], v[182:185], v[214:217], v[0:3]
	v_mfma_f32_16x16x32_bf16 v[52:55], v[178:181], v[194:197], v[52:55]
	v_mfma_f32_16x16x32_bf16 v[48:51], v[186:189], v[194:197], v[48:51]
	v_mfma_f32_16x16x32_bf16 v[36:39], v[178:181], v[202:205], v[36:39]
	v_mfma_f32_16x16x32_bf16 v[32:35], v[186:189], v[202:205], v[32:35]
	v_mfma_f32_16x16x32_bf16 v[20:23], v[178:181], v[210:213], v[20:23]
	v_mfma_f32_16x16x32_bf16 v[16:19], v[186:189], v[210:213], v[16:19]
	v_mfma_f32_16x16x32_bf16 v[4:7], v[178:181], v[238:241], v[4:7]
	v_mfma_f32_16x16x32_bf16 v[0:3], v[186:189], v[238:241], v[0:3]
	s_barrier
	s_add_i32 s22, 0, 0x18000
	s_add_i32 s50, 0, 0x1c000
	v_add_u32_e32 v154, s22, v143
	v_add_u32_e32 v168, s50, v143
	s_add_u32 s48, s92, 0x40000
	s_addc_u32 s49, s93, 0
	s_mov_b32 m0, s31
	s_nop 0
	global_load_lds_dwordx4 v128, s[48:49]
	s_mov_b32 m0, s33
	s_nop 0
	global_load_lds_dwordx4 v130, s[48:49]
	ds_read_b128 v[138:141], v154
	ds_read_b128 v[146:149], v154 offset:1024
	ds_read_b128 v[150:153], v154 offset:2048
	ds_read_b128 v[154:157], v154 offset:3072
	ds_read_b128 v[174:177], v168
	ds_read_b128 v[178:181], v168 offset:1024
	ds_read_b128 v[182:185], v168 offset:2048
	ds_read_b128 v[186:189], v168 offset:3072
	ds_read_b128 v[190:193], v145 offset:32768
	ds_read_b128 v[194:197], v145 offset:33792
	ds_read_b128 v[198:201], v145 offset:34816
	ds_read_b128 v[202:205], v145 offset:35840
	ds_read_b128 v[206:209], v145 offset:36864
	ds_read_b128 v[210:213], v145 offset:37888
	ds_read_b128 v[214:217], v145 offset:38912
	ds_read_b128 v[238:241], v145 offset:39936
	s_waitcnt vmcnt(8)
	s_waitcnt lgkmcnt(0)
	s_barrier
	v_mfma_f32_16x16x32_bf16 v[124:127], v[138:141], v[190:193], v[124:127]
	v_mfma_f32_16x16x32_bf16 v[120:123], v[150:153], v[190:193], v[120:123]
	v_mfma_f32_16x16x32_bf16 v[108:111], v[138:141], v[198:201], v[108:111]
	v_mfma_f32_16x16x32_bf16 v[104:107], v[150:153], v[198:201], v[104:107]
	v_mfma_f32_16x16x32_bf16 v[92:95], v[138:141], v[206:209], v[92:95]
	v_mfma_f32_16x16x32_bf16 v[88:91], v[150:153], v[206:209], v[88:91]
	v_mfma_f32_16x16x32_bf16 v[76:79], v[138:141], v[214:217], v[76:79]
	v_mfma_f32_16x16x32_bf16 v[72:75], v[150:153], v[214:217], v[72:75]
	v_mfma_f32_16x16x32_bf16 v[124:127], v[146:149], v[194:197], v[124:127]
	v_mfma_f32_16x16x32_bf16 v[120:123], v[154:157], v[194:197], v[120:123]
	v_mfma_f32_16x16x32_bf16 v[108:111], v[146:149], v[202:205], v[108:111]
	v_mfma_f32_16x16x32_bf16 v[104:107], v[154:157], v[202:205], v[104:107]
	v_mfma_f32_16x16x32_bf16 v[92:95], v[146:149], v[210:213], v[92:95]
	v_mfma_f32_16x16x32_bf16 v[88:91], v[154:157], v[210:213], v[88:91]
	v_mfma_f32_16x16x32_bf16 v[76:79], v[146:149], v[238:241], v[76:79]
	v_mfma_f32_16x16x32_bf16 v[72:75], v[154:157], v[238:241], v[72:75]
	v_mfma_f32_16x16x32_bf16 v[116:119], v[174:177], v[190:193], v[116:119]
	v_mfma_f32_16x16x32_bf16 v[112:115], v[182:185], v[190:193], v[112:115]
	v_mfma_f32_16x16x32_bf16 v[100:103], v[174:177], v[198:201], v[100:103]
	v_mfma_f32_16x16x32_bf16 v[96:99], v[182:185], v[198:201], v[96:99]
	v_mfma_f32_16x16x32_bf16 v[84:87], v[174:177], v[206:209], v[84:87]
	v_mfma_f32_16x16x32_bf16 v[80:83], v[182:185], v[206:209], v[80:83]
	v_mfma_f32_16x16x32_bf16 v[68:71], v[174:177], v[214:217], v[68:71]
	v_mfma_f32_16x16x32_bf16 v[64:67], v[182:185], v[214:217], v[64:67]
	v_mfma_f32_16x16x32_bf16 v[116:119], v[178:181], v[194:197], v[116:119]
	v_mfma_f32_16x16x32_bf16 v[112:115], v[186:189], v[194:197], v[112:115]
	v_mfma_f32_16x16x32_bf16 v[100:103], v[178:181], v[202:205], v[100:103]
	v_mfma_f32_16x16x32_bf16 v[96:99], v[186:189], v[202:205], v[96:99]
	v_mfma_f32_16x16x32_bf16 v[84:87], v[178:181], v[210:213], v[84:87]
	v_mfma_f32_16x16x32_bf16 v[80:83], v[186:189], v[210:213], v[80:83]
	v_mfma_f32_16x16x32_bf16 v[68:71], v[178:181], v[238:241], v[68:71]
	v_mfma_f32_16x16x32_bf16 v[64:67], v[186:189], v[238:241], v[64:67]
	s_barrier
	s_add_i32 s22, s22, s28
	s_add_i32 m0, s22, 0xffffff80
	s_nop 0
	global_load_lds_dwordx4 v160, s[12:13] offset:128
	s_add_i32 m0, s22, 0x1f80
	s_nop 0
	global_load_lds_dwordx4 v132, s[12:13] offset:128
	s_add_u32 s12, s12, 0x40080
	s_addc_u32 s13, s13, 0
	s_add_i32 s22, s50, s28
	s_mov_b32 m0, s22
	s_nop 0
	global_load_lds_dwordx4 v160, s[12:13]
	s_add_i32 m0, s22, 0x2000
	s_nop 0
	global_load_lds_dwordx4 v132, s[12:13]
	s_add_i32 m0, s34, 0xffffff80
	s_nop 0
	global_load_lds_dwordx4 v128, s[92:93] offset:128
	s_add_i32 m0, s35, 0xffffff80
	s_nop 0
	global_load_lds_dwordx4 v130, s[92:93] offset:128
	ds_read_b128 v[190:193], v145 offset:49152
	ds_read_b128 v[194:197], v145 offset:50176
	ds_read_b128 v[198:201], v145 offset:51200
	ds_read_b128 v[238:241], v145 offset:56320
	ds_read_b128 v[214:217], v145 offset:55296
	ds_read_b128 v[210:213], v145 offset:54272
	ds_read_b128 v[206:209], v145 offset:53248
	ds_read_b128 v[202:205], v145 offset:52224
	s_waitcnt vmcnt(8)
	s_waitcnt lgkmcnt(0)
	s_barrier
	v_mfma_f32_16x16x32_bf16 v[60:63], v[138:141], v[190:193], v[60:63]
	v_mfma_f32_16x16x32_bf16 v[56:59], v[150:153], v[190:193], v[56:59]
	v_mfma_f32_16x16x32_bf16 v[44:47], v[138:141], v[198:201], v[44:47]
	v_mfma_f32_16x16x32_bf16 v[40:43], v[150:153], v[198:201], v[40:43]
	v_mfma_f32_16x16x32_bf16 v[28:31], v[138:141], v[206:209], v[28:31]
	v_mfma_f32_16x16x32_bf16 v[24:27], v[150:153], v[206:209], v[24:27]
	v_mfma_f32_16x16x32_bf16 v[12:15], v[138:141], v[214:217], v[12:15]
	v_mfma_f32_16x16x32_bf16 v[8:11], v[150:153], v[214:217], v[8:11]
	v_mfma_f32_16x16x32_bf16 v[60:63], v[146:149], v[194:197], v[60:63]
	v_mfma_f32_16x16x32_bf16 v[56:59], v[154:157], v[194:197], v[56:59]
	v_mfma_f32_16x16x32_bf16 v[44:47], v[146:149], v[202:205], v[44:47]
	v_mfma_f32_16x16x32_bf16 v[40:43], v[154:157], v[202:205], v[40:43]
	v_mfma_f32_16x16x32_bf16 v[28:31], v[146:149], v[210:213], v[28:31]
	v_mfma_f32_16x16x32_bf16 v[24:27], v[154:157], v[210:213], v[24:27]
	v_mfma_f32_16x16x32_bf16 v[12:15], v[146:149], v[238:241], v[12:15]
	v_mfma_f32_16x16x32_bf16 v[8:11], v[154:157], v[238:241], v[8:11]
	v_mfma_f32_16x16x32_bf16 v[52:55], v[174:177], v[190:193], v[52:55]
	v_mfma_f32_16x16x32_bf16 v[48:51], v[182:185], v[190:193], v[48:51]
	v_mfma_f32_16x16x32_bf16 v[36:39], v[174:177], v[198:201], v[36:39]
	v_mfma_f32_16x16x32_bf16 v[32:35], v[182:185], v[198:201], v[32:35]
	v_mfma_f32_16x16x32_bf16 v[20:23], v[174:177], v[206:209], v[20:23]
	v_mfma_f32_16x16x32_bf16 v[16:19], v[182:185], v[206:209], v[16:19]
	v_mfma_f32_16x16x32_bf16 v[4:7], v[174:177], v[214:217], v[4:7]
	v_mfma_f32_16x16x32_bf16 v[0:3], v[182:185], v[214:217], v[0:3]
	v_mfma_f32_16x16x32_bf16 v[52:55], v[178:181], v[194:197], v[52:55]
	v_mfma_f32_16x16x32_bf16 v[48:51], v[186:189], v[194:197], v[48:51]
	v_mfma_f32_16x16x32_bf16 v[36:39], v[178:181], v[202:205], v[36:39]
	v_mfma_f32_16x16x32_bf16 v[32:35], v[186:189], v[202:205], v[32:35]
	v_mfma_f32_16x16x32_bf16 v[20:23], v[178:181], v[210:213], v[20:23]
	v_mfma_f32_16x16x32_bf16 v[16:19], v[186:189], v[210:213], v[16:19]
	v_mfma_f32_16x16x32_bf16 v[4:7], v[178:181], v[238:241], v[4:7]
	v_mfma_f32_16x16x32_bf16 v[0:3], v[186:189], v[238:241], v[0:3]
	s_barrier
	s_add_i32 s21, s21, 2
	s_add_u32 s90, s90, 0x100
	s_addc_u32 s91, s91, 0
	s_add_u32 vcc_lo, vcc_lo, 0x100
	s_addc_u32 vcc_hi, vcc_hi, 0
	s_cmp_gt_u32 s21, 13
	s_cbranch_scc0 .LBB0_310
	v_lshl_add_u32 v140, s36, 8, v142
	v_lshl_or_b32 v138, s44, 8, v144
	v_lshlrev_b32_e32 v141, 11, v140
	v_lshl_add_u32 v138, v138, 1, v141
	v_lshlrev_b32_e32 v139, 3, v140
	s_mov_b64 s[12:13], s[2:3]
	global_load_dwordx4 v[146:149], v138, s[12:13]
	global_load_dwordx4 v[150:153], v138, s[12:13] offset:256
	s_add_u32 s12, s12, 0x8000
	s_addc_u32 s13, s13, 0
	global_load_dwordx4 v[154:157], v138, s[12:13]
	global_load_dwordx4 v[162:165], v138, s[12:13] offset:256
	s_add_u32 s12, s12, 0x8000
	s_addc_u32 s13, s13, 0
	global_load_dwordx4 v[166:169], v138, s[12:13]
	global_load_dwordx4 v[174:177], v138, s[12:13] offset:256
	s_add_u32 s12, s12, 0x8000
	s_addc_u32 s13, s13, 0
	global_load_dwordx4 v[178:181], v138, s[12:13]
	global_load_dwordx4 v[182:185], v138, s[12:13] offset:256
	s_add_u32 s12, s12, 0x28000
	s_addc_u32 s13, s13, 0
	global_load_dwordx4 v[186:189], v138, s[12:13]
	global_load_dwordx4 v[190:193], v138, s[12:13] offset:256
	s_add_u32 s12, s12, 0x8000
	s_addc_u32 s13, s13, 0
	global_load_dwordx4 v[194:197], v138, s[12:13]
	global_load_dwordx4 v[198:201], v138, s[12:13] offset:256
	s_add_u32 s12, s12, 0x8000
	s_addc_u32 s13, s13, 0
	global_load_dwordx4 v[202:205], v138, s[12:13]
	global_load_dwordx4 v[206:209], v138, s[12:13] offset:256
	s_add_u32 s12, s12, 0x8000
	s_addc_u32 s13, s13, 0
	global_load_dwordx4 v[210:213], v138, s[12:13]
	global_load_dwordx4 v[214:217], v138, s[12:13] offset:256
	s_and_b64 vcc, exec, s[6:7]
	s_cbranch_vccz .LBB0_313
	s_barrier

.LBB0_399:
	s_add_u32 s8, s0, 0xfffc0080
	s_addc_u32 s9, s1, -1
	s_add_i32 s22, 0, 0x10000
	s_cmp_eq_u32 s21, 12
	s_cselect_b32 s11, s7, s9
	s_cselect_b32 s10, s19, s8
	s_cselect_b32 s9, s20, s91
	s_cselect_b32 s8, s33, s90
	s_add_i32 s48, 0, 0x14000
	v_add_u32_e32 v152, s22, v157
	v_add_u32_e32 v162, s48, v157
	s_add_i32 m0, s27, 0xc000
	s_nop 0
	global_load_lds_dwordx4 v142, s[0:1]
	s_add_i32 m0, s27, 0xe000
	s_nop 0
	global_load_lds_dwordx4 v140, s[0:1]
	ds_read_b128 v[128:131], v152
	ds_read_b128 v[144:147], v152 offset:1024
	ds_read_b128 v[148:151], v152 offset:2048
	ds_read_b128 v[152:155], v152 offset:3072
	ds_read_b128 v[176:179], v162
	ds_read_b128 v[180:183], v162 offset:1024
	ds_read_b128 v[184:187], v162 offset:2048
	ds_read_b128 v[188:191], v162 offset:3072
	ds_read_b128 v[192:195], v159
	ds_read_b128 v[196:199], v159 offset:1024
	ds_read_b128 v[200:203], v159 offset:2048
	ds_read_b128 v[204:207], v159 offset:3072
	ds_read_b128 v[208:211], v159 offset:4096
	ds_read_b128 v[212:215], v159 offset:5120
	ds_read_b128 v[238:241], v159 offset:6144
	ds_read_b128 v[246:249], v159 offset:7168
	s_waitcnt vmcnt(8)
	s_waitcnt lgkmcnt(0)
	s_barrier
	v_mfma_f32_16x16x32_bf16 v[124:127], v[128:131], v[192:195], v[124:127]
	v_mfma_f32_16x16x32_bf16 v[116:119], v[148:151], v[192:195], v[116:119]
	v_mfma_f32_16x16x32_bf16 v[108:111], v[128:131], v[200:203], v[108:111]
	v_mfma_f32_16x16x32_bf16 v[100:103], v[148:151], v[200:203], v[100:103]
	v_mfma_f32_16x16x32_bf16 v[92:95], v[128:131], v[208:211], v[92:95]
	v_mfma_f32_16x16x32_bf16 v[84:87], v[148:151], v[208:211], v[84:87]
	v_mfma_f32_16x16x32_bf16 v[76:79], v[128:131], v[238:241], v[76:79]
	v_mfma_f32_16x16x32_bf16 v[68:71], v[148:151], v[238:241], v[68:71]
	v_mfma_f32_16x16x32_bf16 v[124:127], v[144:147], v[196:199], v[124:127]
	v_mfma_f32_16x16x32_bf16 v[116:119], v[152:155], v[196:199], v[116:119]
	v_mfma_f32_16x16x32_bf16 v[108:111], v[144:147], v[204:207], v[108:111]
	v_mfma_f32_16x16x32_bf16 v[100:103], v[152:155], v[204:207], v[100:103]
	v_mfma_f32_16x16x32_bf16 v[92:95], v[144:147], v[212:215], v[92:95]
	v_mfma_f32_16x16x32_bf16 v[84:87], v[152:155], v[212:215], v[84:87]
	v_mfma_f32_16x16x32_bf16 v[76:79], v[144:147], v[246:249], v[76:79]
	v_mfma_f32_16x16x32_bf16 v[68:71], v[152:155], v[246:249], v[68:71]
	v_mfma_f32_16x16x32_bf16 v[120:123], v[176:179], v[192:195], v[120:123]
	v_mfma_f32_16x16x32_bf16 v[112:115], v[184:187], v[192:195], v[112:115]
	v_mfma_f32_16x16x32_bf16 v[104:107], v[176:179], v[200:203], v[104:107]
	v_mfma_f32_16x16x32_bf16 v[96:99], v[184:187], v[200:203], v[96:99]
	v_mfma_f32_16x16x32_bf16 v[88:91], v[176:179], v[208:211], v[88:91]
	v_mfma_f32_16x16x32_bf16 v[80:83], v[184:187], v[208:211], v[80:83]
	v_mfma_f32_16x16x32_bf16 v[72:75], v[176:179], v[238:241], v[72:75]
	v_mfma_f32_16x16x32_bf16 v[64:67], v[184:187], v[238:241], v[64:67]
	v_mfma_f32_16x16x32_bf16 v[120:123], v[180:183], v[196:199], v[120:123]
	v_mfma_f32_16x16x32_bf16 v[112:115], v[188:191], v[196:199], v[112:115]
	v_mfma_f32_16x16x32_bf16 v[104:107], v[180:183], v[204:207], v[104:107]
	v_mfma_f32_16x16x32_bf16 v[96:99], v[188:191], v[204:207], v[96:99]
	v_mfma_f32_16x16x32_bf16 v[88:91], v[180:183], v[212:215], v[88:91]
	v_mfma_f32_16x16x32_bf16 v[80:83], v[188:191], v[212:215], v[80:83]
	v_mfma_f32_16x16x32_bf16 v[72:75], v[180:183], v[246:249], v[72:75]
	v_mfma_f32_16x16x32_bf16 v[64:67], v[188:191], v[246:249], v[64:67]
	s_barrier
	s_add_i32 s22, s22, s25
	s_mov_b32 m0, s22
	s_nop 0
	global_load_lds_dwordx4 v136, s[8:9]
	s_add_i32 m0, s22, 0x2000
	s_add_u32 vcc_lo, s8, 0x40000
	s_addc_u32 vcc_hi, s9, 0
	s_add_i32 s22, s48, s25
	global_load_lds_dwordx4 v132, s[8:9]
	s_mov_b32 m0, s22
	s_nop 0
	global_load_lds_dwordx4 v136, vcc
	s_add_i32 m0, s22, 0x2000
	s_nop 0
	global_load_lds_dwordx4 v132, vcc
	s_mov_b32 m0, s27
	s_nop 0
	global_load_lds_dwordx4 v138, s[10:11]
	s_mov_b32 m0, s45
	s_nop 0
	global_load_lds_dwordx4 v134, s[10:11]
	ds_read_b128 v[192:195], v159 offset:16384
	ds_read_b128 v[196:199], v159 offset:17408
	ds_read_b128 v[200:203], v159 offset:18432
	ds_read_b128 v[204:207], v159 offset:19456
	ds_read_b128 v[246:249], v159 offset:23552
	ds_read_b128 v[238:241], v159 offset:22528
	ds_read_b128 v[212:215], v159 offset:21504
	ds_read_b128 v[208:211], v159 offset:20480
	s_waitcnt vmcnt(8)
	s_waitcnt lgkmcnt(0)
	s_barrier
	v_mfma_f32_16x16x32_bf16 v[60:63], v[128:131], v[192:195], v[60:63]
	v_mfma_f32_16x16x32_bf16 v[52:55], v[148:151], v[192:195], v[52:55]
	v_mfma_f32_16x16x32_bf16 v[44:47], v[128:131], v[200:203], v[44:47]
	v_mfma_f32_16x16x32_bf16 v[36:39], v[148:151], v[200:203], v[36:39]
	v_mfma_f32_16x16x32_bf16 v[28:31], v[128:131], v[208:211], v[28:31]
	v_mfma_f32_16x16x32_bf16 v[20:23], v[148:151], v[208:211], v[20:23]
	v_mfma_f32_16x16x32_bf16 v[12:15], v[128:131], v[238:241], v[12:15]
	v_mfma_f32_16x16x32_bf16 v[4:7], v[148:151], v[238:241], v[4:7]
	v_mfma_f32_16x16x32_bf16 v[60:63], v[144:147], v[196:199], v[60:63]
	v_mfma_f32_16x16x32_bf16 v[52:55], v[152:155], v[196:199], v[52:55]
	v_mfma_f32_16x16x32_bf16 v[44:47], v[144:147], v[204:207], v[44:47]
	v_mfma_f32_16x16x32_bf16 v[36:39], v[152:155], v[204:207], v[36:39]
	v_mfma_f32_16x16x32_bf16 v[28:31], v[144:147], v[212:215], v[28:31]
	v_mfma_f32_16x16x32_bf16 v[20:23], v[152:155], v[212:215], v[20:23]
	v_mfma_f32_16x16x32_bf16 v[12:15], v[144:147], v[246:249], v[12:15]
	v_mfma_f32_16x16x32_bf16 v[4:7], v[152:155], v[246:249], v[4:7]
	v_mfma_f32_16x16x32_bf16 v[56:59], v[176:179], v[192:195], v[56:59]
	v_mfma_f32_16x16x32_bf16 v[48:51], v[184:187], v[192:195], v[48:51]
	v_mfma_f32_16x16x32_bf16 v[40:43], v[176:179], v[200:203], v[40:43]
	v_mfma_f32_16x16x32_bf16 v[32:35], v[184:187], v[200:203], v[32:35]
	v_mfma_f32_16x16x32_bf16 v[24:27], v[176:179], v[208:211], v[24:27]
	v_mfma_f32_16x16x32_bf16 v[16:19], v[184:187], v[208:211], v[16:19]
	v_mfma_f32_16x16x32_bf16 v[8:11], v[176:179], v[238:241], v[8:11]
	v_mfma_f32_16x16x32_bf16 v[0:3], v[184:187], v[238:241], v[0:3]
	v_mfma_f32_16x16x32_bf16 v[56:59], v[180:183], v[196:199], v[56:59]
	v_mfma_f32_16x16x32_bf16 v[48:51], v[188:191], v[196:199], v[48:51]
	v_mfma_f32_16x16x32_bf16 v[40:43], v[180:183], v[204:207], v[40:43]
	v_mfma_f32_16x16x32_bf16 v[32:35], v[188:191], v[204:207], v[32:35]
	v_mfma_f32_16x16x32_bf16 v[24:27], v[180:183], v[212:215], v[24:27]
	v_mfma_f32_16x16x32_bf16 v[16:19], v[188:191], v[212:215], v[16:19]
	v_mfma_f32_16x16x32_bf16 v[8:11], v[180:183], v[246:249], v[8:11]
	v_mfma_f32_16x16x32_bf16 v[0:3], v[188:191], v[246:249], v[0:3]
	s_barrier
	s_add_i32 s22, 0, 0x18000
	s_add_i32 s48, 0, 0x1c000
	v_add_u32_e32 v152, s22, v157
	v_add_u32_e32 v170, s48, v157
	s_mov_b64 s[100:101], s[10:11]
	s_add_u32 s10, s10, 0x40000
	s_addc_u32 s11, s11, 0
	s_mov_b32 m0, s28
	s_nop 0
	global_load_lds_dwordx4 v138, s[10:11]
	s_mov_b32 m0, s29
	s_nop 0
	global_load_lds_dwordx4 v134, s[10:11]
	ds_read_b128 v[128:131], v152
	ds_read_b128 v[144:147], v152 offset:1024
	ds_read_b128 v[148:151], v152 offset:2048
	ds_read_b128 v[152:155], v152 offset:3072
	ds_read_b128 v[176:179], v170
	ds_read_b128 v[180:183], v170 offset:1024
	ds_read_b128 v[184:187], v170 offset:2048
	ds_read_b128 v[188:191], v170 offset:3072
	ds_read_b128 v[192:195], v159 offset:32768
	ds_read_b128 v[196:199], v159 offset:33792
	ds_read_b128 v[200:203], v159 offset:34816
	ds_read_b128 v[204:207], v159 offset:35840
	ds_read_b128 v[208:211], v159 offset:36864
	ds_read_b128 v[212:215], v159 offset:37888
	ds_read_b128 v[238:241], v159 offset:38912
	ds_read_b128 v[246:249], v159 offset:39936
	s_waitcnt vmcnt(8)
	s_waitcnt lgkmcnt(0)
	s_barrier
	v_mfma_f32_16x16x32_bf16 v[124:127], v[128:131], v[192:195], v[124:127]
	v_mfma_f32_16x16x32_bf16 v[116:119], v[148:151], v[192:195], v[116:119]
	v_mfma_f32_16x16x32_bf16 v[108:111], v[128:131], v[200:203], v[108:111]
	v_mfma_f32_16x16x32_bf16 v[100:103], v[148:151], v[200:203], v[100:103]
	v_mfma_f32_16x16x32_bf16 v[92:95], v[128:131], v[208:211], v[92:95]
	v_mfma_f32_16x16x32_bf16 v[84:87], v[148:151], v[208:211], v[84:87]
	v_mfma_f32_16x16x32_bf16 v[76:79], v[128:131], v[238:241], v[76:79]
	v_mfma_f32_16x16x32_bf16 v[68:71], v[148:151], v[238:241], v[68:71]
	v_mfma_f32_16x16x32_bf16 v[124:127], v[144:147], v[196:199], v[124:127]
	v_mfma_f32_16x16x32_bf16 v[116:119], v[152:155], v[196:199], v[116:119]
	v_mfma_f32_16x16x32_bf16 v[108:111], v[144:147], v[204:207], v[108:111]
	v_mfma_f32_16x16x32_bf16 v[100:103], v[152:155], v[204:207], v[100:103]
	v_mfma_f32_16x16x32_bf16 v[92:95], v[144:147], v[212:215], v[92:95]
	v_mfma_f32_16x16x32_bf16 v[84:87], v[152:155], v[212:215], v[84:87]
	v_mfma_f32_16x16x32_bf16 v[76:79], v[144:147], v[246:249], v[76:79]
	v_mfma_f32_16x16x32_bf16 v[68:71], v[152:155], v[246:249], v[68:71]
	v_mfma_f32_16x16x32_bf16 v[120:123], v[176:179], v[192:195], v[120:123]
	v_mfma_f32_16x16x32_bf16 v[112:115], v[184:187], v[192:195], v[112:115]
	v_mfma_f32_16x16x32_bf16 v[104:107], v[176:179], v[200:203], v[104:107]
	v_mfma_f32_16x16x32_bf16 v[96:99], v[184:187], v[200:203], v[96:99]
	v_mfma_f32_16x16x32_bf16 v[88:91], v[176:179], v[208:211], v[88:91]
	v_mfma_f32_16x16x32_bf16 v[80:83], v[184:187], v[208:211], v[80:83]
	v_mfma_f32_16x16x32_bf16 v[72:75], v[176:179], v[238:241], v[72:75]
	v_mfma_f32_16x16x32_bf16 v[64:67], v[184:187], v[238:241], v[64:67]
	v_mfma_f32_16x16x32_bf16 v[120:123], v[180:183], v[196:199], v[120:123]
	v_mfma_f32_16x16x32_bf16 v[112:115], v[188:191], v[196:199], v[112:115]
	v_mfma_f32_16x16x32_bf16 v[104:107], v[180:183], v[204:207], v[104:107]
	v_mfma_f32_16x16x32_bf16 v[96:99], v[188:191], v[204:207], v[96:99]
	v_mfma_f32_16x16x32_bf16 v[88:91], v[180:183], v[212:215], v[88:91]
	v_mfma_f32_16x16x32_bf16 v[80:83], v[188:191], v[212:215], v[80:83]
	v_mfma_f32_16x16x32_bf16 v[72:75], v[180:183], v[246:249], v[72:75]
	v_mfma_f32_16x16x32_bf16 v[64:67], v[188:191], v[246:249], v[64:67]
	s_barrier
	s_add_i32 s10, s22, s25
	s_add_i32 m0, s10, 0xffffff80
	s_nop 0
	global_load_lds_dwordx4 v136, s[8:9] offset:128
	s_add_i32 m0, s10, 0x1f80
	s_nop 0
	global_load_lds_dwordx4 v132, s[8:9] offset:128
	s_add_u32 s8, s8, 0x40080
	s_addc_u32 s9, s9, 0
	s_add_i32 s10, s48, s25
	s_mov_b32 m0, s10
	s_nop 0
	global_load_lds_dwordx4 v136, s[8:9]
	s_add_i32 m0, s10, 0x2000
	s_nop 0
	global_load_lds_dwordx4 v132, s[8:9]
	s_add_i32 m0, s30, 0xffffff80
	s_nop 0
	global_load_lds_dwordx4 v138, s[100:101] offset:128
	s_add_i32 m0, s31, 0xffffff80
	s_nop 0
	global_load_lds_dwordx4 v134, s[100:101] offset:128
	ds_read_b128 v[192:195], v159 offset:49152
	ds_read_b128 v[196:199], v159 offset:50176
	ds_read_b128 v[200:203], v159 offset:51200
	ds_read_b128 v[246:249], v159 offset:56320
	ds_read_b128 v[238:241], v159 offset:55296
	ds_read_b128 v[212:215], v159 offset:54272
	ds_read_b128 v[208:211], v159 offset:53248
	ds_read_b128 v[204:207], v159 offset:52224
	s_waitcnt vmcnt(8)
	s_waitcnt lgkmcnt(0)
	s_barrier
	v_mfma_f32_16x16x32_bf16 v[60:63], v[128:131], v[192:195], v[60:63]
	v_mfma_f32_16x16x32_bf16 v[52:55], v[148:151], v[192:195], v[52:55]
	v_mfma_f32_16x16x32_bf16 v[44:47], v[128:131], v[200:203], v[44:47]
	v_mfma_f32_16x16x32_bf16 v[36:39], v[148:151], v[200:203], v[36:39]
	v_mfma_f32_16x16x32_bf16 v[28:31], v[128:131], v[208:211], v[28:31]
	v_mfma_f32_16x16x32_bf16 v[20:23], v[148:151], v[208:211], v[20:23]
	v_mfma_f32_16x16x32_bf16 v[12:15], v[128:131], v[238:241], v[12:15]
	v_mfma_f32_16x16x32_bf16 v[4:7], v[148:151], v[238:241], v[4:7]
	v_mfma_f32_16x16x32_bf16 v[60:63], v[144:147], v[196:199], v[60:63]
	v_mfma_f32_16x16x32_bf16 v[52:55], v[152:155], v[196:199], v[52:55]
	v_mfma_f32_16x16x32_bf16 v[44:47], v[144:147], v[204:207], v[44:47]
	v_mfma_f32_16x16x32_bf16 v[36:39], v[152:155], v[204:207], v[36:39]
	v_mfma_f32_16x16x32_bf16 v[28:31], v[144:147], v[212:215], v[28:31]
	v_mfma_f32_16x16x32_bf16 v[20:23], v[152:155], v[212:215], v[20:23]
	v_mfma_f32_16x16x32_bf16 v[12:15], v[144:147], v[246:249], v[12:15]
	v_mfma_f32_16x16x32_bf16 v[4:7], v[152:155], v[246:249], v[4:7]
	v_mfma_f32_16x16x32_bf16 v[56:59], v[176:179], v[192:195], v[56:59]
	v_mfma_f32_16x16x32_bf16 v[48:51], v[184:187], v[192:195], v[48:51]
	v_mfma_f32_16x16x32_bf16 v[40:43], v[176:179], v[200:203], v[40:43]
	v_mfma_f32_16x16x32_bf16 v[32:35], v[184:187], v[200:203], v[32:35]
	v_mfma_f32_16x16x32_bf16 v[24:27], v[176:179], v[208:211], v[24:27]
	v_mfma_f32_16x16x32_bf16 v[16:19], v[184:187], v[208:211], v[16:19]
	v_mfma_f32_16x16x32_bf16 v[8:11], v[176:179], v[238:241], v[8:11]
	v_mfma_f32_16x16x32_bf16 v[0:3], v[184:187], v[238:241], v[0:3]
	v_mfma_f32_16x16x32_bf16 v[56:59], v[180:183], v[196:199], v[56:59]
	v_mfma_f32_16x16x32_bf16 v[48:51], v[188:191], v[196:199], v[48:51]
	v_mfma_f32_16x16x32_bf16 v[40:43], v[180:183], v[204:207], v[40:43]
	v_mfma_f32_16x16x32_bf16 v[32:35], v[188:191], v[204:207], v[32:35]
	v_mfma_f32_16x16x32_bf16 v[24:27], v[180:183], v[212:215], v[24:27]
	v_mfma_f32_16x16x32_bf16 v[16:19], v[188:191], v[212:215], v[16:19]
	v_mfma_f32_16x16x32_bf16 v[8:11], v[180:183], v[246:249], v[8:11]
	v_mfma_f32_16x16x32_bf16 v[0:3], v[188:191], v[246:249], v[0:3]
	s_barrier
	s_add_i32 s21, s21, 2
	s_add_u32 s90, s90, 0x100
	s_addc_u32 s91, s91, 0
	s_add_u32 s0, s0, 0x100
	s_addc_u32 s1, s1, 0
	s_cmp_gt_u32 s21, 13
	s_cbranch_scc0 .LBB0_399
	v_lshl_add_u32 v212, s44, 8, v156
	v_lshlrev_b32_e32 v212, 3, v212
	global_load_dwordx2 v[196:197], v212, s[36:37]
	global_load_dwordx2 v[198:199], v212, s[36:37] offset:128
	global_load_dwordx2 v[200:201], v212, s[36:37] offset:256
	global_load_dwordx2 v[202:203], v212, s[36:37] offset:384
	global_load_dwordx2 v[204:205], v212, s[36:37] offset:1024
	global_load_dwordx2 v[206:207], v212, s[36:37] offset:1152
	global_load_dwordx2 v[208:209], v212, s[36:37] offset:1280
	global_load_dwordx2 v[210:211], v212, s[36:37] offset:1408
	s_and_b64 vcc, exec, s[92:93]
	s_cbranch_vccnz .LBB0_404
	s_cmp_gt_i32 s35, 3
	s_mov_b64 s[0:1], -1
	s_cbranch_scc1 .LBB0_405

.LBB0_439:
	s_add_u32 s10, s8, 0x100
	s_addc_u32 s11, s9, 0
	s_add_i32 s48, 0, 0x10000
	s_cmp_eq_u32 s22, 40
	s_cselect_b32 s15, s1, s11
	s_cselect_b32 s14, s0, s10
	s_cselect_b32 s13, s45, s92
	s_cselect_b32 s12, s44, s21
	s_add_i32 s49, 0, 0x14000
	v_add_u32_e32 v154, s48, v143
	v_add_u32_e32 v158, s49, v143
	s_add_i32 m0, s29, 0xc000
	s_nop 0
	global_load_lds_dwordx4 v136, s[8:9]
	s_add_i32 m0, s29, 0xe000
	s_nop 0
	global_load_lds_dwordx4 v134, s[8:9]
	ds_read_b128 v[138:141], v154
	ds_read_b128 v[146:149], v154 offset:1024
	ds_read_b128 v[150:153], v154 offset:2048
	ds_read_b128 v[154:157], v154 offset:3072
	ds_read_b128 v[174:177], v158
	ds_read_b128 v[178:181], v158 offset:1024
	ds_read_b128 v[182:185], v158 offset:2048
	ds_read_b128 v[186:189], v158 offset:3072
	ds_read_b128 v[190:193], v145
	ds_read_b128 v[194:197], v145 offset:1024
	ds_read_b128 v[198:201], v145 offset:2048
	ds_read_b128 v[202:205], v145 offset:3072
	ds_read_b128 v[206:209], v145 offset:4096
	ds_read_b128 v[210:213], v145 offset:5120
	ds_read_b128 v[214:217], v145 offset:6144
	ds_read_b128 v[238:241], v145 offset:7168
	s_waitcnt vmcnt(8)
	s_waitcnt lgkmcnt(0)
	s_barrier
	v_mfma_f32_16x16x32_bf16 v[124:127], v[138:141], v[190:193], v[124:127]
	v_mfma_f32_16x16x32_bf16 v[120:123], v[150:153], v[190:193], v[120:123]
	v_mfma_f32_16x16x32_bf16 v[108:111], v[138:141], v[198:201], v[108:111]
	v_mfma_f32_16x16x32_bf16 v[104:107], v[150:153], v[198:201], v[104:107]
	v_mfma_f32_16x16x32_bf16 v[92:95], v[138:141], v[206:209], v[92:95]
	v_mfma_f32_16x16x32_bf16 v[88:91], v[150:153], v[206:209], v[88:91]
	v_mfma_f32_16x16x32_bf16 v[76:79], v[138:141], v[214:217], v[76:79]
	v_mfma_f32_16x16x32_bf16 v[72:75], v[150:153], v[214:217], v[72:75]
	v_mfma_f32_16x16x32_bf16 v[124:127], v[146:149], v[194:197], v[124:127]
	v_mfma_f32_16x16x32_bf16 v[120:123], v[154:157], v[194:197], v[120:123]
	v_mfma_f32_16x16x32_bf16 v[108:111], v[146:149], v[202:205], v[108:111]
	v_mfma_f32_16x16x32_bf16 v[104:107], v[154:157], v[202:205], v[104:107]
	v_mfma_f32_16x16x32_bf16 v[92:95], v[146:149], v[210:213], v[92:95]
	v_mfma_f32_16x16x32_bf16 v[88:91], v[154:157], v[210:213], v[88:91]
	v_mfma_f32_16x16x32_bf16 v[76:79], v[146:149], v[238:241], v[76:79]
	v_mfma_f32_16x16x32_bf16 v[72:75], v[154:157], v[238:241], v[72:75]
	v_mfma_f32_16x16x32_bf16 v[116:119], v[174:177], v[190:193], v[116:119]
	v_mfma_f32_16x16x32_bf16 v[112:115], v[182:185], v[190:193], v[112:115]
	v_mfma_f32_16x16x32_bf16 v[100:103], v[174:177], v[198:201], v[100:103]
	v_mfma_f32_16x16x32_bf16 v[96:99], v[182:185], v[198:201], v[96:99]
	v_mfma_f32_16x16x32_bf16 v[84:87], v[174:177], v[206:209], v[84:87]
	v_mfma_f32_16x16x32_bf16 v[80:83], v[182:185], v[206:209], v[80:83]
	v_mfma_f32_16x16x32_bf16 v[68:71], v[174:177], v[214:217], v[68:71]
	v_mfma_f32_16x16x32_bf16 v[64:67], v[182:185], v[214:217], v[64:67]
	v_mfma_f32_16x16x32_bf16 v[116:119], v[178:181], v[194:197], v[116:119]
	v_mfma_f32_16x16x32_bf16 v[112:115], v[186:189], v[194:197], v[112:115]
	v_mfma_f32_16x16x32_bf16 v[100:103], v[178:181], v[202:205], v[100:103]
	v_mfma_f32_16x16x32_bf16 v[96:99], v[186:189], v[202:205], v[96:99]
	v_mfma_f32_16x16x32_bf16 v[84:87], v[178:181], v[210:213], v[84:87]
	v_mfma_f32_16x16x32_bf16 v[80:83], v[186:189], v[210:213], v[80:83]
	v_mfma_f32_16x16x32_bf16 v[68:71], v[178:181], v[238:241], v[68:71]
	v_mfma_f32_16x16x32_bf16 v[64:67], v[186:189], v[238:241], v[64:67]
	s_barrier
	s_add_i32 s8, s48, s28
	s_mov_b32 m0, s8
	s_nop 0
	global_load_lds_dwordx4 v160, s[12:13]
	s_add_i32 m0, s8, 0x2000
	s_add_u32 s8, s12, 0xb0000
	s_addc_u32 s9, s13, 0
	s_add_i32 s48, s49, s28
	global_load_lds_dwordx4 v132, s[12:13]
	s_mov_b32 m0, s48
	s_nop 0
	global_load_lds_dwordx4 v160, s[8:9]
	s_add_i32 m0, s48, 0x2000
	s_nop 0
	global_load_lds_dwordx4 v132, s[8:9]
	s_mov_b32 m0, s29
	s_nop 0
	global_load_lds_dwordx4 v128, s[14:15]
	s_mov_b32 m0, s30
	s_nop 0
	global_load_lds_dwordx4 v130, s[14:15]
	ds_read_b128 v[190:193], v145 offset:16384
	ds_read_b128 v[194:197], v145 offset:17408
	ds_read_b128 v[198:201], v145 offset:18432
	ds_read_b128 v[202:205], v145 offset:19456
	ds_read_b128 v[238:241], v145 offset:23552
	ds_read_b128 v[214:217], v145 offset:22528
	ds_read_b128 v[210:213], v145 offset:21504
	ds_read_b128 v[206:209], v145 offset:20480
	s_waitcnt vmcnt(8)
	s_waitcnt lgkmcnt(0)
	s_barrier
	v_mfma_f32_16x16x32_bf16 v[60:63], v[138:141], v[190:193], v[60:63]
	v_mfma_f32_16x16x32_bf16 v[56:59], v[150:153], v[190:193], v[56:59]
	v_mfma_f32_16x16x32_bf16 v[44:47], v[138:141], v[198:201], v[44:47]
	v_mfma_f32_16x16x32_bf16 v[40:43], v[150:153], v[198:201], v[40:43]
	v_mfma_f32_16x16x32_bf16 v[28:31], v[138:141], v[206:209], v[28:31]
	v_mfma_f32_16x16x32_bf16 v[24:27], v[150:153], v[206:209], v[24:27]
	v_mfma_f32_16x16x32_bf16 v[12:15], v[138:141], v[214:217], v[12:15]
	v_mfma_f32_16x16x32_bf16 v[8:11], v[150:153], v[214:217], v[8:11]
	v_mfma_f32_16x16x32_bf16 v[60:63], v[146:149], v[194:197], v[60:63]
	v_mfma_f32_16x16x32_bf16 v[56:59], v[154:157], v[194:197], v[56:59]
	v_mfma_f32_16x16x32_bf16 v[44:47], v[146:149], v[202:205], v[44:47]
	v_mfma_f32_16x16x32_bf16 v[40:43], v[154:157], v[202:205], v[40:43]
	v_mfma_f32_16x16x32_bf16 v[28:31], v[146:149], v[210:213], v[28:31]
	v_mfma_f32_16x16x32_bf16 v[24:27], v[154:157], v[210:213], v[24:27]
	v_mfma_f32_16x16x32_bf16 v[12:15], v[146:149], v[238:241], v[12:15]
	v_mfma_f32_16x16x32_bf16 v[8:11], v[154:157], v[238:241], v[8:11]
	v_mfma_f32_16x16x32_bf16 v[52:55], v[174:177], v[190:193], v[52:55]
	v_mfma_f32_16x16x32_bf16 v[48:51], v[182:185], v[190:193], v[48:51]
	v_mfma_f32_16x16x32_bf16 v[36:39], v[174:177], v[198:201], v[36:39]
	v_mfma_f32_16x16x32_bf16 v[32:35], v[182:185], v[198:201], v[32:35]
	v_mfma_f32_16x16x32_bf16 v[20:23], v[174:177], v[206:209], v[20:23]
	v_mfma_f32_16x16x32_bf16 v[16:19], v[182:185], v[206:209], v[16:19]
	v_mfma_f32_16x16x32_bf16 v[4:7], v[174:177], v[214:217], v[4:7]
	v_mfma_f32_16x16x32_bf16 v[0:3], v[182:185], v[214:217], v[0:3]
	v_mfma_f32_16x16x32_bf16 v[52:55], v[178:181], v[194:197], v[52:55]
	v_mfma_f32_16x16x32_bf16 v[48:51], v[186:189], v[194:197], v[48:51]
	v_mfma_f32_16x16x32_bf16 v[36:39], v[178:181], v[202:205], v[36:39]
	v_mfma_f32_16x16x32_bf16 v[32:35], v[186:189], v[202:205], v[32:35]
	v_mfma_f32_16x16x32_bf16 v[20:23], v[178:181], v[210:213], v[20:23]
	v_mfma_f32_16x16x32_bf16 v[16:19], v[186:189], v[210:213], v[16:19]
	v_mfma_f32_16x16x32_bf16 v[4:7], v[178:181], v[238:241], v[4:7]
	v_mfma_f32_16x16x32_bf16 v[0:3], v[186:189], v[238:241], v[0:3]
	s_barrier
	s_add_i32 s48, 0, 0x18000
	s_add_i32 s49, 0, 0x1c000
	v_add_u32_e32 v154, s48, v143
	v_add_u32_e32 v168, s49, v143
	s_add_u32 s8, s14, 0xb0000
	s_addc_u32 s9, s15, 0
	s_mov_b32 m0, s31
	s_nop 0
	global_load_lds_dwordx4 v128, s[8:9]
	s_mov_b32 m0, s33
	s_nop 0
	global_load_lds_dwordx4 v130, s[8:9]
	ds_read_b128 v[138:141], v154
	ds_read_b128 v[146:149], v154 offset:1024
	ds_read_b128 v[150:153], v154 offset:2048
	ds_read_b128 v[154:157], v154 offset:3072
	ds_read_b128 v[174:177], v168
	ds_read_b128 v[178:181], v168 offset:1024
	ds_read_b128 v[182:185], v168 offset:2048
	ds_read_b128 v[186:189], v168 offset:3072
	ds_read_b128 v[190:193], v145 offset:32768
	ds_read_b128 v[194:197], v145 offset:33792
	ds_read_b128 v[198:201], v145 offset:34816
	ds_read_b128 v[202:205], v145 offset:35840
	ds_read_b128 v[206:209], v145 offset:36864
	ds_read_b128 v[210:213], v145 offset:37888
	ds_read_b128 v[214:217], v145 offset:38912
	ds_read_b128 v[238:241], v145 offset:39936
	s_waitcnt vmcnt(8)
	s_waitcnt lgkmcnt(0)
	s_barrier
	v_mfma_f32_16x16x32_bf16 v[124:127], v[138:141], v[190:193], v[124:127]
	v_mfma_f32_16x16x32_bf16 v[120:123], v[150:153], v[190:193], v[120:123]
	v_mfma_f32_16x16x32_bf16 v[108:111], v[138:141], v[198:201], v[108:111]
	v_mfma_f32_16x16x32_bf16 v[104:107], v[150:153], v[198:201], v[104:107]
	v_mfma_f32_16x16x32_bf16 v[92:95], v[138:141], v[206:209], v[92:95]
	v_mfma_f32_16x16x32_bf16 v[88:91], v[150:153], v[206:209], v[88:91]
	v_mfma_f32_16x16x32_bf16 v[76:79], v[138:141], v[214:217], v[76:79]
	v_mfma_f32_16x16x32_bf16 v[72:75], v[150:153], v[214:217], v[72:75]
	v_mfma_f32_16x16x32_bf16 v[124:127], v[146:149], v[194:197], v[124:127]
	v_mfma_f32_16x16x32_bf16 v[120:123], v[154:157], v[194:197], v[120:123]
	v_mfma_f32_16x16x32_bf16 v[108:111], v[146:149], v[202:205], v[108:111]
	v_mfma_f32_16x16x32_bf16 v[104:107], v[154:157], v[202:205], v[104:107]
	v_mfma_f32_16x16x32_bf16 v[92:95], v[146:149], v[210:213], v[92:95]
	v_mfma_f32_16x16x32_bf16 v[88:91], v[154:157], v[210:213], v[88:91]
	v_mfma_f32_16x16x32_bf16 v[76:79], v[146:149], v[238:241], v[76:79]
	v_mfma_f32_16x16x32_bf16 v[72:75], v[154:157], v[238:241], v[72:75]
	v_mfma_f32_16x16x32_bf16 v[116:119], v[174:177], v[190:193], v[116:119]
	v_mfma_f32_16x16x32_bf16 v[112:115], v[182:185], v[190:193], v[112:115]
	v_mfma_f32_16x16x32_bf16 v[100:103], v[174:177], v[198:201], v[100:103]
	v_mfma_f32_16x16x32_bf16 v[96:99], v[182:185], v[198:201], v[96:99]
	v_mfma_f32_16x16x32_bf16 v[84:87], v[174:177], v[206:209], v[84:87]
	v_mfma_f32_16x16x32_bf16 v[80:83], v[182:185], v[206:209], v[80:83]
	v_mfma_f32_16x16x32_bf16 v[68:71], v[174:177], v[214:217], v[68:71]
	v_mfma_f32_16x16x32_bf16 v[64:67], v[182:185], v[214:217], v[64:67]
	v_mfma_f32_16x16x32_bf16 v[116:119], v[178:181], v[194:197], v[116:119]
	v_mfma_f32_16x16x32_bf16 v[112:115], v[186:189], v[194:197], v[112:115]
	v_mfma_f32_16x16x32_bf16 v[100:103], v[178:181], v[202:205], v[100:103]
	v_mfma_f32_16x16x32_bf16 v[96:99], v[186:189], v[202:205], v[96:99]
	v_mfma_f32_16x16x32_bf16 v[84:87], v[178:181], v[210:213], v[84:87]
	v_mfma_f32_16x16x32_bf16 v[80:83], v[186:189], v[210:213], v[80:83]
	v_mfma_f32_16x16x32_bf16 v[68:71], v[178:181], v[238:241], v[68:71]
	v_mfma_f32_16x16x32_bf16 v[64:67], v[186:189], v[238:241], v[64:67]
	s_barrier
	s_add_i32 s8, s48, s28
	s_add_i32 m0, s8, 0xffffff80
	s_nop 0
	global_load_lds_dwordx4 v160, s[12:13] offset:128
	s_add_i32 m0, s8, 0x1f80
	s_add_u32 s8, s12, 0xb0080
	s_addc_u32 s9, s13, 0
	global_load_lds_dwordx4 v132, s[12:13] offset:128
	s_add_i32 s12, s49, s28
	s_mov_b32 m0, s12
	s_nop 0
	global_load_lds_dwordx4 v160, s[8:9]
	s_add_i32 m0, s12, 0x2000
	s_nop 0
	global_load_lds_dwordx4 v132, s[8:9]
	s_add_i32 m0, s34, 0xffffff80
	s_nop 0
	global_load_lds_dwordx4 v128, s[14:15] offset:128
	s_add_i32 m0, s35, 0xffffff80
	s_nop 0
	global_load_lds_dwordx4 v130, s[14:15] offset:128
	ds_read_b128 v[190:193], v145 offset:49152
	ds_read_b128 v[194:197], v145 offset:50176
	ds_read_b128 v[198:201], v145 offset:51200
	ds_read_b128 v[202:205], v145 offset:52224
	ds_read_b128 v[238:241], v145 offset:56320
	ds_read_b128 v[214:217], v145 offset:55296
	ds_read_b128 v[210:213], v145 offset:54272
	ds_read_b128 v[206:209], v145 offset:53248
	s_waitcnt vmcnt(8)
	s_waitcnt lgkmcnt(0)
	s_barrier
	v_mfma_f32_16x16x32_bf16 v[60:63], v[138:141], v[190:193], v[60:63]
	v_mfma_f32_16x16x32_bf16 v[56:59], v[150:153], v[190:193], v[56:59]
	v_mfma_f32_16x16x32_bf16 v[44:47], v[138:141], v[198:201], v[44:47]
	v_mfma_f32_16x16x32_bf16 v[40:43], v[150:153], v[198:201], v[40:43]
	v_mfma_f32_16x16x32_bf16 v[28:31], v[138:141], v[206:209], v[28:31]
	v_mfma_f32_16x16x32_bf16 v[24:27], v[150:153], v[206:209], v[24:27]
	v_mfma_f32_16x16x32_bf16 v[12:15], v[138:141], v[214:217], v[12:15]
	v_mfma_f32_16x16x32_bf16 v[8:11], v[150:153], v[214:217], v[8:11]
	v_mfma_f32_16x16x32_bf16 v[60:63], v[146:149], v[194:197], v[60:63]
	v_mfma_f32_16x16x32_bf16 v[56:59], v[154:157], v[194:197], v[56:59]
	v_mfma_f32_16x16x32_bf16 v[44:47], v[146:149], v[202:205], v[44:47]
	v_mfma_f32_16x16x32_bf16 v[40:43], v[154:157], v[202:205], v[40:43]
	v_mfma_f32_16x16x32_bf16 v[28:31], v[146:149], v[210:213], v[28:31]
	v_mfma_f32_16x16x32_bf16 v[24:27], v[154:157], v[210:213], v[24:27]
	v_mfma_f32_16x16x32_bf16 v[12:15], v[146:149], v[238:241], v[12:15]
	v_mfma_f32_16x16x32_bf16 v[8:11], v[154:157], v[238:241], v[8:11]
	v_mfma_f32_16x16x32_bf16 v[52:55], v[174:177], v[190:193], v[52:55]
	v_mfma_f32_16x16x32_bf16 v[48:51], v[182:185], v[190:193], v[48:51]
	v_mfma_f32_16x16x32_bf16 v[36:39], v[174:177], v[198:201], v[36:39]
	v_mfma_f32_16x16x32_bf16 v[32:35], v[182:185], v[198:201], v[32:35]
	v_mfma_f32_16x16x32_bf16 v[20:23], v[174:177], v[206:209], v[20:23]
	v_mfma_f32_16x16x32_bf16 v[16:19], v[182:185], v[206:209], v[16:19]
	v_mfma_f32_16x16x32_bf16 v[4:7], v[174:177], v[214:217], v[4:7]
	v_mfma_f32_16x16x32_bf16 v[0:3], v[182:185], v[214:217], v[0:3]
	v_mfma_f32_16x16x32_bf16 v[52:55], v[178:181], v[194:197], v[52:55]
	v_mfma_f32_16x16x32_bf16 v[48:51], v[186:189], v[194:197], v[48:51]
	v_mfma_f32_16x16x32_bf16 v[36:39], v[178:181], v[202:205], v[36:39]
	v_mfma_f32_16x16x32_bf16 v[32:35], v[186:189], v[202:205], v[32:35]
	v_mfma_f32_16x16x32_bf16 v[20:23], v[178:181], v[210:213], v[20:23]
	v_mfma_f32_16x16x32_bf16 v[16:19], v[186:189], v[210:213], v[16:19]
	v_mfma_f32_16x16x32_bf16 v[4:7], v[178:181], v[238:241], v[4:7]
	v_mfma_f32_16x16x32_bf16 v[0:3], v[186:189], v[238:241], v[0:3]
	s_barrier
	s_add_i32 s22, s22, 2
	s_add_u32 s21, s21, 0x100
	s_addc_u32 s92, s92, 0
	s_cmp_gt_u32 s22, 41
	s_mov_b64 s[8:9], s[10:11]
	s_cbranch_scc0 .LBB0_439
	v_lshl_add_u32 v140, s20, 8, v142
	v_lshl_or_b32 v138, s91, 8, v144
	v_lshlrev_b32_e32 v141, 11, v140
	v_lshl_add_u32 v138, v138, 1, v141
	v_lshlrev_b32_e32 v139, 3, v140
	s_mov_b64 s[8:9], s[4:5]
	global_load_dwordx4 v[146:149], v138, s[8:9]
	global_load_dwordx4 v[150:153], v138, s[8:9] offset:256
	s_add_u32 s8, s8, 0x8000
	s_addc_u32 s9, s9, 0
	global_load_dwordx4 v[154:157], v138, s[8:9]
	global_load_dwordx4 v[162:165], v138, s[8:9] offset:256
	s_add_u32 s8, s8, 0x8000
	s_addc_u32 s9, s9, 0
	global_load_dwordx4 v[166:169], v138, s[8:9]
	global_load_dwordx4 v[174:177], v138, s[8:9] offset:256
	s_add_u32 s8, s8, 0x8000
	s_addc_u32 s9, s9, 0
	global_load_dwordx4 v[178:181], v138, s[8:9]
	global_load_dwordx4 v[182:185], v138, s[8:9] offset:256
	s_add_u32 s8, s8, 0x28000
	s_addc_u32 s9, s9, 0
	global_load_dwordx4 v[186:189], v138, s[8:9]
	global_load_dwordx4 v[190:193], v138, s[8:9] offset:256
	s_add_u32 s8, s8, 0x8000
	s_addc_u32 s9, s9, 0
	global_load_dwordx4 v[194:197], v138, s[8:9]
	global_load_dwordx4 v[198:201], v138, s[8:9] offset:256
	s_add_u32 s8, s8, 0x8000
	s_addc_u32 s9, s9, 0
	global_load_dwordx4 v[202:205], v138, s[8:9]
	global_load_dwordx4 v[206:209], v138, s[8:9] offset:256
	s_add_u32 s8, s8, 0x8000
	s_addc_u32 s9, s9, 0
	global_load_dwordx4 v[210:213], v138, s[8:9]
	global_load_dwordx4 v[214:217], v138, s[8:9] offset:256
	s_and_b64 vcc, exec, s[36:37]
	s_cbranch_vccz .LBB0_442
	s_barrier

.LBB0_474:
	s_add_u32 s12, s10, 0xfffc0080
	s_addc_u32 s13, s11, -1
	s_add_i32 s22, 0, 0x10000
	s_cmp_eq_u32 s21, 12
	s_cselect_b32 s15, s20, s13
	s_cselect_b32 s14, s37, s12
	s_cselect_b32 s13, s41, s93
	s_cselect_b32 s12, s91, s92
	s_add_i32 s48, 0, 0x14000
	v_add_u32_e32 v154, s22, v147
	v_add_u32_e32 v158, s48, v147
	s_add_i32 m0, s30, 0xc000
	s_nop 0
	global_load_lds_dwordx4 v136, s[10:11]
	s_add_i32 m0, s30, 0xe000
	s_nop 0
	global_load_lds_dwordx4 v134, s[10:11]
	ds_read_b128 v[138:141], v154
	ds_read_b128 v[142:145], v154 offset:1024
	ds_read_b128 v[150:153], v154 offset:2048
	ds_read_b128 v[154:157], v154 offset:3072
	ds_read_b128 v[174:177], v158
	ds_read_b128 v[178:181], v158 offset:1024
	ds_read_b128 v[182:185], v158 offset:2048
	ds_read_b128 v[186:189], v158 offset:3072
	ds_read_b128 v[190:193], v149
	ds_read_b128 v[194:197], v149 offset:1024
	ds_read_b128 v[198:201], v149 offset:2048
	ds_read_b128 v[202:205], v149 offset:3072
	ds_read_b128 v[206:209], v149 offset:4096
	ds_read_b128 v[210:213], v149 offset:5120
	ds_read_b128 v[214:217], v149 offset:6144
	ds_read_b128 v[238:241], v149 offset:7168
	s_waitcnt vmcnt(8)
	s_waitcnt lgkmcnt(0)
	s_barrier
	v_mfma_f32_16x16x32_bf16 v[124:127], v[138:141], v[190:193], v[124:127]
	v_mfma_f32_16x16x32_bf16 v[116:119], v[150:153], v[190:193], v[116:119]
	v_mfma_f32_16x16x32_bf16 v[108:111], v[138:141], v[198:201], v[108:111]
	v_mfma_f32_16x16x32_bf16 v[100:103], v[150:153], v[198:201], v[100:103]
	v_mfma_f32_16x16x32_bf16 v[92:95], v[138:141], v[206:209], v[92:95]
	v_mfma_f32_16x16x32_bf16 v[84:87], v[150:153], v[206:209], v[84:87]
	v_mfma_f32_16x16x32_bf16 v[76:79], v[138:141], v[214:217], v[76:79]
	v_mfma_f32_16x16x32_bf16 v[64:67], v[150:153], v[214:217], v[64:67]
	v_mfma_f32_16x16x32_bf16 v[124:127], v[142:145], v[194:197], v[124:127]
	v_mfma_f32_16x16x32_bf16 v[116:119], v[154:157], v[194:197], v[116:119]
	v_mfma_f32_16x16x32_bf16 v[108:111], v[142:145], v[202:205], v[108:111]
	v_mfma_f32_16x16x32_bf16 v[100:103], v[154:157], v[202:205], v[100:103]
	v_mfma_f32_16x16x32_bf16 v[92:95], v[142:145], v[210:213], v[92:95]
	v_mfma_f32_16x16x32_bf16 v[84:87], v[154:157], v[210:213], v[84:87]
	v_mfma_f32_16x16x32_bf16 v[76:79], v[142:145], v[238:241], v[76:79]
	v_mfma_f32_16x16x32_bf16 v[64:67], v[154:157], v[238:241], v[64:67]
	v_mfma_f32_16x16x32_bf16 v[120:123], v[174:177], v[190:193], v[120:123]
	v_mfma_f32_16x16x32_bf16 v[112:115], v[182:185], v[190:193], v[112:115]
	v_mfma_f32_16x16x32_bf16 v[104:107], v[174:177], v[198:201], v[104:107]
	v_mfma_f32_16x16x32_bf16 v[96:99], v[182:185], v[198:201], v[96:99]
	v_mfma_f32_16x16x32_bf16 v[88:91], v[174:177], v[206:209], v[88:91]
	v_mfma_f32_16x16x32_bf16 v[80:83], v[182:185], v[206:209], v[80:83]
	v_mfma_f32_16x16x32_bf16 v[72:75], v[174:177], v[214:217], v[72:75]
	v_mfma_f32_16x16x32_bf16 v[68:71], v[182:185], v[214:217], v[68:71]
	v_mfma_f32_16x16x32_bf16 v[120:123], v[178:181], v[194:197], v[120:123]
	v_mfma_f32_16x16x32_bf16 v[112:115], v[186:189], v[194:197], v[112:115]
	v_mfma_f32_16x16x32_bf16 v[104:107], v[178:181], v[202:205], v[104:107]
	v_mfma_f32_16x16x32_bf16 v[96:99], v[186:189], v[202:205], v[96:99]
	v_mfma_f32_16x16x32_bf16 v[88:91], v[178:181], v[210:213], v[88:91]
	v_mfma_f32_16x16x32_bf16 v[80:83], v[186:189], v[210:213], v[80:83]
	v_mfma_f32_16x16x32_bf16 v[72:75], v[178:181], v[238:241], v[72:75]
	v_mfma_f32_16x16x32_bf16 v[68:71], v[186:189], v[238:241], v[68:71]
	s_barrier
	s_add_i32 s22, s22, s28
	s_mov_b32 m0, s22
	s_nop 0
	global_load_lds_dwordx4 v160, s[12:13]
	s_add_i32 m0, s22, 0x2000
	s_add_u32 s96, s12, 0x40000
	s_addc_u32 s97, s13, 0
	s_add_i32 s22, s48, s28
	global_load_lds_dwordx4 v128, s[12:13]
	s_mov_b32 m0, s22
	s_nop 0
	global_load_lds_dwordx4 v160, s[96:97]
	s_add_i32 m0, s22, 0x2000
	s_nop 0
	global_load_lds_dwordx4 v128, s[96:97]
	s_mov_b32 m0, s30
	s_nop 0
	global_load_lds_dwordx4 v132, s[14:15]
	s_mov_b32 m0, s31
	s_nop 0
	global_load_lds_dwordx4 v130, s[14:15]
	ds_read_b128 v[190:193], v149 offset:16384
	ds_read_b128 v[194:197], v149 offset:17408
	ds_read_b128 v[198:201], v149 offset:18432
	ds_read_b128 v[202:205], v149 offset:19456
	ds_read_b128 v[238:241], v149 offset:23552
	ds_read_b128 v[214:217], v149 offset:22528
	ds_read_b128 v[210:213], v149 offset:21504
	ds_read_b128 v[206:209], v149 offset:20480
	s_waitcnt vmcnt(8)
	s_waitcnt lgkmcnt(0)
	s_barrier
	v_mfma_f32_16x16x32_bf16 v[60:63], v[138:141], v[190:193], v[60:63]
	v_mfma_f32_16x16x32_bf16 v[48:51], v[150:153], v[190:193], v[48:51]
	v_mfma_f32_16x16x32_bf16 v[44:47], v[138:141], v[198:201], v[44:47]
	v_mfma_f32_16x16x32_bf16 v[32:35], v[150:153], v[198:201], v[32:35]
	v_mfma_f32_16x16x32_bf16 v[28:31], v[138:141], v[206:209], v[28:31]
	v_mfma_f32_16x16x32_bf16 v[16:19], v[150:153], v[206:209], v[16:19]
	v_mfma_f32_16x16x32_bf16 v[12:15], v[138:141], v[214:217], v[12:15]
	v_mfma_f32_16x16x32_bf16 v[0:3], v[150:153], v[214:217], v[0:3]
	v_mfma_f32_16x16x32_bf16 v[60:63], v[142:145], v[194:197], v[60:63]
	v_mfma_f32_16x16x32_bf16 v[48:51], v[154:157], v[194:197], v[48:51]
	v_mfma_f32_16x16x32_bf16 v[44:47], v[142:145], v[202:205], v[44:47]
	v_mfma_f32_16x16x32_bf16 v[32:35], v[154:157], v[202:205], v[32:35]
	v_mfma_f32_16x16x32_bf16 v[28:31], v[142:145], v[210:213], v[28:31]
	v_mfma_f32_16x16x32_bf16 v[16:19], v[154:157], v[210:213], v[16:19]
	v_mfma_f32_16x16x32_bf16 v[12:15], v[142:145], v[238:241], v[12:15]
	v_mfma_f32_16x16x32_bf16 v[0:3], v[154:157], v[238:241], v[0:3]
	v_mfma_f32_16x16x32_bf16 v[56:59], v[174:177], v[190:193], v[56:59]
	v_mfma_f32_16x16x32_bf16 v[52:55], v[182:185], v[190:193], v[52:55]
	v_mfma_f32_16x16x32_bf16 v[40:43], v[174:177], v[198:201], v[40:43]
	v_mfma_f32_16x16x32_bf16 v[36:39], v[182:185], v[198:201], v[36:39]
	v_mfma_f32_16x16x32_bf16 v[24:27], v[174:177], v[206:209], v[24:27]
	v_mfma_f32_16x16x32_bf16 v[20:23], v[182:185], v[206:209], v[20:23]
	v_mfma_f32_16x16x32_bf16 v[8:11], v[174:177], v[214:217], v[8:11]
	v_mfma_f32_16x16x32_bf16 v[4:7], v[182:185], v[214:217], v[4:7]
	v_mfma_f32_16x16x32_bf16 v[56:59], v[178:181], v[194:197], v[56:59]
	v_mfma_f32_16x16x32_bf16 v[52:55], v[186:189], v[194:197], v[52:55]
	v_mfma_f32_16x16x32_bf16 v[40:43], v[178:181], v[202:205], v[40:43]
	v_mfma_f32_16x16x32_bf16 v[36:39], v[186:189], v[202:205], v[36:39]
	v_mfma_f32_16x16x32_bf16 v[24:27], v[178:181], v[210:213], v[24:27]
	v_mfma_f32_16x16x32_bf16 v[20:23], v[186:189], v[210:213], v[20:23]
	v_mfma_f32_16x16x32_bf16 v[8:11], v[178:181], v[238:241], v[8:11]
	v_mfma_f32_16x16x32_bf16 v[4:7], v[186:189], v[238:241], v[4:7]
	s_barrier
	s_add_i32 s22, 0, 0x18000
	s_add_i32 s48, 0, 0x1c000
	v_add_u32_e32 v154, s22, v147
	v_add_u32_e32 v168, s48, v147
	s_mov_b64 s[100:101], s[14:15]
	s_add_u32 s14, s14, 0x40000
	s_addc_u32 s15, s15, 0
	s_mov_b32 m0, s33
	s_nop 0
	global_load_lds_dwordx4 v132, s[14:15]
	s_mov_b32 m0, s34
	s_nop 0
	global_load_lds_dwordx4 v130, s[14:15]
	ds_read_b128 v[138:141], v154
	ds_read_b128 v[142:145], v154 offset:1024
	ds_read_b128 v[150:153], v154 offset:2048
	ds_read_b128 v[154:157], v154 offset:3072
	ds_read_b128 v[174:177], v168
	ds_read_b128 v[178:181], v168 offset:1024
	ds_read_b128 v[182:185], v168 offset:2048
	ds_read_b128 v[186:189], v168 offset:3072
	ds_read_b128 v[190:193], v149 offset:32768
	ds_read_b128 v[194:197], v149 offset:33792
	ds_read_b128 v[198:201], v149 offset:34816
	ds_read_b128 v[202:205], v149 offset:35840
	ds_read_b128 v[206:209], v149 offset:36864
	ds_read_b128 v[210:213], v149 offset:37888
	ds_read_b128 v[214:217], v149 offset:38912
	ds_read_b128 v[238:241], v149 offset:39936
	s_waitcnt vmcnt(8)
	s_waitcnt lgkmcnt(0)
	s_barrier
	v_mfma_f32_16x16x32_bf16 v[124:127], v[138:141], v[190:193], v[124:127]
	v_mfma_f32_16x16x32_bf16 v[116:119], v[150:153], v[190:193], v[116:119]
	v_mfma_f32_16x16x32_bf16 v[108:111], v[138:141], v[198:201], v[108:111]
	v_mfma_f32_16x16x32_bf16 v[100:103], v[150:153], v[198:201], v[100:103]
	v_mfma_f32_16x16x32_bf16 v[92:95], v[138:141], v[206:209], v[92:95]
	v_mfma_f32_16x16x32_bf16 v[84:87], v[150:153], v[206:209], v[84:87]
	v_mfma_f32_16x16x32_bf16 v[76:79], v[138:141], v[214:217], v[76:79]
	v_mfma_f32_16x16x32_bf16 v[64:67], v[150:153], v[214:217], v[64:67]
	v_mfma_f32_16x16x32_bf16 v[124:127], v[142:145], v[194:197], v[124:127]
	v_mfma_f32_16x16x32_bf16 v[116:119], v[154:157], v[194:197], v[116:119]
	v_mfma_f32_16x16x32_bf16 v[108:111], v[142:145], v[202:205], v[108:111]
	v_mfma_f32_16x16x32_bf16 v[100:103], v[154:157], v[202:205], v[100:103]
	v_mfma_f32_16x16x32_bf16 v[92:95], v[142:145], v[210:213], v[92:95]
	v_mfma_f32_16x16x32_bf16 v[84:87], v[154:157], v[210:213], v[84:87]
	v_mfma_f32_16x16x32_bf16 v[76:79], v[142:145], v[238:241], v[76:79]
	v_mfma_f32_16x16x32_bf16 v[64:67], v[154:157], v[238:241], v[64:67]
	v_mfma_f32_16x16x32_bf16 v[120:123], v[174:177], v[190:193], v[120:123]
	v_mfma_f32_16x16x32_bf16 v[112:115], v[182:185], v[190:193], v[112:115]
	v_mfma_f32_16x16x32_bf16 v[104:107], v[174:177], v[198:201], v[104:107]
	v_mfma_f32_16x16x32_bf16 v[96:99], v[182:185], v[198:201], v[96:99]
	v_mfma_f32_16x16x32_bf16 v[88:91], v[174:177], v[206:209], v[88:91]
	v_mfma_f32_16x16x32_bf16 v[80:83], v[182:185], v[206:209], v[80:83]
	v_mfma_f32_16x16x32_bf16 v[72:75], v[174:177], v[214:217], v[72:75]
	v_mfma_f32_16x16x32_bf16 v[68:71], v[182:185], v[214:217], v[68:71]
	v_mfma_f32_16x16x32_bf16 v[120:123], v[178:181], v[194:197], v[120:123]
	v_mfma_f32_16x16x32_bf16 v[112:115], v[186:189], v[194:197], v[112:115]
	v_mfma_f32_16x16x32_bf16 v[104:107], v[178:181], v[202:205], v[104:107]
	v_mfma_f32_16x16x32_bf16 v[96:99], v[186:189], v[202:205], v[96:99]
	v_mfma_f32_16x16x32_bf16 v[88:91], v[178:181], v[210:213], v[88:91]
	v_mfma_f32_16x16x32_bf16 v[80:83], v[186:189], v[210:213], v[80:83]
	v_mfma_f32_16x16x32_bf16 v[72:75], v[178:181], v[238:241], v[72:75]
	v_mfma_f32_16x16x32_bf16 v[68:71], v[186:189], v[238:241], v[68:71]
	s_barrier
	s_add_i32 s14, s22, s28
	s_add_i32 m0, s14, 0xffffff80
	s_nop 0
	global_load_lds_dwordx4 v160, s[12:13] offset:128
	s_add_i32 m0, s14, 0x1f80
	s_nop 0
	global_load_lds_dwordx4 v128, s[12:13] offset:128
	s_add_u32 s12, s12, 0x40080
	s_addc_u32 s13, s13, 0
	s_add_i32 s14, s48, s28
	s_mov_b32 m0, s14
	s_nop 0
	global_load_lds_dwordx4 v160, s[12:13]
	s_add_i32 m0, s14, 0x2000
	s_nop 0
	global_load_lds_dwordx4 v128, s[12:13]
	s_add_i32 m0, s35, 0xffffff80
	s_nop 0
	global_load_lds_dwordx4 v132, s[100:101] offset:128
	s_add_i32 m0, s90, 0xffffff80
	s_nop 0
	global_load_lds_dwordx4 v130, s[100:101] offset:128
	ds_read_b128 v[190:193], v149 offset:49152
	ds_read_b128 v[194:197], v149 offset:50176
	ds_read_b128 v[198:201], v149 offset:51200
	ds_read_b128 v[238:241], v149 offset:56320
	ds_read_b128 v[214:217], v149 offset:55296
	ds_read_b128 v[210:213], v149 offset:54272
	ds_read_b128 v[206:209], v149 offset:53248
	ds_read_b128 v[202:205], v149 offset:52224
	s_waitcnt vmcnt(8)
	s_waitcnt lgkmcnt(0)
	s_barrier
	v_mfma_f32_16x16x32_bf16 v[60:63], v[138:141], v[190:193], v[60:63]
	v_mfma_f32_16x16x32_bf16 v[48:51], v[150:153], v[190:193], v[48:51]
	v_mfma_f32_16x16x32_bf16 v[44:47], v[138:141], v[198:201], v[44:47]
	v_mfma_f32_16x16x32_bf16 v[32:35], v[150:153], v[198:201], v[32:35]
	v_mfma_f32_16x16x32_bf16 v[28:31], v[138:141], v[206:209], v[28:31]
	v_mfma_f32_16x16x32_bf16 v[16:19], v[150:153], v[206:209], v[16:19]
	v_mfma_f32_16x16x32_bf16 v[12:15], v[138:141], v[214:217], v[12:15]
	v_mfma_f32_16x16x32_bf16 v[0:3], v[150:153], v[214:217], v[0:3]
	v_mfma_f32_16x16x32_bf16 v[60:63], v[142:145], v[194:197], v[60:63]
	v_mfma_f32_16x16x32_bf16 v[48:51], v[154:157], v[194:197], v[48:51]
	v_mfma_f32_16x16x32_bf16 v[44:47], v[142:145], v[202:205], v[44:47]
	v_mfma_f32_16x16x32_bf16 v[32:35], v[154:157], v[202:205], v[32:35]
	v_mfma_f32_16x16x32_bf16 v[28:31], v[142:145], v[210:213], v[28:31]
	v_mfma_f32_16x16x32_bf16 v[16:19], v[154:157], v[210:213], v[16:19]
	v_mfma_f32_16x16x32_bf16 v[12:15], v[142:145], v[238:241], v[12:15]
	v_mfma_f32_16x16x32_bf16 v[0:3], v[154:157], v[238:241], v[0:3]
	v_mfma_f32_16x16x32_bf16 v[56:59], v[174:177], v[190:193], v[56:59]
	v_mfma_f32_16x16x32_bf16 v[52:55], v[182:185], v[190:193], v[52:55]
	v_mfma_f32_16x16x32_bf16 v[40:43], v[174:177], v[198:201], v[40:43]
	v_mfma_f32_16x16x32_bf16 v[36:39], v[182:185], v[198:201], v[36:39]
	v_mfma_f32_16x16x32_bf16 v[24:27], v[174:177], v[206:209], v[24:27]
	v_mfma_f32_16x16x32_bf16 v[20:23], v[182:185], v[206:209], v[20:23]
	v_mfma_f32_16x16x32_bf16 v[8:11], v[174:177], v[214:217], v[8:11]
	v_mfma_f32_16x16x32_bf16 v[4:7], v[182:185], v[214:217], v[4:7]
	v_mfma_f32_16x16x32_bf16 v[56:59], v[178:181], v[194:197], v[56:59]
	v_mfma_f32_16x16x32_bf16 v[52:55], v[186:189], v[194:197], v[52:55]
	v_mfma_f32_16x16x32_bf16 v[40:43], v[178:181], v[202:205], v[40:43]
	v_mfma_f32_16x16x32_bf16 v[36:39], v[186:189], v[202:205], v[36:39]
	v_mfma_f32_16x16x32_bf16 v[24:27], v[178:181], v[210:213], v[24:27]
	v_mfma_f32_16x16x32_bf16 v[20:23], v[186:189], v[210:213], v[20:23]
	v_mfma_f32_16x16x32_bf16 v[8:11], v[178:181], v[238:241], v[8:11]
	v_mfma_f32_16x16x32_bf16 v[4:7], v[186:189], v[238:241], v[4:7]
	s_barrier
	s_add_i32 s21, s21, 2
	s_add_u32 s92, s92, 0x100
	s_addc_u32 s93, s93, 0
	s_add_u32 s10, s10, 0x100
	s_addc_u32 s11, s11, 0
	s_cmp_gt_u32 s21, 13
	s_cbranch_scc0 .LBB0_474
	v_lshl_add_u32 v192, s8, 8, v146
	v_lshlrev_b32_e32 v192, 3, v192
	global_load_dwordx2 v[176:177], v192, s[4:5]
	global_load_dwordx2 v[178:179], v192, s[4:5] offset:128
	global_load_dwordx2 v[180:181], v192, s[4:5] offset:256
	global_load_dwordx2 v[182:183], v192, s[4:5] offset:384
	global_load_dwordx2 v[184:185], v192, s[4:5] offset:1024
	global_load_dwordx2 v[186:187], v192, s[4:5] offset:1152
	global_load_dwordx2 v[188:189], v192, s[4:5] offset:1280
	global_load_dwordx2 v[190:191], v192, s[4:5] offset:1408
	s_and_b64 vcc, exec, s[6:7]
	s_cbranch_vccz .LBB0_477
	s_barrier
